# A/B deletion of all s_setprio flips in the eight GEMM K-loops
# speedup vs baseline: 1.0088x; 1.0088x over previous
; #define PG8_STAGE(bufoff, gbase, voff) do { _Pragma("unroll") for (int _i = 0; _i < 2; ++_i) \
;         __builtin_amdgcn_global_load_lds((const unsigned*)((const char*)(gbase) + (voff)[_i]), (LAS unsigned*)(lds + (bufoff) + ldsw + _i * 8192), 16, 0, 0); } while (0)
; #define PG8_LDA(dst, b, h) do { _Pragma("unroll") for (int m = 0; m < 4; ++m) _Pragma("unroll") for (int k = 0; k < 2; ++k) dst[m][k] = *(const LAS bf16x8*)(lds + PG8_SA(b, h) + aoff + m * 2048 + k * 1024); } while (0)
; #define PG8_LDB(dst, b, h) do { _Pragma("unroll") for (int n = 0; n < 2; ++n) _Pragma("unroll") for (int k = 0; k < 2; ++k) dst[n][k] = *(const LAS bf16x8*)(lds + PG8_SB(b, h) + boff + n * 2048 + k * 1024); } while (0)
; #define PG8_MMA(ai, bj, At, Bt) do { __builtin_amdgcn_s_setprio(1); _Pragma("unroll") for (int m = 0; m < 4; ++m) _Pragma("unroll") for (int n = 0; n < 2; ++n) _Pragma("unroll") for (int k = 0; k < 2; ++k) \
;         acc[ai][bj][m][n] = __builtin_amdgcn_mfma_f32_16x16x32_bf16(Bt[n][k], At[m][k], acc[ai][bj][m][n], 0, 0, 0); __builtin_amdgcn_s_setprio(0); } while (0)
; #define PG8_WAIT_V(n) asm volatile("s_waitcnt vmcnt(" #n ")" ::: "memory")
; #define PG8_WAIT_L(n) asm volatile("s_waitcnt lgkmcnt(" #n ")" ::: "memory")
; #define PG8_BAR __builtin_amdgcn_s_barrier()
; #define PG8_SCHED __builtin_amdgcn_sched_barrier(0)
; template <class Epi, bool ALIGN_EPI, bool ASLOT = false>
; __device__ __forceinline__ void gemm_phase(LAS unsigned char* lds, const Gemm g, const Sched& S, const Epi& E) {
;     ...
;             const bool last = (t == nt - 2);
;             const char* a1 = cA + (size_t)(t + 1) * kstep;
;             const char* a2 = last ? nA : cA + (size_t)(t + 2) * kstep; const char* b2 = last ? nB : cB + (size_t)(t + 2) * kstep;
;             const char* a3 = a2 + kstep; const char* b3 = b2 + kstep;
;             PG8_LDB(B0, 0, 0); PG8_LDB(B1, 0, 1); PG8_SCHED; PG8_LDA(At, 0, 0); PG8_STAGE(PG8_SA(1, 1), a1 + hstep, voffA);
;             PG8_WAIT_V(8); PG8_WAIT_L(0); PG8_BAR; PG8_MMA(0, 0, At, B0); PG8_MMA(0, 1, At, B1); PG8_BAR; PG8_SCHED;
;             PG8_LDA(At, 0, 1); PG8_STAGE(PG8_SB(0, 0), b2, voffB); PG8_STAGE(PG8_SB(0, 1), b2 + hstep, voffB); PG8_STAGE(PG8_SA(0, 0), a2, voffA);
;             PG8_WAIT_V(8); PG8_WAIT_L(0); PG8_BAR; PG8_MMA(1, 0, At, B0); PG8_MMA(1, 1, At, B1); PG8_BAR; PG8_SCHED;
.LBB0_122:
	s_add_u32 s18, s14, 0xfffc0080
	s_addc_u32 s19, s15, -1
	s_add_i32 s28, 0, 0x10000
	s_cmp_eq_u32 s48, 12
	s_cselect_b32 s21, s7, s19
	s_cselect_b32 s20, s24, s18
	v_add_u32_e32 v156, s28, v158
	s_cselect_b32 s19, s9, s47
	s_cselect_b32 s18, s25, s46
	s_add_i32 s33, 0, 0x14000
	ds_read_b128 v[162:165], v156
	ds_read_b128 v[166:169], v156 offset:1024
	ds_read_b128 v[170:173], v156 offset:2048
	ds_read_b128 v[174:177], v156 offset:3072
	v_add_u32_e32 v156, s33, v158
	ds_read_b128 v[178:181], v156
	ds_read_b128 v[182:185], v156 offset:1024
	ds_read_b128 v[186:189], v156 offset:2048
	ds_read_b128 v[190:193], v156 offset:3072
	v_lshl_add_u64 v[156:157], s[14:15], 0, v[152:153]
	s_add_i32 m0, s40, 0xc000
	ds_read_b128 v[194:197], v160
	ds_read_b128 v[198:201], v160 offset:1024
	ds_read_b128 v[202:205], v160 offset:2048
	ds_read_b128 v[206:209], v160 offset:3072
	ds_read_b128 v[210:213], v160 offset:4096
	ds_read_b128 v[236:239], v160 offset:5120
	ds_read_b128 v[240:243], v160 offset:6144
	ds_read_b128 v[244:247], v160 offset:7168
	global_load_lds_dwordx4 v[156:157], off
	v_lshl_add_u64 v[156:157], s[14:15], 0, v[154:155]
	s_add_i32 m0, s40, 0xe000
	s_nop 0
	global_load_lds_dwordx4 v[156:157], off
	s_waitcnt vmcnt(8)
	s_waitcnt lgkmcnt(0)
	s_barrier
	s_waitcnt lgkmcnt(0)
	v_mfma_f32_16x16x32_bf16 v[126:129], v[162:165], v[194:197], v[126:129]
	v_mfma_f32_16x16x32_bf16 v[122:125], v[170:173], v[194:197], v[122:125]
	v_mfma_f32_16x16x32_bf16 v[110:113], v[162:165], v[202:205], v[110:113]
	v_mfma_f32_16x16x32_bf16 v[106:109], v[170:173], v[202:205], v[106:109]
	v_mfma_f32_16x16x32_bf16 v[94:97], v[162:165], v[210:213], v[94:97]
	v_mfma_f32_16x16x32_bf16 v[90:93], v[170:173], v[210:213], v[90:93]
	v_mfma_f32_16x16x32_bf16 v[78:81], v[162:165], v[240:243], v[78:81]
	v_mfma_f32_16x16x32_bf16 v[74:77], v[170:173], v[240:243], v[74:77]
	v_mfma_f32_16x16x32_bf16 v[126:129], v[166:169], v[198:201], v[126:129]
	v_mfma_f32_16x16x32_bf16 v[122:125], v[174:177], v[198:201], v[122:125]
	v_mfma_f32_16x16x32_bf16 v[110:113], v[166:169], v[206:209], v[110:113]
	v_mfma_f32_16x16x32_bf16 v[106:109], v[174:177], v[206:209], v[106:109]
	v_mfma_f32_16x16x32_bf16 v[94:97], v[166:169], v[236:239], v[94:97]
	v_mfma_f32_16x16x32_bf16 v[90:93], v[174:177], v[236:239], v[90:93]
	v_mfma_f32_16x16x32_bf16 v[78:81], v[166:169], v[244:247], v[78:81]
	v_mfma_f32_16x16x32_bf16 v[74:77], v[174:177], v[244:247], v[74:77]
	v_mfma_f32_16x16x32_bf16 v[118:121], v[178:181], v[194:197], v[118:121]
	v_mfma_f32_16x16x32_bf16 v[114:117], v[186:189], v[194:197], v[114:117]
	v_mfma_f32_16x16x32_bf16 v[102:105], v[178:181], v[202:205], v[102:105]
	v_mfma_f32_16x16x32_bf16 v[98:101], v[186:189], v[202:205], v[98:101]
	v_mfma_f32_16x16x32_bf16 v[86:89], v[178:181], v[210:213], v[86:89]
	v_mfma_f32_16x16x32_bf16 v[82:85], v[186:189], v[210:213], v[82:85]
	v_mfma_f32_16x16x32_bf16 v[70:73], v[178:181], v[240:243], v[70:73]
	v_mfma_f32_16x16x32_bf16 v[66:69], v[186:189], v[240:243], v[66:69]
	v_mfma_f32_16x16x32_bf16 v[118:121], v[182:185], v[198:201], v[118:121]
	v_mfma_f32_16x16x32_bf16 v[114:117], v[190:193], v[198:201], v[114:117]
	v_mfma_f32_16x16x32_bf16 v[102:105], v[182:185], v[206:209], v[102:105]
	v_mfma_f32_16x16x32_bf16 v[98:101], v[190:193], v[206:209], v[98:101]
	v_mfma_f32_16x16x32_bf16 v[86:89], v[182:185], v[236:239], v[86:89]
	v_mfma_f32_16x16x32_bf16 v[82:85], v[190:193], v[236:239], v[82:85]
	v_mfma_f32_16x16x32_bf16 v[70:73], v[182:185], v[244:247], v[70:73]
	v_mfma_f32_16x16x32_bf16 v[66:69], v[190:193], v[244:247], v[66:69]
	s_barrier
	s_add_i32 s22, s28, s39
	v_lshl_add_u64 v[156:157], s[18:19], 0, v[0:1]
	s_mov_b32 m0, s22
	ds_read_b128 v[194:197], v160 offset:16384
	ds_read_b128 v[198:201], v160 offset:17408
	ds_read_b128 v[202:205], v160 offset:18432
	ds_read_b128 v[206:209], v160 offset:19456
	ds_read_b128 v[210:213], v160 offset:20480
	ds_read_b128 v[236:239], v160 offset:21504
	ds_read_b128 v[240:243], v160 offset:22528
	ds_read_b128 v[244:247], v160 offset:23552
	global_load_lds_dwordx4 v[156:157], off
	s_add_i32 m0, s22, 0x2000
	s_add_u32 s22, s18, 0x40000
	v_lshl_add_u64 v[214:215], s[18:19], 0, v[134:135]
	s_addc_u32 s23, s19, 0
	s_add_i32 s26, s33, s39
	global_load_lds_dwordx4 v[214:215], off
	v_lshl_add_u64 v[220:221], s[22:23], 0, v[0:1]
	s_mov_b32 m0, s26
	v_lshl_add_u64 v[222:223], s[20:21], 0, v[132:133]
	global_load_lds_dwordx4 v[220:221], off
	v_lshl_add_u64 v[220:221], s[22:23], 0, v[134:135]
	s_add_i32 m0, s26, 0x2000
	s_nop 0
	global_load_lds_dwordx4 v[220:221], off
	v_lshl_add_u64 v[220:221], s[20:21], 0, v[130:131]
	s_mov_b32 m0, s40
	s_nop 0
	global_load_lds_dwordx4 v[220:221], off
	s_mov_b32 m0, s41
	s_nop 0
	global_load_lds_dwordx4 v[222:223], off
	s_waitcnt vmcnt(8)
	s_waitcnt lgkmcnt(0)
	s_barrier
; #define PG8_STAGE(bufoff, gbase, voff) do { _Pragma("unroll") for (int _i = 0; _i < 2; ++_i) \
;         __builtin_amdgcn_global_load_lds((const unsigned*)((const char*)(gbase) + (voff)[_i]), (LAS unsigned*)(lds + (bufoff) + ldsw + _i * 8192), 16, 0, 0); } while (0)
; #define PG8_LDA(dst, b, h) do { _Pragma("unroll") for (int m = 0; m < 4; ++m) _Pragma("unroll") for (int k = 0; k < 2; ++k) dst[m][k] = *(const LAS bf16x8*)(lds + PG8_SA(b, h) + aoff + m * 2048 + k * 1024); } while (0)
; #define PG8_LDB(dst, b, h) do { _Pragma("unroll") for (int n = 0; n < 2; ++n) _Pragma("unroll") for (int k = 0; k < 2; ++k) dst[n][k] = *(const LAS bf16x8*)(lds + PG8_SB(b, h) + boff + n * 2048 + k * 1024); } while (0)
; #define PG8_MMA(ai, bj, At, Bt) do { __builtin_amdgcn_s_setprio(1); _Pragma("unroll") for (int m = 0; m < 4; ++m) _Pragma("unroll") for (int n = 0; n < 2; ++n) _Pragma("unroll") for (int k = 0; k < 2; ++k) \
;         acc[ai][bj][m][n] = __builtin_amdgcn_mfma_f32_16x16x32_bf16(Bt[n][k], At[m][k], acc[ai][bj][m][n], 0, 0, 0); __builtin_amdgcn_s_setprio(0); } while (0)
; #define PG8_WAIT_V(n) asm volatile("s_waitcnt vmcnt(" #n ")" ::: "memory")
; #define PG8_WAIT_L(n) asm volatile("s_waitcnt lgkmcnt(" #n ")" ::: "memory")
; #define PG8_BAR __builtin_amdgcn_s_barrier()
; #define PG8_SCHED __builtin_amdgcn_sched_barrier(0)
; template <class Epi, bool ALIGN_EPI, bool ASLOT = false>
; __device__ __forceinline__ void gemm_phase(LAS unsigned char* lds, const Gemm g, const Sched& S, const Epi& E) {
;     ...
;             PG8_WAIT_V(8); PG8_WAIT_L(0); PG8_BAR; PG8_MMA(1, 0, At, B0); PG8_MMA(1, 1, At, B1); PG8_BAR; PG8_SCHED;
;             PG8_LDB(B0, 1, 0); PG8_LDB(B1, 1, 1); PG8_SCHED; PG8_LDA(At, 1, 0); PG8_STAGE(PG8_SA(0, 1), a2 + hstep, voffA);
;             PG8_WAIT_V(8); PG8_WAIT_L(0); PG8_BAR; PG8_MMA(0, 0, At, B0); PG8_MMA(0, 1, At, B1); PG8_BAR; PG8_SCHED;
	s_waitcnt lgkmcnt(0)
	v_mfma_f32_16x16x32_bf16 v[62:65], v[162:165], v[194:197], v[62:65]
	v_mfma_f32_16x16x32_bf16 v[58:61], v[170:173], v[194:197], v[58:61]
	v_mfma_f32_16x16x32_bf16 v[46:49], v[162:165], v[202:205], v[46:49]
	v_mfma_f32_16x16x32_bf16 v[42:45], v[170:173], v[202:205], v[42:45]
	v_mfma_f32_16x16x32_bf16 v[30:33], v[162:165], v[210:213], v[30:33]
	v_mfma_f32_16x16x32_bf16 v[26:29], v[170:173], v[210:213], v[26:29]
	v_mfma_f32_16x16x32_bf16 v[14:17], v[162:165], v[240:243], v[14:17]
	v_mfma_f32_16x16x32_bf16 v[10:13], v[170:173], v[240:243], v[10:13]
	v_mfma_f32_16x16x32_bf16 v[62:65], v[166:169], v[198:201], v[62:65]
	v_mfma_f32_16x16x32_bf16 v[58:61], v[174:177], v[198:201], v[58:61]
	v_mfma_f32_16x16x32_bf16 v[46:49], v[166:169], v[206:209], v[46:49]
	v_mfma_f32_16x16x32_bf16 v[42:45], v[174:177], v[206:209], v[42:45]
	v_mfma_f32_16x16x32_bf16 v[30:33], v[166:169], v[236:239], v[30:33]
	v_mfma_f32_16x16x32_bf16 v[26:29], v[174:177], v[236:239], v[26:29]
	v_mfma_f32_16x16x32_bf16 v[14:17], v[166:169], v[244:247], v[14:17]
	v_mfma_f32_16x16x32_bf16 v[10:13], v[174:177], v[244:247], v[10:13]
	v_mfma_f32_16x16x32_bf16 v[54:57], v[178:181], v[194:197], v[54:57]
	v_mfma_f32_16x16x32_bf16 v[50:53], v[186:189], v[194:197], v[50:53]
	v_mfma_f32_16x16x32_bf16 v[38:41], v[178:181], v[202:205], v[38:41]
	v_mfma_f32_16x16x32_bf16 v[34:37], v[186:189], v[202:205], v[34:37]
	v_mfma_f32_16x16x32_bf16 v[22:25], v[178:181], v[210:213], v[22:25]
	v_mfma_f32_16x16x32_bf16 v[18:21], v[186:189], v[210:213], v[18:21]
	v_mfma_f32_16x16x32_bf16 v[6:9], v[178:181], v[240:243], v[6:9]
	v_mfma_f32_16x16x32_bf16 v[2:5], v[186:189], v[240:243], v[2:5]
	v_mfma_f32_16x16x32_bf16 v[54:57], v[182:185], v[198:201], v[54:57]
	v_mfma_f32_16x16x32_bf16 v[50:53], v[190:193], v[198:201], v[50:53]
	v_mfma_f32_16x16x32_bf16 v[38:41], v[182:185], v[206:209], v[38:41]
	v_mfma_f32_16x16x32_bf16 v[34:37], v[190:193], v[206:209], v[34:37]
	v_mfma_f32_16x16x32_bf16 v[22:25], v[182:185], v[236:239], v[22:25]
	v_mfma_f32_16x16x32_bf16 v[18:21], v[190:193], v[236:239], v[18:21]
	v_mfma_f32_16x16x32_bf16 v[6:9], v[182:185], v[244:247], v[6:9]
	v_mfma_f32_16x16x32_bf16 v[2:5], v[190:193], v[244:247], v[2:5]
	s_barrier
	s_add_i32 s29, 0, 0x18000
	v_add_u32_e32 v161, s29, v158
	s_add_i32 s26, 0, 0x1c000
	ds_read_b128 v[162:165], v161
	ds_read_b128 v[166:169], v161 offset:1024
	ds_read_b128 v[170:173], v161 offset:2048
	ds_read_b128 v[174:177], v161 offset:3072
	v_add_u32_e32 v161, s26, v158
	ds_read_b128 v[178:181], v161
	ds_read_b128 v[182:185], v161 offset:1024
	ds_read_b128 v[186:189], v161 offset:2048
	ds_read_b128 v[190:193], v161 offset:3072
	s_add_u32 s20, s20, 0x40000
	s_addc_u32 s21, s21, 0
	s_mov_b32 m0, s42
	v_lshl_add_u64 v[232:233], s[20:21], 0, v[130:131]
	ds_read_b128 v[194:197], v160 offset:32768
	ds_read_b128 v[198:201], v160 offset:33792
	ds_read_b128 v[202:205], v160 offset:34816
	ds_read_b128 v[206:209], v160 offset:35840
	ds_read_b128 v[210:213], v160 offset:36864
	ds_read_b128 v[236:239], v160 offset:37888
	ds_read_b128 v[240:243], v160 offset:38912
	ds_read_b128 v[244:247], v160 offset:39936
	global_load_lds_dwordx4 v[232:233], off
	v_lshl_add_u64 v[232:233], s[20:21], 0, v[132:133]
	s_mov_b32 m0, s43
	s_nop 0
	global_load_lds_dwordx4 v[232:233], off
	s_waitcnt vmcnt(8)
	s_waitcnt lgkmcnt(0)
	s_barrier
	s_waitcnt lgkmcnt(0)
	v_mfma_f32_16x16x32_bf16 v[126:129], v[162:165], v[194:197], v[126:129]
	v_mfma_f32_16x16x32_bf16 v[122:125], v[170:173], v[194:197], v[122:125]
	v_mfma_f32_16x16x32_bf16 v[110:113], v[162:165], v[202:205], v[110:113]
	v_mfma_f32_16x16x32_bf16 v[106:109], v[170:173], v[202:205], v[106:109]
	v_mfma_f32_16x16x32_bf16 v[94:97], v[162:165], v[210:213], v[94:97]
	v_mfma_f32_16x16x32_bf16 v[90:93], v[170:173], v[210:213], v[90:93]
	v_mfma_f32_16x16x32_bf16 v[78:81], v[162:165], v[240:243], v[78:81]
	v_mfma_f32_16x16x32_bf16 v[74:77], v[170:173], v[240:243], v[74:77]
	v_mfma_f32_16x16x32_bf16 v[126:129], v[166:169], v[198:201], v[126:129]
	v_mfma_f32_16x16x32_bf16 v[122:125], v[174:177], v[198:201], v[122:125]
	v_mfma_f32_16x16x32_bf16 v[110:113], v[166:169], v[206:209], v[110:113]
	v_mfma_f32_16x16x32_bf16 v[106:109], v[174:177], v[206:209], v[106:109]
	v_mfma_f32_16x16x32_bf16 v[94:97], v[166:169], v[236:239], v[94:97]
	v_mfma_f32_16x16x32_bf16 v[90:93], v[174:177], v[236:239], v[90:93]
	v_mfma_f32_16x16x32_bf16 v[78:81], v[166:169], v[244:247], v[78:81]
	v_mfma_f32_16x16x32_bf16 v[74:77], v[174:177], v[244:247], v[74:77]
	v_mfma_f32_16x16x32_bf16 v[118:121], v[178:181], v[194:197], v[118:121]
	v_mfma_f32_16x16x32_bf16 v[114:117], v[186:189], v[194:197], v[114:117]
	v_mfma_f32_16x16x32_bf16 v[102:105], v[178:181], v[202:205], v[102:105]
	v_mfma_f32_16x16x32_bf16 v[98:101], v[186:189], v[202:205], v[98:101]
	v_mfma_f32_16x16x32_bf16 v[86:89], v[178:181], v[210:213], v[86:89]
	v_mfma_f32_16x16x32_bf16 v[82:85], v[186:189], v[210:213], v[82:85]
	v_mfma_f32_16x16x32_bf16 v[70:73], v[178:181], v[240:243], v[70:73]
	v_mfma_f32_16x16x32_bf16 v[66:69], v[186:189], v[240:243], v[66:69]
	v_mfma_f32_16x16x32_bf16 v[118:121], v[182:185], v[198:201], v[118:121]
	v_mfma_f32_16x16x32_bf16 v[114:117], v[190:193], v[198:201], v[114:117]
	v_mfma_f32_16x16x32_bf16 v[102:105], v[182:185], v[206:209], v[102:105]
	v_mfma_f32_16x16x32_bf16 v[98:101], v[190:193], v[206:209], v[98:101]
	v_mfma_f32_16x16x32_bf16 v[86:89], v[182:185], v[236:239], v[86:89]
	v_mfma_f32_16x16x32_bf16 v[82:85], v[190:193], v[236:239], v[82:85]
	v_mfma_f32_16x16x32_bf16 v[70:73], v[182:185], v[244:247], v[70:73]
	v_mfma_f32_16x16x32_bf16 v[66:69], v[190:193], v[244:247], v[66:69]
	s_barrier
; #define PG8_STAGE(bufoff, gbase, voff) do { _Pragma("unroll") for (int _i = 0; _i < 2; ++_i) \
;         __builtin_amdgcn_global_load_lds((const unsigned*)((const char*)(gbase) + (voff)[_i]), (LAS unsigned*)(lds + (bufoff) + ldsw + _i * 8192), 16, 0, 0); } while (0)
; #define PG8_LDA(dst, b, h) do { _Pragma("unroll") for (int m = 0; m < 4; ++m) _Pragma("unroll") for (int k = 0; k < 2; ++k) dst[m][k] = *(const LAS bf16x8*)(lds + PG8_SA(b, h) + aoff + m * 2048 + k * 1024); } while (0)
; #define PG8_MMA(ai, bj, At, Bt) do { __builtin_amdgcn_s_setprio(1); _Pragma("unroll") for (int m = 0; m < 4; ++m) _Pragma("unroll") for (int n = 0; n < 2; ++n) _Pragma("unroll") for (int k = 0; k < 2; ++k) \
;         acc[ai][bj][m][n] = __builtin_amdgcn_mfma_f32_16x16x32_bf16(Bt[n][k], At[m][k], acc[ai][bj][m][n], 0, 0, 0); __builtin_amdgcn_s_setprio(0); } while (0)
; #define PG8_WAIT_V(n) asm volatile("s_waitcnt vmcnt(" #n ")" ::: "memory")
; #define PG8_WAIT_L(n) asm volatile("s_waitcnt lgkmcnt(" #n ")" ::: "memory")
; #define PG8_BAR __builtin_amdgcn_s_barrier()
; #define PG8_SCHED __builtin_amdgcn_sched_barrier(0)
; template <class Epi, bool ALIGN_EPI, bool ASLOT = false>
; __device__ __forceinline__ void gemm_phase(LAS unsigned char* lds, const Gemm g, const Sched& S, const Epi& E) {
;     ...
;             PG8_LDA(At, 1, 1); PG8_STAGE(PG8_SB(1, 0), b3, voffB); PG8_STAGE(PG8_SB(1, 1), b3 + hstep, voffB); PG8_STAGE(PG8_SA(1, 0), a3, voffA);
;             PG8_WAIT_V(8); PG8_WAIT_L(0); PG8_BAR; PG8_MMA(1, 0, At, B0); PG8_MMA(1, 1, At, B1); PG8_BAR; PG8_SCHED;
;         }
;         if constexpr (ALIGN_EPI) { if (wr == 0) PG8_BAR; }
	s_add_i32 s20, s29, s39
	v_lshl_add_u64 v[156:157], v[156:157], 0, s[16:17]
	s_mov_b32 m0, s20
	ds_read_b128 v[194:197], v160 offset:49152
	ds_read_b128 v[198:201], v160 offset:50176
	ds_read_b128 v[202:205], v160 offset:51200
	ds_read_b128 v[206:209], v160 offset:52224
	ds_read_b128 v[210:213], v160 offset:53248
	ds_read_b128 v[236:239], v160 offset:54272
	ds_read_b128 v[240:243], v160 offset:55296
	ds_read_b128 v[244:247], v160 offset:56320
	global_load_lds_dwordx4 v[156:157], off
	s_add_i32 m0, s20, 0x2000
	s_add_u32 s18, s18, 0x40080
	v_lshl_add_u64 v[156:157], v[214:215], 0, s[16:17]
	s_addc_u32 s19, s19, 0
	s_add_i32 s20, s26, s39
	global_load_lds_dwordx4 v[156:157], off
	v_lshl_add_u64 v[156:157], s[18:19], 0, v[0:1]
	s_mov_b32 m0, s20
	s_nop 0
	global_load_lds_dwordx4 v[156:157], off
	v_lshl_add_u64 v[156:157], s[18:19], 0, v[134:135]
	s_add_i32 m0, s20, 0x2000
	s_nop 0
	global_load_lds_dwordx4 v[156:157], off
	v_lshl_add_u64 v[156:157], v[220:221], 0, s[16:17]
	s_mov_b32 m0, s44
	s_nop 0
	global_load_lds_dwordx4 v[156:157], off
	v_lshl_add_u64 v[156:157], v[222:223], 0, s[16:17]
	s_mov_b32 m0, s45
	s_nop 0
	global_load_lds_dwordx4 v[156:157], off
	s_waitcnt vmcnt(8)
	s_waitcnt lgkmcnt(0)
	s_barrier
	s_waitcnt lgkmcnt(0)
	v_mfma_f32_16x16x32_bf16 v[62:65], v[162:165], v[194:197], v[62:65]
	v_mfma_f32_16x16x32_bf16 v[58:61], v[170:173], v[194:197], v[58:61]
	v_mfma_f32_16x16x32_bf16 v[46:49], v[162:165], v[202:205], v[46:49]
	v_mfma_f32_16x16x32_bf16 v[42:45], v[170:173], v[202:205], v[42:45]
	v_mfma_f32_16x16x32_bf16 v[30:33], v[162:165], v[210:213], v[30:33]
	v_mfma_f32_16x16x32_bf16 v[26:29], v[170:173], v[210:213], v[26:29]
	v_mfma_f32_16x16x32_bf16 v[14:17], v[162:165], v[240:243], v[14:17]
	v_mfma_f32_16x16x32_bf16 v[10:13], v[170:173], v[240:243], v[10:13]
	v_mfma_f32_16x16x32_bf16 v[62:65], v[166:169], v[198:201], v[62:65]
	v_mfma_f32_16x16x32_bf16 v[58:61], v[174:177], v[198:201], v[58:61]
	v_mfma_f32_16x16x32_bf16 v[46:49], v[166:169], v[206:209], v[46:49]
	v_mfma_f32_16x16x32_bf16 v[42:45], v[174:177], v[206:209], v[42:45]
	v_mfma_f32_16x16x32_bf16 v[30:33], v[166:169], v[236:239], v[30:33]
	v_mfma_f32_16x16x32_bf16 v[26:29], v[174:177], v[236:239], v[26:29]
	v_mfma_f32_16x16x32_bf16 v[14:17], v[166:169], v[244:247], v[14:17]
	v_mfma_f32_16x16x32_bf16 v[10:13], v[174:177], v[244:247], v[10:13]
	v_mfma_f32_16x16x32_bf16 v[54:57], v[178:181], v[194:197], v[54:57]
	v_mfma_f32_16x16x32_bf16 v[50:53], v[186:189], v[194:197], v[50:53]
	v_mfma_f32_16x16x32_bf16 v[38:41], v[178:181], v[202:205], v[38:41]
	v_mfma_f32_16x16x32_bf16 v[34:37], v[186:189], v[202:205], v[34:37]
	v_mfma_f32_16x16x32_bf16 v[22:25], v[178:181], v[210:213], v[22:25]
	v_mfma_f32_16x16x32_bf16 v[18:21], v[186:189], v[210:213], v[18:21]
	v_mfma_f32_16x16x32_bf16 v[6:9], v[178:181], v[240:243], v[6:9]
	v_mfma_f32_16x16x32_bf16 v[2:5], v[186:189], v[240:243], v[2:5]
	v_mfma_f32_16x16x32_bf16 v[54:57], v[182:185], v[198:201], v[54:57]
	v_mfma_f32_16x16x32_bf16 v[50:53], v[190:193], v[198:201], v[50:53]
	v_mfma_f32_16x16x32_bf16 v[38:41], v[182:185], v[206:209], v[38:41]
	v_mfma_f32_16x16x32_bf16 v[34:37], v[190:193], v[206:209], v[34:37]
	v_mfma_f32_16x16x32_bf16 v[22:25], v[182:185], v[236:239], v[22:25]
	v_mfma_f32_16x16x32_bf16 v[18:21], v[190:193], v[236:239], v[18:21]
	v_mfma_f32_16x16x32_bf16 v[6:9], v[182:185], v[244:247], v[6:9]
	v_mfma_f32_16x16x32_bf16 v[2:5], v[190:193], v[244:247], v[2:5]
	s_barrier
	s_add_i32 s48, s48, 2
	s_add_u32 s14, s14, 0x100
	s_addc_u32 s15, s15, 0
	s_add_u32 s46, s46, 0x100
	s_addc_u32 s47, s47, 0
	s_cmp_gt_u32 s48, 13
	s_cbranch_scc0 .LBB0_122
	s_and_b64 vcc, exec, s[4:5]
	s_cbranch_vccz .LBB0_125
	s_barrier

; #define PG8_STAGE(bufoff, gbase, voff) do { _Pragma("unroll") for (int _i = 0; _i < 2; ++_i) \
;         __builtin_amdgcn_global_load_lds((const unsigned*)((const char*)(gbase) + (voff)[_i]), (LAS unsigned*)(lds + (bufoff) + ldsw + _i * 8192), 16, 0, 0); } while (0)
; #define PG8_LDA(dst, b, h) do { _Pragma("unroll") for (int m = 0; m < 4; ++m) _Pragma("unroll") for (int k = 0; k < 2; ++k) dst[m][k] = *(const LAS bf16x8*)(lds + PG8_SA(b, h) + aoff + m * 2048 + k * 1024); } while (0)
; #define PG8_LDB(dst, b, h) do { _Pragma("unroll") for (int n = 0; n < 2; ++n) _Pragma("unroll") for (int k = 0; k < 2; ++k) dst[n][k] = *(const LAS bf16x8*)(lds + PG8_SB(b, h) + boff + n * 2048 + k * 1024); } while (0)
; #define PG8_MMA(ai, bj, At, Bt) do { __builtin_amdgcn_s_setprio(1); _Pragma("unroll") for (int m = 0; m < 4; ++m) _Pragma("unroll") for (int n = 0; n < 2; ++n) _Pragma("unroll") for (int k = 0; k < 2; ++k) \
;         acc[ai][bj][m][n] = __builtin_amdgcn_mfma_f32_16x16x32_bf16(Bt[n][k], At[m][k], acc[ai][bj][m][n], 0, 0, 0); __builtin_amdgcn_s_setprio(0); } while (0)
; #define PG8_WAIT_V(n) asm volatile("s_waitcnt vmcnt(" #n ")" ::: "memory")
; #define PG8_WAIT_L(n) asm volatile("s_waitcnt lgkmcnt(" #n ")" ::: "memory")
; #define PG8_BAR __builtin_amdgcn_s_barrier()
; #define PG8_SCHED __builtin_amdgcn_sched_barrier(0)
; template <class Epi, bool ALIGN_EPI, bool ASLOT = false>
; __device__ __forceinline__ void gemm_phase(LAS unsigned char* lds, const Gemm g, const Sched& S, const Epi& E) {
;     ...
;             const bool last = (t == nt - 2);
;             const char* a1 = cA + (size_t)(t + 1) * kstep;
;             const char* a2 = last ? nA : cA + (size_t)(t + 2) * kstep; const char* b2 = last ? nB : cB + (size_t)(t + 2) * kstep;
;             const char* a3 = a2 + kstep; const char* b3 = b2 + kstep;
;             PG8_LDB(B0, 0, 0); PG8_LDB(B1, 0, 1); PG8_SCHED; PG8_LDA(At, 0, 0); PG8_STAGE(PG8_SA(1, 1), a1 + hstep, voffA);
;             PG8_WAIT_V(8); PG8_WAIT_L(0); PG8_BAR; PG8_MMA(0, 0, At, B0); PG8_MMA(0, 1, At, B1); PG8_BAR; PG8_SCHED;
;             PG8_LDA(At, 0, 1); PG8_STAGE(PG8_SB(0, 0), b2, voffB); PG8_STAGE(PG8_SB(0, 1), b2 + hstep, voffB); PG8_STAGE(PG8_SA(0, 0), a2, voffA);
.LBB0_140:
	v_add_u32_e32 v156, s28, v141
	v_add_u32_e32 v172, s33, v141
	ds_read_b128 v[144:147], v156
	ds_read_b128 v[148:151], v156 offset:1024
	ds_read_b128 v[152:155], v156 offset:2048
	ds_read_b128 v[156:159], v156 offset:3072
	ds_read_b128 v[160:163], v172
	ds_read_b128 v[164:167], v172 offset:1024
	ds_read_b128 v[168:171], v172 offset:2048
	ds_read_b128 v[172:175], v172 offset:3072
	s_add_u32 s18, s44, 0xfffc0080
	s_addc_u32 s19, s45, -1
	s_cmp_eq_u32 s50, 12
	s_cselect_b32 s21, s11, s19
	s_cselect_b32 s20, s13, s18
	s_cselect_b32 s19, s39, s49
	s_cselect_b32 s18, s38, s15
	v_lshl_add_u64 v[208:209], s[44:45], 0, v[136:137]
	s_add_i32 m0, s3, 0xc000
	ds_read_b128 v[176:179], v143
	ds_read_b128 v[180:183], v143 offset:1024
	ds_read_b128 v[184:187], v143 offset:2048
	ds_read_b128 v[188:191], v143 offset:3072
	ds_read_b128 v[192:195], v143 offset:4096
	ds_read_b128 v[196:199], v143 offset:5120
	ds_read_b128 v[200:203], v143 offset:6144
	ds_read_b128 v[204:207], v143 offset:7168
	global_load_lds_dwordx4 v[208:209], off
	v_lshl_add_u64 v[208:209], s[44:45], 0, v[138:139]
	s_add_i32 m0, s3, 0xe000
	s_nop 0
	global_load_lds_dwordx4 v[208:209], off
	s_waitcnt vmcnt(8)
	s_waitcnt lgkmcnt(0)
	s_barrier
	s_waitcnt lgkmcnt(0)
	v_mfma_f32_16x16x32_bf16 v[126:129], v[144:147], v[176:179], v[126:129]
	v_mfma_f32_16x16x32_bf16 v[122:125], v[152:155], v[176:179], v[122:125]
	v_mfma_f32_16x16x32_bf16 v[118:121], v[144:147], v[184:187], v[118:121]
	v_mfma_f32_16x16x32_bf16 v[114:117], v[152:155], v[184:187], v[114:117]
	v_mfma_f32_16x16x32_bf16 v[102:105], v[144:147], v[192:195], v[102:105]
	v_mfma_f32_16x16x32_bf16 v[98:101], v[152:155], v[192:195], v[98:101]
	v_mfma_f32_16x16x32_bf16 v[86:89], v[144:147], v[200:203], v[86:89]
	v_mfma_f32_16x16x32_bf16 v[82:85], v[152:155], v[200:203], v[82:85]
	v_mfma_f32_16x16x32_bf16 v[126:129], v[148:151], v[180:183], v[126:129]
	v_mfma_f32_16x16x32_bf16 v[122:125], v[156:159], v[180:183], v[122:125]
	v_mfma_f32_16x16x32_bf16 v[118:121], v[148:151], v[188:191], v[118:121]
	v_mfma_f32_16x16x32_bf16 v[114:117], v[156:159], v[188:191], v[114:117]
	v_mfma_f32_16x16x32_bf16 v[102:105], v[148:151], v[196:199], v[102:105]
	v_mfma_f32_16x16x32_bf16 v[98:101], v[156:159], v[196:199], v[98:101]
	v_mfma_f32_16x16x32_bf16 v[86:89], v[148:151], v[204:207], v[86:89]
	v_mfma_f32_16x16x32_bf16 v[82:85], v[156:159], v[204:207], v[82:85]
	v_mfma_f32_16x16x32_bf16 v[110:113], v[160:163], v[176:179], v[110:113]
	v_mfma_f32_16x16x32_bf16 v[106:109], v[168:171], v[176:179], v[106:109]
	v_mfma_f32_16x16x32_bf16 v[94:97], v[160:163], v[184:187], v[94:97]
	v_mfma_f32_16x16x32_bf16 v[90:93], v[168:171], v[184:187], v[90:93]
	v_mfma_f32_16x16x32_bf16 v[78:81], v[160:163], v[192:195], v[78:81]
	v_mfma_f32_16x16x32_bf16 v[74:77], v[168:171], v[192:195], v[74:77]
	v_mfma_f32_16x16x32_bf16 v[70:73], v[160:163], v[200:203], v[70:73]
	v_mfma_f32_16x16x32_bf16 v[66:69], v[168:171], v[200:203], v[66:69]
	v_mfma_f32_16x16x32_bf16 v[110:113], v[164:167], v[180:183], v[110:113]
	v_mfma_f32_16x16x32_bf16 v[106:109], v[172:175], v[180:183], v[106:109]
	v_mfma_f32_16x16x32_bf16 v[94:97], v[164:167], v[188:191], v[94:97]
	v_mfma_f32_16x16x32_bf16 v[90:93], v[172:175], v[188:191], v[90:93]
	v_mfma_f32_16x16x32_bf16 v[78:81], v[164:167], v[196:199], v[78:81]
	v_mfma_f32_16x16x32_bf16 v[74:77], v[172:175], v[196:199], v[74:77]
	v_mfma_f32_16x16x32_bf16 v[70:73], v[164:167], v[204:207], v[70:73]
	v_mfma_f32_16x16x32_bf16 v[66:69], v[172:175], v[204:207], v[66:69]
	s_barrier
	s_add_i32 s22, s28, s2
	v_lshl_add_u64 v[208:209], s[18:19], 0, v[0:1]
	s_mov_b32 m0, s22
	ds_read_b128 v[176:179], v143 offset:16384
	ds_read_b128 v[180:183], v143 offset:17408
	ds_read_b128 v[184:187], v143 offset:18432
	ds_read_b128 v[188:191], v143 offset:19456
	ds_read_b128 v[192:195], v143 offset:20480
	ds_read_b128 v[196:199], v143 offset:21504
	ds_read_b128 v[200:203], v143 offset:22528
	ds_read_b128 v[204:207], v143 offset:23552
	global_load_lds_dwordx4 v[208:209], off
	s_add_i32 m0, s22, 0x2000
	s_add_u32 s22, s18, 0x40000
	v_lshl_add_u64 v[210:211], s[18:19], 0, v[130:131]
	s_addc_u32 s23, s19, 0
	s_add_i32 s30, s33, s2
	global_load_lds_dwordx4 v[210:211], off
	v_lshl_add_u64 v[212:213], s[22:23], 0, v[0:1]
	s_mov_b32 m0, s30
	v_lshl_add_u64 v[214:215], s[20:21], 0, v[132:133]
	global_load_lds_dwordx4 v[212:213], off
	v_lshl_add_u64 v[212:213], s[22:23], 0, v[130:131]
	s_add_i32 m0, s30, 0x2000
	s_nop 0
	global_load_lds_dwordx4 v[212:213], off
	v_lshl_add_u64 v[212:213], s[20:21], 0, v[134:135]
	s_mov_b32 m0, s3
	s_nop 0
	global_load_lds_dwordx4 v[212:213], off
	s_mov_b32 m0, s24
	s_nop 0
	global_load_lds_dwordx4 v[214:215], off
	s_waitcnt vmcnt(8)
	s_waitcnt lgkmcnt(0)
	s_barrier
; #define PG8_STAGE(bufoff, gbase, voff) do { _Pragma("unroll") for (int _i = 0; _i < 2; ++_i) \
;         __builtin_amdgcn_global_load_lds((const unsigned*)((const char*)(gbase) + (voff)[_i]), (LAS unsigned*)(lds + (bufoff) + ldsw + _i * 8192), 16, 0, 0); } while (0)
; #define PG8_LDA(dst, b, h) do { _Pragma("unroll") for (int m = 0; m < 4; ++m) _Pragma("unroll") for (int k = 0; k < 2; ++k) dst[m][k] = *(const LAS bf16x8*)(lds + PG8_SA(b, h) + aoff + m * 2048 + k * 1024); } while (0)
; #define PG8_LDB(dst, b, h) do { _Pragma("unroll") for (int n = 0; n < 2; ++n) _Pragma("unroll") for (int k = 0; k < 2; ++k) dst[n][k] = *(const LAS bf16x8*)(lds + PG8_SB(b, h) + boff + n * 2048 + k * 1024); } while (0)
; #define PG8_MMA(ai, bj, At, Bt) do { __builtin_amdgcn_s_setprio(1); _Pragma("unroll") for (int m = 0; m < 4; ++m) _Pragma("unroll") for (int n = 0; n < 2; ++n) _Pragma("unroll") for (int k = 0; k < 2; ++k) \
;         acc[ai][bj][m][n] = __builtin_amdgcn_mfma_f32_16x16x32_bf16(Bt[n][k], At[m][k], acc[ai][bj][m][n], 0, 0, 0); __builtin_amdgcn_s_setprio(0); } while (0)
; #define PG8_WAIT_V(n) asm volatile("s_waitcnt vmcnt(" #n ")" ::: "memory")
; template <class Epi, bool ALIGN_EPI, bool ASLOT = false>
; __device__ __forceinline__ void gemm_phase(LAS unsigned char* lds, const Gemm g, const Sched& S, const Epi& E) {
;     ...
;             PG8_LDB(B0, 0, 0); PG8_LDB(B1, 0, 1); PG8_SCHED; PG8_LDA(At, 0, 0); PG8_STAGE(PG8_SA(1, 1), a1 + hstep, voffA);
;             PG8_WAIT_V(8); PG8_WAIT_L(0); PG8_BAR; PG8_MMA(0, 0, At, B0); PG8_MMA(0, 1, At, B1); PG8_BAR; PG8_SCHED;
;             PG8_LDA(At, 0, 1); PG8_STAGE(PG8_SB(0, 0), b2, voffB); PG8_STAGE(PG8_SB(0, 1), b2 + hstep, voffB); PG8_STAGE(PG8_SA(0, 0), a2, voffA);
;             PG8_WAIT_V(8); PG8_WAIT_L(0); PG8_BAR; PG8_MMA(1, 0, At, B0); PG8_MMA(1, 1, At, B1); PG8_BAR; PG8_SCHED;
;             PG8_LDB(B0, 1, 0); PG8_LDB(B1, 1, 1); PG8_SCHED; PG8_LDA(At, 1, 0); PG8_STAGE(PG8_SA(0, 1), a2 + hstep, voffA);
;             PG8_WAIT_V(8); PG8_WAIT_L(0); PG8_BAR; PG8_MMA(0, 0, At, B0); PG8_MMA(0, 1, At, B1); PG8_BAR; PG8_SCHED;
;             PG8_LDA(At, 1, 1); PG8_STAGE(PG8_SB(1, 0), b3, voffB); PG8_STAGE(PG8_SB(1, 1), b3 + hstep, voffB); PG8_STAGE(PG8_SA(1, 0), a3, voffA);
;             PG8_WAIT_V(8); PG8_WAIT_L(0); PG8_BAR; PG8_MMA(1, 0, At, B0); PG8_MMA(1, 1, At, B1); PG8_BAR; PG8_SCHED;
	s_waitcnt lgkmcnt(0)
	v_mfma_f32_16x16x32_bf16 v[62:65], v[144:147], v[176:179], v[62:65]
	v_mfma_f32_16x16x32_bf16 v[58:61], v[152:155], v[176:179], v[58:61]
	v_mfma_f32_16x16x32_bf16 v[54:57], v[144:147], v[184:187], v[54:57]
	v_mfma_f32_16x16x32_bf16 v[50:53], v[152:155], v[184:187], v[50:53]
	v_mfma_f32_16x16x32_bf16 v[38:41], v[144:147], v[192:195], v[38:41]
	v_mfma_f32_16x16x32_bf16 v[34:37], v[152:155], v[192:195], v[34:37]
	v_mfma_f32_16x16x32_bf16 v[22:25], v[144:147], v[200:203], v[22:25]
	v_mfma_f32_16x16x32_bf16 v[18:21], v[152:155], v[200:203], v[18:21]
	v_mfma_f32_16x16x32_bf16 v[62:65], v[148:151], v[180:183], v[62:65]
	v_mfma_f32_16x16x32_bf16 v[58:61], v[156:159], v[180:183], v[58:61]
	v_mfma_f32_16x16x32_bf16 v[54:57], v[148:151], v[188:191], v[54:57]
	v_mfma_f32_16x16x32_bf16 v[50:53], v[156:159], v[188:191], v[50:53]
	v_mfma_f32_16x16x32_bf16 v[38:41], v[148:151], v[196:199], v[38:41]
	v_mfma_f32_16x16x32_bf16 v[34:37], v[156:159], v[196:199], v[34:37]
	v_mfma_f32_16x16x32_bf16 v[22:25], v[148:151], v[204:207], v[22:25]
	v_mfma_f32_16x16x32_bf16 v[18:21], v[156:159], v[204:207], v[18:21]
	v_mfma_f32_16x16x32_bf16 v[46:49], v[160:163], v[176:179], v[46:49]
	v_mfma_f32_16x16x32_bf16 v[42:45], v[168:171], v[176:179], v[42:45]
	v_mfma_f32_16x16x32_bf16 v[30:33], v[160:163], v[184:187], v[30:33]
	v_mfma_f32_16x16x32_bf16 v[26:29], v[168:171], v[184:187], v[26:29]
	v_mfma_f32_16x16x32_bf16 v[14:17], v[160:163], v[192:195], v[14:17]
	v_mfma_f32_16x16x32_bf16 v[10:13], v[168:171], v[192:195], v[10:13]
	v_mfma_f32_16x16x32_bf16 v[6:9], v[160:163], v[200:203], v[6:9]
	v_mfma_f32_16x16x32_bf16 v[2:5], v[168:171], v[200:203], v[2:5]
	v_mfma_f32_16x16x32_bf16 v[46:49], v[164:167], v[180:183], v[46:49]
	v_mfma_f32_16x16x32_bf16 v[42:45], v[172:175], v[180:183], v[42:45]
	v_mfma_f32_16x16x32_bf16 v[30:33], v[164:167], v[188:191], v[30:33]
	v_mfma_f32_16x16x32_bf16 v[26:29], v[172:175], v[188:191], v[26:29]
	v_mfma_f32_16x16x32_bf16 v[14:17], v[164:167], v[196:199], v[14:17]
	v_mfma_f32_16x16x32_bf16 v[10:13], v[172:175], v[196:199], v[10:13]
	v_mfma_f32_16x16x32_bf16 v[6:9], v[164:167], v[204:207], v[6:9]
	v_mfma_f32_16x16x32_bf16 v[2:5], v[172:175], v[204:207], v[2:5]
	s_barrier
	v_add_u32_e32 v156, s29, v141
	v_add_u32_e32 v172, s26, v141
	ds_read_b128 v[144:147], v156
	ds_read_b128 v[148:151], v156 offset:1024
	ds_read_b128 v[152:155], v156 offset:2048
	ds_read_b128 v[156:159], v156 offset:3072
	ds_read_b128 v[160:163], v172
	ds_read_b128 v[164:167], v172 offset:1024
	ds_read_b128 v[168:171], v172 offset:2048
	ds_read_b128 v[172:175], v172 offset:3072
	s_add_u32 s20, s20, 0x40000
	s_addc_u32 s21, s21, 0
	s_mov_b32 m0, s25
	v_lshl_add_u64 v[220:221], s[20:21], 0, v[134:135]
	ds_read_b128 v[176:179], v143 offset:32768
	ds_read_b128 v[180:183], v143 offset:33792
	ds_read_b128 v[184:187], v143 offset:34816
	ds_read_b128 v[188:191], v143 offset:35840
	ds_read_b128 v[192:195], v143 offset:36864
	ds_read_b128 v[196:199], v143 offset:37888
	ds_read_b128 v[200:203], v143 offset:38912
	ds_read_b128 v[204:207], v143 offset:39936
	global_load_lds_dwordx4 v[220:221], off
	v_lshl_add_u64 v[220:221], s[20:21], 0, v[132:133]
	s_mov_b32 m0, s27
	s_nop 0
	global_load_lds_dwordx4 v[220:221], off
	s_waitcnt vmcnt(8)
	s_waitcnt lgkmcnt(0)
	s_barrier
	s_waitcnt lgkmcnt(0)
	v_mfma_f32_16x16x32_bf16 v[126:129], v[144:147], v[176:179], v[126:129]
	v_mfma_f32_16x16x32_bf16 v[122:125], v[152:155], v[176:179], v[122:125]
	v_mfma_f32_16x16x32_bf16 v[118:121], v[144:147], v[184:187], v[118:121]
	v_mfma_f32_16x16x32_bf16 v[114:117], v[152:155], v[184:187], v[114:117]
	v_mfma_f32_16x16x32_bf16 v[102:105], v[144:147], v[192:195], v[102:105]
	v_mfma_f32_16x16x32_bf16 v[98:101], v[152:155], v[192:195], v[98:101]
	v_mfma_f32_16x16x32_bf16 v[86:89], v[144:147], v[200:203], v[86:89]
	v_mfma_f32_16x16x32_bf16 v[82:85], v[152:155], v[200:203], v[82:85]
	v_mfma_f32_16x16x32_bf16 v[126:129], v[148:151], v[180:183], v[126:129]
	v_mfma_f32_16x16x32_bf16 v[122:125], v[156:159], v[180:183], v[122:125]
	v_mfma_f32_16x16x32_bf16 v[118:121], v[148:151], v[188:191], v[118:121]
	v_mfma_f32_16x16x32_bf16 v[114:117], v[156:159], v[188:191], v[114:117]
	v_mfma_f32_16x16x32_bf16 v[102:105], v[148:151], v[196:199], v[102:105]
	v_mfma_f32_16x16x32_bf16 v[98:101], v[156:159], v[196:199], v[98:101]
	v_mfma_f32_16x16x32_bf16 v[86:89], v[148:151], v[204:207], v[86:89]
	v_mfma_f32_16x16x32_bf16 v[82:85], v[156:159], v[204:207], v[82:85]
	v_mfma_f32_16x16x32_bf16 v[110:113], v[160:163], v[176:179], v[110:113]
	v_mfma_f32_16x16x32_bf16 v[106:109], v[168:171], v[176:179], v[106:109]
	v_mfma_f32_16x16x32_bf16 v[94:97], v[160:163], v[184:187], v[94:97]
	v_mfma_f32_16x16x32_bf16 v[90:93], v[168:171], v[184:187], v[90:93]
	v_mfma_f32_16x16x32_bf16 v[78:81], v[160:163], v[192:195], v[78:81]
	v_mfma_f32_16x16x32_bf16 v[74:77], v[168:171], v[192:195], v[74:77]
	v_mfma_f32_16x16x32_bf16 v[70:73], v[160:163], v[200:203], v[70:73]
	v_mfma_f32_16x16x32_bf16 v[66:69], v[168:171], v[200:203], v[66:69]
	v_mfma_f32_16x16x32_bf16 v[110:113], v[164:167], v[180:183], v[110:113]
	v_mfma_f32_16x16x32_bf16 v[106:109], v[172:175], v[180:183], v[106:109]
	v_mfma_f32_16x16x32_bf16 v[94:97], v[164:167], v[188:191], v[94:97]
	v_mfma_f32_16x16x32_bf16 v[90:93], v[172:175], v[188:191], v[90:93]
	v_mfma_f32_16x16x32_bf16 v[78:81], v[164:167], v[196:199], v[78:81]
	v_mfma_f32_16x16x32_bf16 v[74:77], v[172:175], v[196:199], v[74:77]
	v_mfma_f32_16x16x32_bf16 v[70:73], v[164:167], v[204:207], v[70:73]
	v_mfma_f32_16x16x32_bf16 v[66:69], v[172:175], v[204:207], v[66:69]
	s_barrier
; #define PG8_STAGE(bufoff, gbase, voff) do { _Pragma("unroll") for (int _i = 0; _i < 2; ++_i) \
;         __builtin_amdgcn_global_load_lds((const unsigned*)((const char*)(gbase) + (voff)[_i]), (LAS unsigned*)(lds + (bufoff) + ldsw + _i * 8192), 16, 0, 0); } while (0)
; #define PG8_LDA(dst, b, h) do { _Pragma("unroll") for (int m = 0; m < 4; ++m) _Pragma("unroll") for (int k = 0; k < 2; ++k) dst[m][k] = *(const LAS bf16x8*)(lds + PG8_SA(b, h) + aoff + m * 2048 + k * 1024); } while (0)
; #define PG8_MMA(ai, bj, At, Bt) do { __builtin_amdgcn_s_setprio(1); _Pragma("unroll") for (int m = 0; m < 4; ++m) _Pragma("unroll") for (int n = 0; n < 2; ++n) _Pragma("unroll") for (int k = 0; k < 2; ++k) \
;         acc[ai][bj][m][n] = __builtin_amdgcn_mfma_f32_16x16x32_bf16(Bt[n][k], At[m][k], acc[ai][bj][m][n], 0, 0, 0); __builtin_amdgcn_s_setprio(0); } while (0)
; #define PG8_WAIT_V(n) asm volatile("s_waitcnt vmcnt(" #n ")" ::: "memory")
; #define PG8_WAIT_L(n) asm volatile("s_waitcnt lgkmcnt(" #n ")" ::: "memory")
; #define PG8_BAR __builtin_amdgcn_s_barrier()
; #define PG8_SCHED __builtin_amdgcn_sched_barrier(0)
; template <class Epi, bool ALIGN_EPI, bool ASLOT = false>
; __device__ __forceinline__ void gemm_phase(LAS unsigned char* lds, const Gemm g, const Sched& S, const Epi& E) {
;     ...
;             PG8_LDA(At, 1, 1); PG8_STAGE(PG8_SB(1, 0), b3, voffB); PG8_STAGE(PG8_SB(1, 1), b3 + hstep, voffB); PG8_STAGE(PG8_SA(1, 0), a3, voffA);
;             PG8_WAIT_V(8); PG8_WAIT_L(0); PG8_BAR; PG8_MMA(1, 0, At, B0); PG8_MMA(1, 1, At, B1); PG8_BAR; PG8_SCHED;
;         }
	s_add_i32 s20, s29, s2
	v_lshl_add_u64 v[208:209], v[208:209], 0, s[16:17]
	s_mov_b32 m0, s20
	ds_read_b128 v[176:179], v143 offset:49152
	ds_read_b128 v[180:183], v143 offset:50176
	ds_read_b128 v[184:187], v143 offset:51200
	ds_read_b128 v[188:191], v143 offset:52224
	ds_read_b128 v[192:195], v143 offset:53248
	ds_read_b128 v[196:199], v143 offset:54272
	ds_read_b128 v[200:203], v143 offset:55296
	ds_read_b128 v[204:207], v143 offset:56320
	global_load_lds_dwordx4 v[208:209], off
	s_add_i32 m0, s20, 0x2000
	s_add_u32 s18, s18, 0x40080
	v_lshl_add_u64 v[208:209], v[210:211], 0, s[16:17]
	s_addc_u32 s19, s19, 0
	s_add_i32 s20, s26, s2
	global_load_lds_dwordx4 v[208:209], off
	v_lshl_add_u64 v[208:209], s[18:19], 0, v[0:1]
	s_mov_b32 m0, s20
	s_nop 0
	global_load_lds_dwordx4 v[208:209], off
	v_lshl_add_u64 v[208:209], s[18:19], 0, v[130:131]
	s_add_i32 m0, s20, 0x2000
	s_nop 0
	global_load_lds_dwordx4 v[208:209], off
	v_lshl_add_u64 v[208:209], v[212:213], 0, s[16:17]
	s_mov_b32 m0, s46
	s_nop 0
	global_load_lds_dwordx4 v[208:209], off
	v_lshl_add_u64 v[208:209], v[214:215], 0, s[16:17]
	s_mov_b32 m0, s47
	s_nop 0
	global_load_lds_dwordx4 v[208:209], off
	s_waitcnt vmcnt(8)
	s_waitcnt lgkmcnt(0)
	s_barrier
	s_waitcnt lgkmcnt(0)
	v_mfma_f32_16x16x32_bf16 v[62:65], v[144:147], v[176:179], v[62:65]
	v_mfma_f32_16x16x32_bf16 v[58:61], v[152:155], v[176:179], v[58:61]
	v_mfma_f32_16x16x32_bf16 v[54:57], v[144:147], v[184:187], v[54:57]
	v_mfma_f32_16x16x32_bf16 v[50:53], v[152:155], v[184:187], v[50:53]
	v_mfma_f32_16x16x32_bf16 v[38:41], v[144:147], v[192:195], v[38:41]
	v_mfma_f32_16x16x32_bf16 v[34:37], v[152:155], v[192:195], v[34:37]
	v_mfma_f32_16x16x32_bf16 v[22:25], v[144:147], v[200:203], v[22:25]
	v_mfma_f32_16x16x32_bf16 v[18:21], v[152:155], v[200:203], v[18:21]
	v_mfma_f32_16x16x32_bf16 v[62:65], v[148:151], v[180:183], v[62:65]
	v_mfma_f32_16x16x32_bf16 v[58:61], v[156:159], v[180:183], v[58:61]
	v_mfma_f32_16x16x32_bf16 v[54:57], v[148:151], v[188:191], v[54:57]
	v_mfma_f32_16x16x32_bf16 v[50:53], v[156:159], v[188:191], v[50:53]
	v_mfma_f32_16x16x32_bf16 v[38:41], v[148:151], v[196:199], v[38:41]
	v_mfma_f32_16x16x32_bf16 v[34:37], v[156:159], v[196:199], v[34:37]
	v_mfma_f32_16x16x32_bf16 v[22:25], v[148:151], v[204:207], v[22:25]
	v_mfma_f32_16x16x32_bf16 v[18:21], v[156:159], v[204:207], v[18:21]
	v_mfma_f32_16x16x32_bf16 v[46:49], v[160:163], v[176:179], v[46:49]
	v_mfma_f32_16x16x32_bf16 v[42:45], v[168:171], v[176:179], v[42:45]
	v_mfma_f32_16x16x32_bf16 v[30:33], v[160:163], v[184:187], v[30:33]
	v_mfma_f32_16x16x32_bf16 v[26:29], v[168:171], v[184:187], v[26:29]
	v_mfma_f32_16x16x32_bf16 v[14:17], v[160:163], v[192:195], v[14:17]
	v_mfma_f32_16x16x32_bf16 v[10:13], v[168:171], v[192:195], v[10:13]
	v_mfma_f32_16x16x32_bf16 v[6:9], v[160:163], v[200:203], v[6:9]
	v_mfma_f32_16x16x32_bf16 v[2:5], v[168:171], v[200:203], v[2:5]
	v_mfma_f32_16x16x32_bf16 v[46:49], v[164:167], v[180:183], v[46:49]
	v_mfma_f32_16x16x32_bf16 v[42:45], v[172:175], v[180:183], v[42:45]
	v_mfma_f32_16x16x32_bf16 v[30:33], v[164:167], v[188:191], v[30:33]
	v_mfma_f32_16x16x32_bf16 v[26:29], v[172:175], v[188:191], v[26:29]
	v_mfma_f32_16x16x32_bf16 v[14:17], v[164:167], v[196:199], v[14:17]
	v_mfma_f32_16x16x32_bf16 v[10:13], v[172:175], v[196:199], v[10:13]
	v_mfma_f32_16x16x32_bf16 v[6:9], v[164:167], v[204:207], v[6:9]
	v_mfma_f32_16x16x32_bf16 v[2:5], v[172:175], v[204:207], v[2:5]
	s_barrier
	s_add_i32 s50, s50, 2
	s_add_u32 s44, s44, 0x100
	s_addc_u32 s45, s45, 0
	s_add_u32 s15, s15, 0x100
	s_addc_u32 s49, s49, 0
	s_cmp_gt_u32 s50, 13
	s_cbranch_scc0 .LBB0_140
	s_and_b64 vcc, exec, s[8:9]
	s_cbranch_vccz .LBB0_143
	s_barrier

; #define PG8_STAGE(bufoff, gbase, voff) do { _Pragma("unroll") for (int _i = 0; _i < 2; ++_i) \
;         __builtin_amdgcn_global_load_lds((const unsigned*)((const char*)(gbase) + (voff)[_i]), (LAS unsigned*)(lds + (bufoff) + ldsw + _i * 8192), 16, 0, 0); } while (0)
; #define PG8_LDA(dst, b, h) do { _Pragma("unroll") for (int m = 0; m < 4; ++m) _Pragma("unroll") for (int k = 0; k < 2; ++k) dst[m][k] = *(const LAS bf16x8*)(lds + PG8_SA(b, h) + aoff + m * 2048 + k * 1024); } while (0)
; #define PG8_LDB(dst, b, h) do { _Pragma("unroll") for (int n = 0; n < 2; ++n) _Pragma("unroll") for (int k = 0; k < 2; ++k) dst[n][k] = *(const LAS bf16x8*)(lds + PG8_SB(b, h) + boff + n * 2048 + k * 1024); } while (0)
; #define PG8_MMA(ai, bj, At, Bt) do { __builtin_amdgcn_s_setprio(1); _Pragma("unroll") for (int m = 0; m < 4; ++m) _Pragma("unroll") for (int n = 0; n < 2; ++n) _Pragma("unroll") for (int k = 0; k < 2; ++k) \
;         acc[ai][bj][m][n] = __builtin_amdgcn_mfma_f32_16x16x32_bf16(Bt[n][k], At[m][k], acc[ai][bj][m][n], 0, 0, 0); __builtin_amdgcn_s_setprio(0); } while (0)
; #define PG8_WAIT_V(n) asm volatile("s_waitcnt vmcnt(" #n ")" ::: "memory")
; #define PG8_WAIT_L(n) asm volatile("s_waitcnt lgkmcnt(" #n ")" ::: "memory")
; #define PG8_BAR __builtin_amdgcn_s_barrier()
; #define PG8_SCHED __builtin_amdgcn_sched_barrier(0)
; template <class Epi, bool ALIGN_EPI, bool ASLOT = false>
; __device__ __forceinline__ void gemm_phase(LAS unsigned char* lds, const Gemm g, const Sched& S, const Epi& E) {
;     ...
;         for (int t = 0; t < nt; t += 2) {
;             const bool last = (t == nt - 2);
;             const char* a1 = cA + (size_t)(t + 1) * kstep;
;             const char* a2 = last ? nA : cA + (size_t)(t + 2) * kstep; const char* b2 = last ? nB : cB + (size_t)(t + 2) * kstep;
;             const char* a3 = a2 + kstep; const char* b3 = b2 + kstep;
;             PG8_LDB(B0, 0, 0); PG8_LDB(B1, 0, 1); PG8_SCHED; PG8_LDA(At, 0, 0); PG8_STAGE(PG8_SA(1, 1), a1 + hstep, voffA);
;             PG8_WAIT_V(8); PG8_WAIT_L(0); PG8_BAR; PG8_MMA(0, 0, At, B0); PG8_MMA(0, 1, At, B1); PG8_BAR; PG8_SCHED;
;             PG8_LDA(At, 0, 1); PG8_STAGE(PG8_SB(0, 0), b2, voffB); PG8_STAGE(PG8_SB(0, 1), b2 + hstep, voffB); PG8_STAGE(PG8_SA(0, 0), a2, voffA);
;             PG8_WAIT_V(8); PG8_WAIT_L(0); PG8_BAR; PG8_MMA(1, 0, At, B0); PG8_MMA(1, 1, At, B1); PG8_BAR; PG8_SCHED;
.LBB0_175:
	v_add_u32_e32 v156, s28, v142
	v_add_u32_e32 v172, s33, v142
	s_add_u32 s12, s31, s10
	ds_read_b128 v[144:147], v156
	ds_read_b128 v[148:151], v156 offset:1024
	ds_read_b128 v[152:155], v156 offset:2048
	ds_read_b128 v[156:159], v156 offset:3072
	ds_read_b128 v[160:163], v172
	ds_read_b128 v[164:167], v172 offset:1024
	ds_read_b128 v[168:171], v172 offset:2048
	ds_read_b128 v[172:175], v172 offset:3072
	s_addc_u32 s13, s35, s11
	s_add_u32 s12, s12, 0x8800100
	s_addc_u32 s13, s13, 0
	s_add_u32 s22, s34, s10
	s_addc_u32 s23, s36, s11
	s_cmpk_eq_i32 s10, 0x1500
	s_cselect_b32 s15, s39, s13
	s_cselect_b32 s14, s38, s12
	s_cselect_b32 s13, s9, s23
	s_cselect_b32 s12, s8, s22
	v_lshl_add_u64 v[208:209], v[136:137], 0, s[10:11]
	s_add_i32 m0, s18, 0xc000
	ds_read_b128 v[176:179], v143
	ds_read_b128 v[180:183], v143 offset:1024
	ds_read_b128 v[184:187], v143 offset:2048
	ds_read_b128 v[188:191], v143 offset:3072
	ds_read_b128 v[192:195], v143 offset:4096
	ds_read_b128 v[196:199], v143 offset:5120
	ds_read_b128 v[200:203], v143 offset:6144
	ds_read_b128 v[204:207], v143 offset:7168
	global_load_lds_dwordx4 v[208:209], off
	v_lshl_add_u64 v[208:209], v[138:139], 0, s[10:11]
	s_add_i32 m0, s18, 0xe000
	s_nop 0
	global_load_lds_dwordx4 v[208:209], off
	s_waitcnt vmcnt(8)
	s_waitcnt lgkmcnt(0)
	s_barrier
	s_waitcnt lgkmcnt(0)
	v_mfma_f32_16x16x32_bf16 v[126:129], v[144:147], v[176:179], v[126:129]
	v_mfma_f32_16x16x32_bf16 v[122:125], v[152:155], v[176:179], v[122:125]
	v_mfma_f32_16x16x32_bf16 v[118:121], v[144:147], v[184:187], v[118:121]
	v_mfma_f32_16x16x32_bf16 v[114:117], v[152:155], v[184:187], v[114:117]
	v_mfma_f32_16x16x32_bf16 v[102:105], v[144:147], v[192:195], v[102:105]
	v_mfma_f32_16x16x32_bf16 v[98:101], v[152:155], v[192:195], v[98:101]
	v_mfma_f32_16x16x32_bf16 v[86:89], v[144:147], v[200:203], v[86:89]
	v_mfma_f32_16x16x32_bf16 v[82:85], v[152:155], v[200:203], v[82:85]
	v_mfma_f32_16x16x32_bf16 v[126:129], v[148:151], v[180:183], v[126:129]
	v_mfma_f32_16x16x32_bf16 v[122:125], v[156:159], v[180:183], v[122:125]
	v_mfma_f32_16x16x32_bf16 v[118:121], v[148:151], v[188:191], v[118:121]
	v_mfma_f32_16x16x32_bf16 v[114:117], v[156:159], v[188:191], v[114:117]
	v_mfma_f32_16x16x32_bf16 v[102:105], v[148:151], v[196:199], v[102:105]
	v_mfma_f32_16x16x32_bf16 v[98:101], v[156:159], v[196:199], v[98:101]
	v_mfma_f32_16x16x32_bf16 v[86:89], v[148:151], v[204:207], v[86:89]
	v_mfma_f32_16x16x32_bf16 v[82:85], v[156:159], v[204:207], v[82:85]
	v_mfma_f32_16x16x32_bf16 v[110:113], v[160:163], v[176:179], v[110:113]
	v_mfma_f32_16x16x32_bf16 v[106:109], v[168:171], v[176:179], v[106:109]
	v_mfma_f32_16x16x32_bf16 v[94:97], v[160:163], v[184:187], v[94:97]
	v_mfma_f32_16x16x32_bf16 v[90:93], v[168:171], v[184:187], v[90:93]
	v_mfma_f32_16x16x32_bf16 v[78:81], v[160:163], v[192:195], v[78:81]
	v_mfma_f32_16x16x32_bf16 v[74:77], v[168:171], v[192:195], v[74:77]
	v_mfma_f32_16x16x32_bf16 v[70:73], v[160:163], v[200:203], v[70:73]
	v_mfma_f32_16x16x32_bf16 v[66:69], v[168:171], v[200:203], v[66:69]
	v_mfma_f32_16x16x32_bf16 v[110:113], v[164:167], v[180:183], v[110:113]
	v_mfma_f32_16x16x32_bf16 v[106:109], v[172:175], v[180:183], v[106:109]
	v_mfma_f32_16x16x32_bf16 v[94:97], v[164:167], v[188:191], v[94:97]
	v_mfma_f32_16x16x32_bf16 v[90:93], v[172:175], v[188:191], v[90:93]
	v_mfma_f32_16x16x32_bf16 v[78:81], v[164:167], v[196:199], v[78:81]
	v_mfma_f32_16x16x32_bf16 v[74:77], v[172:175], v[196:199], v[74:77]
	v_mfma_f32_16x16x32_bf16 v[70:73], v[164:167], v[204:207], v[70:73]
	v_mfma_f32_16x16x32_bf16 v[66:69], v[172:175], v[204:207], v[66:69]
	s_barrier
	s_add_i32 s22, s28, s3
	v_lshl_add_u64 v[208:209], s[12:13], 0, v[0:1]
	s_mov_b32 m0, s22
	ds_read_b128 v[176:179], v143 offset:16384
	ds_read_b128 v[180:183], v143 offset:17408
	ds_read_b128 v[184:187], v143 offset:18432
	ds_read_b128 v[188:191], v143 offset:19456
	ds_read_b128 v[192:195], v143 offset:20480
	ds_read_b128 v[196:199], v143 offset:21504
	ds_read_b128 v[200:203], v143 offset:22528
	ds_read_b128 v[204:207], v143 offset:23552
	global_load_lds_dwordx4 v[208:209], off
	s_add_i32 m0, s22, 0x2000
	s_add_u32 s22, s12, 0xb0000
	v_lshl_add_u64 v[210:211], s[12:13], 0, v[134:135]
	s_addc_u32 s23, s13, 0
	s_add_i32 s30, s33, s3
	global_load_lds_dwordx4 v[210:211], off
	v_lshl_add_u64 v[212:213], s[22:23], 0, v[0:1]
	s_mov_b32 m0, s30
	v_lshl_add_u64 v[214:215], s[14:15], 0, v[132:133]
	global_load_lds_dwordx4 v[212:213], off
	v_lshl_add_u64 v[212:213], s[22:23], 0, v[134:135]
	s_add_i32 m0, s30, 0x2000
	s_nop 0
	global_load_lds_dwordx4 v[212:213], off
	v_lshl_add_u64 v[212:213], s[14:15], 0, v[130:131]
	s_mov_b32 m0, s18
	s_nop 0
	global_load_lds_dwordx4 v[212:213], off
	s_mov_b32 m0, s19
	s_nop 0
	global_load_lds_dwordx4 v[214:215], off
	s_waitcnt vmcnt(8)
	s_waitcnt lgkmcnt(0)
	s_barrier
; #define PG8_STAGE(bufoff, gbase, voff) do { _Pragma("unroll") for (int _i = 0; _i < 2; ++_i) \
;         __builtin_amdgcn_global_load_lds((const unsigned*)((const char*)(gbase) + (voff)[_i]), (LAS unsigned*)(lds + (bufoff) + ldsw + _i * 8192), 16, 0, 0); } while (0)
; #define PG8_LDA(dst, b, h) do { _Pragma("unroll") for (int m = 0; m < 4; ++m) _Pragma("unroll") for (int k = 0; k < 2; ++k) dst[m][k] = *(const LAS bf16x8*)(lds + PG8_SA(b, h) + aoff + m * 2048 + k * 1024); } while (0)
; #define PG8_LDB(dst, b, h) do { _Pragma("unroll") for (int n = 0; n < 2; ++n) _Pragma("unroll") for (int k = 0; k < 2; ++k) dst[n][k] = *(const LAS bf16x8*)(lds + PG8_SB(b, h) + boff + n * 2048 + k * 1024); } while (0)
; #define PG8_MMA(ai, bj, At, Bt) do { __builtin_amdgcn_s_setprio(1); _Pragma("unroll") for (int m = 0; m < 4; ++m) _Pragma("unroll") for (int n = 0; n < 2; ++n) _Pragma("unroll") for (int k = 0; k < 2; ++k) \
;         acc[ai][bj][m][n] = __builtin_amdgcn_mfma_f32_16x16x32_bf16(Bt[n][k], At[m][k], acc[ai][bj][m][n], 0, 0, 0); __builtin_amdgcn_s_setprio(0); } while (0)
; #define PG8_WAIT_V(n) asm volatile("s_waitcnt vmcnt(" #n ")" ::: "memory")
; #define PG8_WAIT_L(n) asm volatile("s_waitcnt lgkmcnt(" #n ")" ::: "memory")
; #define PG8_BAR __builtin_amdgcn_s_barrier()
; #define PG8_SCHED __builtin_amdgcn_sched_barrier(0)
; template <class Epi, bool ALIGN_EPI, bool ASLOT = false>
; __device__ __forceinline__ void gemm_phase(LAS unsigned char* lds, const Gemm g, const Sched& S, const Epi& E) {
;     ...
;             PG8_WAIT_V(8); PG8_WAIT_L(0); PG8_BAR; PG8_MMA(1, 0, At, B0); PG8_MMA(1, 1, At, B1); PG8_BAR; PG8_SCHED;
;             PG8_LDB(B0, 1, 0); PG8_LDB(B1, 1, 1); PG8_SCHED; PG8_LDA(At, 1, 0); PG8_STAGE(PG8_SA(0, 1), a2 + hstep, voffA);
;             PG8_WAIT_V(8); PG8_WAIT_L(0); PG8_BAR; PG8_MMA(0, 0, At, B0); PG8_MMA(0, 1, At, B1); PG8_BAR; PG8_SCHED;
	s_waitcnt lgkmcnt(0)
	v_mfma_f32_16x16x32_bf16 v[62:65], v[144:147], v[176:179], v[62:65]
	v_mfma_f32_16x16x32_bf16 v[58:61], v[152:155], v[176:179], v[58:61]
	v_mfma_f32_16x16x32_bf16 v[54:57], v[144:147], v[184:187], v[54:57]
	v_mfma_f32_16x16x32_bf16 v[50:53], v[152:155], v[184:187], v[50:53]
	v_mfma_f32_16x16x32_bf16 v[38:41], v[144:147], v[192:195], v[38:41]
	v_mfma_f32_16x16x32_bf16 v[34:37], v[152:155], v[192:195], v[34:37]
	v_mfma_f32_16x16x32_bf16 v[22:25], v[144:147], v[200:203], v[22:25]
	v_mfma_f32_16x16x32_bf16 v[18:21], v[152:155], v[200:203], v[18:21]
	v_mfma_f32_16x16x32_bf16 v[62:65], v[148:151], v[180:183], v[62:65]
	v_mfma_f32_16x16x32_bf16 v[58:61], v[156:159], v[180:183], v[58:61]
	v_mfma_f32_16x16x32_bf16 v[54:57], v[148:151], v[188:191], v[54:57]
	v_mfma_f32_16x16x32_bf16 v[50:53], v[156:159], v[188:191], v[50:53]
	v_mfma_f32_16x16x32_bf16 v[38:41], v[148:151], v[196:199], v[38:41]
	v_mfma_f32_16x16x32_bf16 v[34:37], v[156:159], v[196:199], v[34:37]
	v_mfma_f32_16x16x32_bf16 v[22:25], v[148:151], v[204:207], v[22:25]
	v_mfma_f32_16x16x32_bf16 v[18:21], v[156:159], v[204:207], v[18:21]
	v_mfma_f32_16x16x32_bf16 v[46:49], v[160:163], v[176:179], v[46:49]
	v_mfma_f32_16x16x32_bf16 v[42:45], v[168:171], v[176:179], v[42:45]
	v_mfma_f32_16x16x32_bf16 v[30:33], v[160:163], v[184:187], v[30:33]
	v_mfma_f32_16x16x32_bf16 v[26:29], v[168:171], v[184:187], v[26:29]
	v_mfma_f32_16x16x32_bf16 v[14:17], v[160:163], v[192:195], v[14:17]
	v_mfma_f32_16x16x32_bf16 v[10:13], v[168:171], v[192:195], v[10:13]
	v_mfma_f32_16x16x32_bf16 v[6:9], v[160:163], v[200:203], v[6:9]
	v_mfma_f32_16x16x32_bf16 v[2:5], v[168:171], v[200:203], v[2:5]
	v_mfma_f32_16x16x32_bf16 v[46:49], v[164:167], v[180:183], v[46:49]
	v_mfma_f32_16x16x32_bf16 v[42:45], v[172:175], v[180:183], v[42:45]
	v_mfma_f32_16x16x32_bf16 v[30:33], v[164:167], v[188:191], v[30:33]
	v_mfma_f32_16x16x32_bf16 v[26:29], v[172:175], v[188:191], v[26:29]
	v_mfma_f32_16x16x32_bf16 v[14:17], v[164:167], v[196:199], v[14:17]
	v_mfma_f32_16x16x32_bf16 v[10:13], v[172:175], v[196:199], v[10:13]
	v_mfma_f32_16x16x32_bf16 v[6:9], v[164:167], v[204:207], v[6:9]
	v_mfma_f32_16x16x32_bf16 v[2:5], v[172:175], v[204:207], v[2:5]
	s_barrier
	v_add_u32_e32 v156, s29, v142
	v_add_u32_e32 v172, s26, v142
	ds_read_b128 v[144:147], v156
	ds_read_b128 v[148:151], v156 offset:1024
	ds_read_b128 v[152:155], v156 offset:2048
	ds_read_b128 v[156:159], v156 offset:3072
	ds_read_b128 v[160:163], v172
	ds_read_b128 v[164:167], v172 offset:1024
	ds_read_b128 v[168:171], v172 offset:2048
	ds_read_b128 v[172:175], v172 offset:3072
	s_add_u32 s14, s14, 0xb0000
	s_addc_u32 s15, s15, 0
	s_mov_b32 m0, s20
	v_lshl_add_u64 v[220:221], s[14:15], 0, v[130:131]
	ds_read_b128 v[176:179], v143 offset:32768
	ds_read_b128 v[180:183], v143 offset:33792
	ds_read_b128 v[184:187], v143 offset:34816
	ds_read_b128 v[188:191], v143 offset:35840
	ds_read_b128 v[192:195], v143 offset:36864
	ds_read_b128 v[196:199], v143 offset:37888
	ds_read_b128 v[200:203], v143 offset:38912
	ds_read_b128 v[204:207], v143 offset:39936
	global_load_lds_dwordx4 v[220:221], off
	v_lshl_add_u64 v[220:221], s[14:15], 0, v[132:133]
	s_mov_b32 m0, s21
	s_nop 0
	global_load_lds_dwordx4 v[220:221], off
	s_waitcnt vmcnt(8)
	s_waitcnt lgkmcnt(0)
	s_barrier
	s_waitcnt lgkmcnt(0)
	v_mfma_f32_16x16x32_bf16 v[126:129], v[144:147], v[176:179], v[126:129]
	v_mfma_f32_16x16x32_bf16 v[122:125], v[152:155], v[176:179], v[122:125]
	v_mfma_f32_16x16x32_bf16 v[118:121], v[144:147], v[184:187], v[118:121]
	v_mfma_f32_16x16x32_bf16 v[114:117], v[152:155], v[184:187], v[114:117]
	v_mfma_f32_16x16x32_bf16 v[102:105], v[144:147], v[192:195], v[102:105]
	v_mfma_f32_16x16x32_bf16 v[98:101], v[152:155], v[192:195], v[98:101]
	v_mfma_f32_16x16x32_bf16 v[86:89], v[144:147], v[200:203], v[86:89]
	v_mfma_f32_16x16x32_bf16 v[82:85], v[152:155], v[200:203], v[82:85]
	v_mfma_f32_16x16x32_bf16 v[126:129], v[148:151], v[180:183], v[126:129]
	v_mfma_f32_16x16x32_bf16 v[122:125], v[156:159], v[180:183], v[122:125]
	v_mfma_f32_16x16x32_bf16 v[118:121], v[148:151], v[188:191], v[118:121]
	v_mfma_f32_16x16x32_bf16 v[114:117], v[156:159], v[188:191], v[114:117]
	v_mfma_f32_16x16x32_bf16 v[102:105], v[148:151], v[196:199], v[102:105]
	v_mfma_f32_16x16x32_bf16 v[98:101], v[156:159], v[196:199], v[98:101]
	v_mfma_f32_16x16x32_bf16 v[86:89], v[148:151], v[204:207], v[86:89]
	v_mfma_f32_16x16x32_bf16 v[82:85], v[156:159], v[204:207], v[82:85]
	v_mfma_f32_16x16x32_bf16 v[110:113], v[160:163], v[176:179], v[110:113]
	v_mfma_f32_16x16x32_bf16 v[106:109], v[168:171], v[176:179], v[106:109]
	v_mfma_f32_16x16x32_bf16 v[94:97], v[160:163], v[184:187], v[94:97]
	v_mfma_f32_16x16x32_bf16 v[90:93], v[168:171], v[184:187], v[90:93]
	v_mfma_f32_16x16x32_bf16 v[78:81], v[160:163], v[192:195], v[78:81]
	v_mfma_f32_16x16x32_bf16 v[74:77], v[168:171], v[192:195], v[74:77]
	v_mfma_f32_16x16x32_bf16 v[70:73], v[160:163], v[200:203], v[70:73]
	v_mfma_f32_16x16x32_bf16 v[66:69], v[168:171], v[200:203], v[66:69]
	v_mfma_f32_16x16x32_bf16 v[110:113], v[164:167], v[180:183], v[110:113]
	v_mfma_f32_16x16x32_bf16 v[106:109], v[172:175], v[180:183], v[106:109]
	v_mfma_f32_16x16x32_bf16 v[94:97], v[164:167], v[188:191], v[94:97]
	v_mfma_f32_16x16x32_bf16 v[90:93], v[172:175], v[188:191], v[90:93]
	v_mfma_f32_16x16x32_bf16 v[78:81], v[164:167], v[196:199], v[78:81]
	v_mfma_f32_16x16x32_bf16 v[74:77], v[172:175], v[196:199], v[74:77]
	v_mfma_f32_16x16x32_bf16 v[70:73], v[164:167], v[204:207], v[70:73]
	v_mfma_f32_16x16x32_bf16 v[66:69], v[172:175], v[204:207], v[66:69]
	s_barrier
; #define PG8_STAGE(bufoff, gbase, voff) do { _Pragma("unroll") for (int _i = 0; _i < 2; ++_i) \
;         __builtin_amdgcn_global_load_lds((const unsigned*)((const char*)(gbase) + (voff)[_i]), (LAS unsigned*)(lds + (bufoff) + ldsw + _i * 8192), 16, 0, 0); } while (0)
; #define PG8_LDA(dst, b, h) do { _Pragma("unroll") for (int m = 0; m < 4; ++m) _Pragma("unroll") for (int k = 0; k < 2; ++k) dst[m][k] = *(const LAS bf16x8*)(lds + PG8_SA(b, h) + aoff + m * 2048 + k * 1024); } while (0)
; #define PG8_MMA(ai, bj, At, Bt) do { __builtin_amdgcn_s_setprio(1); _Pragma("unroll") for (int m = 0; m < 4; ++m) _Pragma("unroll") for (int n = 0; n < 2; ++n) _Pragma("unroll") for (int k = 0; k < 2; ++k) \
;         acc[ai][bj][m][n] = __builtin_amdgcn_mfma_f32_16x16x32_bf16(Bt[n][k], At[m][k], acc[ai][bj][m][n], 0, 0, 0); __builtin_amdgcn_s_setprio(0); } while (0)
; #define PG8_WAIT_V(n) asm volatile("s_waitcnt vmcnt(" #n ")" ::: "memory")
; #define PG8_WAIT_L(n) asm volatile("s_waitcnt lgkmcnt(" #n ")" ::: "memory")
; #define PG8_BAR __builtin_amdgcn_s_barrier()
; #define PG8_SCHED __builtin_amdgcn_sched_barrier(0)
; template <class Epi, bool ALIGN_EPI, bool ASLOT = false>
; __device__ __forceinline__ void gemm_phase(LAS unsigned char* lds, const Gemm g, const Sched& S, const Epi& E) {
;     ...
;             PG8_LDA(At, 1, 1); PG8_STAGE(PG8_SB(1, 0), b3, voffB); PG8_STAGE(PG8_SB(1, 1), b3 + hstep, voffB); PG8_STAGE(PG8_SA(1, 0), a3, voffA);
;             PG8_WAIT_V(8); PG8_WAIT_L(0); PG8_BAR; PG8_MMA(1, 0, At, B0); PG8_MMA(1, 1, At, B1); PG8_BAR; PG8_SCHED;
;         }
	s_add_i32 s14, s29, s3
	v_lshl_add_u64 v[208:209], v[208:209], 0, s[16:17]
	s_mov_b32 m0, s14
	ds_read_b128 v[176:179], v143 offset:49152
	ds_read_b128 v[180:183], v143 offset:50176
	ds_read_b128 v[184:187], v143 offset:51200
	ds_read_b128 v[188:191], v143 offset:52224
	ds_read_b128 v[192:195], v143 offset:53248
	ds_read_b128 v[196:199], v143 offset:54272
	ds_read_b128 v[200:203], v143 offset:55296
	ds_read_b128 v[204:207], v143 offset:56320
	global_load_lds_dwordx4 v[208:209], off
	s_add_i32 m0, s14, 0x2000
	s_add_u32 s12, s12, 0xb0080
	v_lshl_add_u64 v[208:209], v[210:211], 0, s[16:17]
	s_addc_u32 s13, s13, 0
	s_add_i32 s14, s26, s3
	global_load_lds_dwordx4 v[208:209], off
	v_lshl_add_u64 v[208:209], s[12:13], 0, v[0:1]
	s_mov_b32 m0, s14
	s_nop 0
	global_load_lds_dwordx4 v[208:209], off
	v_lshl_add_u64 v[208:209], s[12:13], 0, v[134:135]
	s_add_i32 m0, s14, 0x2000
	s_nop 0
	global_load_lds_dwordx4 v[208:209], off
	v_lshl_add_u64 v[208:209], v[212:213], 0, s[16:17]
	s_mov_b32 m0, s25
	s_nop 0
	global_load_lds_dwordx4 v[208:209], off
	v_lshl_add_u64 v[208:209], v[214:215], 0, s[16:17]
	s_mov_b32 m0, s27
	s_nop 0
	global_load_lds_dwordx4 v[208:209], off
	s_waitcnt vmcnt(8)
	s_waitcnt lgkmcnt(0)
	s_barrier
	s_waitcnt lgkmcnt(0)
	v_mfma_f32_16x16x32_bf16 v[62:65], v[144:147], v[176:179], v[62:65]
	v_mfma_f32_16x16x32_bf16 v[58:61], v[152:155], v[176:179], v[58:61]
	v_mfma_f32_16x16x32_bf16 v[54:57], v[144:147], v[184:187], v[54:57]
	v_mfma_f32_16x16x32_bf16 v[50:53], v[152:155], v[184:187], v[50:53]
	v_mfma_f32_16x16x32_bf16 v[38:41], v[144:147], v[192:195], v[38:41]
	v_mfma_f32_16x16x32_bf16 v[34:37], v[152:155], v[192:195], v[34:37]
	v_mfma_f32_16x16x32_bf16 v[22:25], v[144:147], v[200:203], v[22:25]
	v_mfma_f32_16x16x32_bf16 v[18:21], v[152:155], v[200:203], v[18:21]
	v_mfma_f32_16x16x32_bf16 v[62:65], v[148:151], v[180:183], v[62:65]
	v_mfma_f32_16x16x32_bf16 v[58:61], v[156:159], v[180:183], v[58:61]
	v_mfma_f32_16x16x32_bf16 v[54:57], v[148:151], v[188:191], v[54:57]
	v_mfma_f32_16x16x32_bf16 v[50:53], v[156:159], v[188:191], v[50:53]
	v_mfma_f32_16x16x32_bf16 v[38:41], v[148:151], v[196:199], v[38:41]
	v_mfma_f32_16x16x32_bf16 v[34:37], v[156:159], v[196:199], v[34:37]
	v_mfma_f32_16x16x32_bf16 v[22:25], v[148:151], v[204:207], v[22:25]
	v_mfma_f32_16x16x32_bf16 v[18:21], v[156:159], v[204:207], v[18:21]
	v_mfma_f32_16x16x32_bf16 v[46:49], v[160:163], v[176:179], v[46:49]
	v_mfma_f32_16x16x32_bf16 v[42:45], v[168:171], v[176:179], v[42:45]
	v_mfma_f32_16x16x32_bf16 v[30:33], v[160:163], v[184:187], v[30:33]
	v_mfma_f32_16x16x32_bf16 v[26:29], v[168:171], v[184:187], v[26:29]
	v_mfma_f32_16x16x32_bf16 v[14:17], v[160:163], v[192:195], v[14:17]
	v_mfma_f32_16x16x32_bf16 v[10:13], v[168:171], v[192:195], v[10:13]
	v_mfma_f32_16x16x32_bf16 v[6:9], v[160:163], v[200:203], v[6:9]
	v_mfma_f32_16x16x32_bf16 v[2:5], v[168:171], v[200:203], v[2:5]
	v_mfma_f32_16x16x32_bf16 v[46:49], v[164:167], v[180:183], v[46:49]
	v_mfma_f32_16x16x32_bf16 v[42:45], v[172:175], v[180:183], v[42:45]
	v_mfma_f32_16x16x32_bf16 v[30:33], v[164:167], v[188:191], v[30:33]
	v_mfma_f32_16x16x32_bf16 v[26:29], v[172:175], v[188:191], v[26:29]
	v_mfma_f32_16x16x32_bf16 v[14:17], v[164:167], v[196:199], v[14:17]
	v_mfma_f32_16x16x32_bf16 v[10:13], v[172:175], v[196:199], v[10:13]
	v_mfma_f32_16x16x32_bf16 v[6:9], v[164:167], v[204:207], v[6:9]
	v_mfma_f32_16x16x32_bf16 v[2:5], v[172:175], v[204:207], v[2:5]
	s_barrier
	s_add_i32 s37, s37, 2
	s_add_u32 s10, s10, 0x100
	s_addc_u32 s11, s11, 0
	s_cmp_gt_u32 s37, 41
	s_cbranch_scc0 .LBB0_175
	s_cmpk_lt_u32 s2, 0x100
	s_cbranch_scc0 .LBB0_178
	s_barrier

; #define PG8_STAGE(bufoff, gbase, voff) do { _Pragma("unroll") for (int _i = 0; _i < 2; ++_i) \
;         __builtin_amdgcn_global_load_lds((const unsigned*)((const char*)(gbase) + (voff)[_i]), (LAS unsigned*)(lds + (bufoff) + ldsw + _i * 8192), 16, 0, 0); } while (0)
; #define PG8_LDA(dst, b, h) do { _Pragma("unroll") for (int m = 0; m < 4; ++m) _Pragma("unroll") for (int k = 0; k < 2; ++k) dst[m][k] = *(const LAS bf16x8*)(lds + PG8_SA(b, h) + aoff + m * 2048 + k * 1024); } while (0)
; #define PG8_LDB(dst, b, h) do { _Pragma("unroll") for (int n = 0; n < 2; ++n) _Pragma("unroll") for (int k = 0; k < 2; ++k) dst[n][k] = *(const LAS bf16x8*)(lds + PG8_SB(b, h) + boff + n * 2048 + k * 1024); } while (0)
; #define PG8_MMA(ai, bj, At, Bt) do { __builtin_amdgcn_s_setprio(1); _Pragma("unroll") for (int m = 0; m < 4; ++m) _Pragma("unroll") for (int n = 0; n < 2; ++n) _Pragma("unroll") for (int k = 0; k < 2; ++k) \
;         acc[ai][bj][m][n] = __builtin_amdgcn_mfma_f32_16x16x32_bf16(Bt[n][k], At[m][k], acc[ai][bj][m][n], 0, 0, 0); __builtin_amdgcn_s_setprio(0); } while (0)
; #define PG8_WAIT_V(n) asm volatile("s_waitcnt vmcnt(" #n ")" ::: "memory")
; #define PG8_WAIT_L(n) asm volatile("s_waitcnt lgkmcnt(" #n ")" ::: "memory")
; #define PG8_BAR __builtin_amdgcn_s_barrier()
; #define PG8_SCHED __builtin_amdgcn_sched_barrier(0)
; template <class Epi, bool ALIGN_EPI, bool ASLOT = false>
; __device__ __forceinline__ void gemm_phase(LAS unsigned char* lds, const Gemm g, const Sched& S, const Epi& E) {
;     ...
;         for (int t = 0; t < nt; t += 2) {
;             const bool last = (t == nt - 2);
;             const char* a1 = cA + (size_t)(t + 1) * kstep;
;             const char* a2 = last ? nA : cA + (size_t)(t + 2) * kstep; const char* b2 = last ? nB : cB + (size_t)(t + 2) * kstep;
;             const char* a3 = a2 + kstep; const char* b3 = b2 + kstep;
;             PG8_LDB(B0, 0, 0); PG8_LDB(B1, 0, 1); PG8_SCHED; PG8_LDA(At, 0, 0); PG8_STAGE(PG8_SA(1, 1), a1 + hstep, voffA);
;             PG8_WAIT_V(8); PG8_WAIT_L(0); PG8_BAR; PG8_MMA(0, 0, At, B0); PG8_MMA(0, 1, At, B1); PG8_BAR; PG8_SCHED;
;             PG8_LDA(At, 0, 1); PG8_STAGE(PG8_SB(0, 0), b2, voffB); PG8_STAGE(PG8_SB(0, 1), b2 + hstep, voffB); PG8_STAGE(PG8_SA(0, 0), a2, voffA);
;             PG8_WAIT_V(8); PG8_WAIT_L(0); PG8_BAR; PG8_MMA(1, 0, At, B0); PG8_MMA(1, 1, At, B1); PG8_BAR; PG8_SCHED;
.LBB0_300:
	v_add_u32_e32 v0, s28, v177
	ds_read_b128 v[130:133], v0
	ds_read_b128 v[134:137], v0 offset:1024
	ds_read_b128 v[138:141], v0 offset:2048
	ds_read_b128 v[142:145], v0 offset:3072
	v_add_u32_e32 v0, s33, v177
	ds_read_b128 v[158:161], v0
	ds_read_b128 v[162:165], v0 offset:1024
	ds_read_b128 v[166:169], v0 offset:2048
	ds_read_b128 v[170:173], v0 offset:3072
	s_add_u32 s14, s0, 0xfffc0080
	s_addc_u32 s15, s1, -1
	s_cmp_eq_u32 s57, 12
	s_cselect_b32 s19, s3, s15
	s_cselect_b32 s18, s24, s14
	s_cselect_b32 s15, s25, s45
	s_cselect_b32 s14, s41, s43
	v_lshl_add_u64 v[174:175], s[0:1], 0, v[154:155]
	s_add_i32 m0, s50, 0xc000
	ds_read_b128 v[182:185], v180
	ds_read_b128 v[186:189], v180 offset:1024
	ds_read_b128 v[190:193], v180 offset:2048
	ds_read_b128 v[194:197], v180 offset:3072
	ds_read_b128 v[198:201], v180 offset:4096
	ds_read_b128 v[202:205], v180 offset:5120
	ds_read_b128 v[206:209], v180 offset:6144
	ds_read_b128 v[210:213], v180 offset:7168
	global_load_lds_dwordx4 v[174:175], off
	v_lshl_add_u64 v[174:175], s[0:1], 0, v[156:157]
	s_add_i32 m0, s50, 0xe000
	s_nop 0
	global_load_lds_dwordx4 v[174:175], off
	s_waitcnt vmcnt(8)
	s_waitcnt lgkmcnt(0)
	s_barrier
	s_waitcnt lgkmcnt(0)
	v_mfma_f32_16x16x32_bf16 v[126:129], v[130:133], v[182:185], v[126:129]
	v_mfma_f32_16x16x32_bf16 v[122:125], v[138:141], v[182:185], v[122:125]
	v_mfma_f32_16x16x32_bf16 v[110:113], v[130:133], v[190:193], v[110:113]
	v_mfma_f32_16x16x32_bf16 v[106:109], v[138:141], v[190:193], v[106:109]
	v_mfma_f32_16x16x32_bf16 v[94:97], v[130:133], v[198:201], v[94:97]
	v_mfma_f32_16x16x32_bf16 v[90:93], v[138:141], v[198:201], v[90:93]
	v_mfma_f32_16x16x32_bf16 v[78:81], v[130:133], v[206:209], v[78:81]
	v_mfma_f32_16x16x32_bf16 v[74:77], v[138:141], v[206:209], v[74:77]
	v_mfma_f32_16x16x32_bf16 v[126:129], v[134:137], v[186:189], v[126:129]
	v_mfma_f32_16x16x32_bf16 v[122:125], v[142:145], v[186:189], v[122:125]
	v_mfma_f32_16x16x32_bf16 v[110:113], v[134:137], v[194:197], v[110:113]
	v_mfma_f32_16x16x32_bf16 v[106:109], v[142:145], v[194:197], v[106:109]
	v_mfma_f32_16x16x32_bf16 v[94:97], v[134:137], v[202:205], v[94:97]
	v_mfma_f32_16x16x32_bf16 v[90:93], v[142:145], v[202:205], v[90:93]
	v_mfma_f32_16x16x32_bf16 v[78:81], v[134:137], v[210:213], v[78:81]
	v_mfma_f32_16x16x32_bf16 v[74:77], v[142:145], v[210:213], v[74:77]
	v_mfma_f32_16x16x32_bf16 v[118:121], v[158:161], v[182:185], v[118:121]
	v_mfma_f32_16x16x32_bf16 v[114:117], v[166:169], v[182:185], v[114:117]
	v_mfma_f32_16x16x32_bf16 v[102:105], v[158:161], v[190:193], v[102:105]
	v_mfma_f32_16x16x32_bf16 v[98:101], v[166:169], v[190:193], v[98:101]
	v_mfma_f32_16x16x32_bf16 v[86:89], v[158:161], v[198:201], v[86:89]
	v_mfma_f32_16x16x32_bf16 v[82:85], v[166:169], v[198:201], v[82:85]
	v_mfma_f32_16x16x32_bf16 v[70:73], v[158:161], v[206:209], v[70:73]
	v_mfma_f32_16x16x32_bf16 v[66:69], v[166:169], v[206:209], v[66:69]
	v_mfma_f32_16x16x32_bf16 v[118:121], v[162:165], v[186:189], v[118:121]
	v_mfma_f32_16x16x32_bf16 v[114:117], v[170:173], v[186:189], v[114:117]
	v_mfma_f32_16x16x32_bf16 v[102:105], v[162:165], v[194:197], v[102:105]
	v_mfma_f32_16x16x32_bf16 v[98:101], v[170:173], v[194:197], v[98:101]
	v_mfma_f32_16x16x32_bf16 v[86:89], v[162:165], v[202:205], v[86:89]
	v_mfma_f32_16x16x32_bf16 v[82:85], v[170:173], v[202:205], v[82:85]
	v_mfma_f32_16x16x32_bf16 v[70:73], v[162:165], v[210:213], v[70:73]
	v_mfma_f32_16x16x32_bf16 v[66:69], v[170:173], v[210:213], v[66:69]
	s_barrier
	s_add_i32 s22, s28, s27
	v_lshl_add_u64 v[174:175], s[14:15], 0, v[148:149]
	s_mov_b32 m0, s22
	ds_read_b128 v[182:185], v180 offset:16384
	ds_read_b128 v[186:189], v180 offset:17408
	ds_read_b128 v[190:193], v180 offset:18432
	ds_read_b128 v[194:197], v180 offset:19456
	ds_read_b128 v[198:201], v180 offset:20480
	ds_read_b128 v[202:205], v180 offset:21504
	ds_read_b128 v[206:209], v180 offset:22528
	ds_read_b128 v[210:213], v180 offset:23552
	global_load_lds_dwordx4 v[174:175], off
	s_add_i32 m0, s22, 0x2000
	s_add_u32 s22, s14, 0x40000
	v_lshl_add_u64 v[214:215], s[14:15], 0, v[152:153]
	s_addc_u32 s23, s15, 0
	s_add_i32 s30, s33, s27
	global_load_lds_dwordx4 v[214:215], off
	v_lshl_add_u64 v[220:221], s[22:23], 0, v[148:149]
	s_mov_b32 m0, s30
	v_lshl_add_u64 v[222:223], s[18:19], 0, v[150:151]
	global_load_lds_dwordx4 v[220:221], off
	v_lshl_add_u64 v[220:221], s[22:23], 0, v[152:153]
	s_add_i32 m0, s30, 0x2000
	s_nop 0
	global_load_lds_dwordx4 v[220:221], off
	v_lshl_add_u64 v[220:221], s[18:19], 0, v[146:147]
	s_mov_b32 m0, s50
	s_nop 0
	global_load_lds_dwordx4 v[220:221], off
	s_mov_b32 m0, s51
	s_nop 0
	global_load_lds_dwordx4 v[222:223], off
	s_waitcnt vmcnt(8)
	s_waitcnt lgkmcnt(0)
	s_barrier
; #define PG8_STAGE(bufoff, gbase, voff) do { _Pragma("unroll") for (int _i = 0; _i < 2; ++_i) \
;         __builtin_amdgcn_global_load_lds((const unsigned*)((const char*)(gbase) + (voff)[_i]), (LAS unsigned*)(lds + (bufoff) + ldsw + _i * 8192), 16, 0, 0); } while (0)
; #define PG8_LDA(dst, b, h) do { _Pragma("unroll") for (int m = 0; m < 4; ++m) _Pragma("unroll") for (int k = 0; k < 2; ++k) dst[m][k] = *(const LAS bf16x8*)(lds + PG8_SA(b, h) + aoff + m * 2048 + k * 1024); } while (0)
; #define PG8_LDB(dst, b, h) do { _Pragma("unroll") for (int n = 0; n < 2; ++n) _Pragma("unroll") for (int k = 0; k < 2; ++k) dst[n][k] = *(const LAS bf16x8*)(lds + PG8_SB(b, h) + boff + n * 2048 + k * 1024); } while (0)
; #define PG8_MMA(ai, bj, At, Bt) do { __builtin_amdgcn_s_setprio(1); _Pragma("unroll") for (int m = 0; m < 4; ++m) _Pragma("unroll") for (int n = 0; n < 2; ++n) _Pragma("unroll") for (int k = 0; k < 2; ++k) \
;         acc[ai][bj][m][n] = __builtin_amdgcn_mfma_f32_16x16x32_bf16(Bt[n][k], At[m][k], acc[ai][bj][m][n], 0, 0, 0); __builtin_amdgcn_s_setprio(0); } while (0)
; #define PG8_WAIT_V(n) asm volatile("s_waitcnt vmcnt(" #n ")" ::: "memory")
; #define PG8_WAIT_L(n) asm volatile("s_waitcnt lgkmcnt(" #n ")" ::: "memory")
; #define PG8_BAR __builtin_amdgcn_s_barrier()
; #define PG8_SCHED __builtin_amdgcn_sched_barrier(0)
; template <class Epi, bool ALIGN_EPI, bool ASLOT = false>
; __device__ __forceinline__ void gemm_phase(LAS unsigned char* lds, const Gemm g, const Sched& S, const Epi& E) {
;     ...
;             PG8_WAIT_V(8); PG8_WAIT_L(0); PG8_BAR; PG8_MMA(1, 0, At, B0); PG8_MMA(1, 1, At, B1); PG8_BAR; PG8_SCHED;
;             PG8_LDB(B0, 1, 0); PG8_LDB(B1, 1, 1); PG8_SCHED; PG8_LDA(At, 1, 0); PG8_STAGE(PG8_SA(0, 1), a2 + hstep, voffA);
;             PG8_WAIT_V(8); PG8_WAIT_L(0); PG8_BAR; PG8_MMA(0, 0, At, B0); PG8_MMA(0, 1, At, B1); PG8_BAR; PG8_SCHED;
	s_waitcnt lgkmcnt(0)
	v_mfma_f32_16x16x32_bf16 v[62:65], v[130:133], v[182:185], v[62:65]
	v_mfma_f32_16x16x32_bf16 v[58:61], v[138:141], v[182:185], v[58:61]
	v_mfma_f32_16x16x32_bf16 v[46:49], v[130:133], v[190:193], v[46:49]
	v_mfma_f32_16x16x32_bf16 v[42:45], v[138:141], v[190:193], v[42:45]
	v_mfma_f32_16x16x32_bf16 v[30:33], v[130:133], v[198:201], v[30:33]
	v_mfma_f32_16x16x32_bf16 v[26:29], v[138:141], v[198:201], v[26:29]
	v_mfma_f32_16x16x32_bf16 v[14:17], v[130:133], v[206:209], v[14:17]
	v_mfma_f32_16x16x32_bf16 v[10:13], v[138:141], v[206:209], v[10:13]
	v_mfma_f32_16x16x32_bf16 v[62:65], v[134:137], v[186:189], v[62:65]
	v_mfma_f32_16x16x32_bf16 v[58:61], v[142:145], v[186:189], v[58:61]
	v_mfma_f32_16x16x32_bf16 v[46:49], v[134:137], v[194:197], v[46:49]
	v_mfma_f32_16x16x32_bf16 v[42:45], v[142:145], v[194:197], v[42:45]
	v_mfma_f32_16x16x32_bf16 v[30:33], v[134:137], v[202:205], v[30:33]
	v_mfma_f32_16x16x32_bf16 v[26:29], v[142:145], v[202:205], v[26:29]
	v_mfma_f32_16x16x32_bf16 v[14:17], v[134:137], v[210:213], v[14:17]
	v_mfma_f32_16x16x32_bf16 v[10:13], v[142:145], v[210:213], v[10:13]
	v_mfma_f32_16x16x32_bf16 v[54:57], v[158:161], v[182:185], v[54:57]
	v_mfma_f32_16x16x32_bf16 v[50:53], v[166:169], v[182:185], v[50:53]
	v_mfma_f32_16x16x32_bf16 v[38:41], v[158:161], v[190:193], v[38:41]
	v_mfma_f32_16x16x32_bf16 v[34:37], v[166:169], v[190:193], v[34:37]
	v_mfma_f32_16x16x32_bf16 v[22:25], v[158:161], v[198:201], v[22:25]
	v_mfma_f32_16x16x32_bf16 v[18:21], v[166:169], v[198:201], v[18:21]
	v_mfma_f32_16x16x32_bf16 v[6:9], v[158:161], v[206:209], v[6:9]
	v_mfma_f32_16x16x32_bf16 v[2:5], v[166:169], v[206:209], v[2:5]
	v_mfma_f32_16x16x32_bf16 v[54:57], v[162:165], v[186:189], v[54:57]
	v_mfma_f32_16x16x32_bf16 v[50:53], v[170:173], v[186:189], v[50:53]
	v_mfma_f32_16x16x32_bf16 v[38:41], v[162:165], v[194:197], v[38:41]
	v_mfma_f32_16x16x32_bf16 v[34:37], v[170:173], v[194:197], v[34:37]
	v_mfma_f32_16x16x32_bf16 v[22:25], v[162:165], v[202:205], v[22:25]
	v_mfma_f32_16x16x32_bf16 v[18:21], v[170:173], v[202:205], v[18:21]
	v_mfma_f32_16x16x32_bf16 v[6:9], v[162:165], v[210:213], v[6:9]
	v_mfma_f32_16x16x32_bf16 v[2:5], v[170:173], v[210:213], v[2:5]
	s_barrier
	v_add_u32_e32 v0, s29, v177
	ds_read_b128 v[130:133], v0
	ds_read_b128 v[134:137], v0 offset:1024
	ds_read_b128 v[138:141], v0 offset:2048
	ds_read_b128 v[142:145], v0 offset:3072
	v_add_u32_e32 v0, s26, v177
	ds_read_b128 v[158:161], v0
	ds_read_b128 v[162:165], v0 offset:1024
	ds_read_b128 v[166:169], v0 offset:2048
	ds_read_b128 v[170:173], v0 offset:3072
	s_add_u32 s18, s18, 0x40000
	s_addc_u32 s19, s19, 0
	s_mov_b32 m0, s52
	v_lshl_add_u64 v[232:233], s[18:19], 0, v[146:147]
	ds_read_b128 v[182:185], v180 offset:32768
	ds_read_b128 v[186:189], v180 offset:33792
	ds_read_b128 v[190:193], v180 offset:34816
	ds_read_b128 v[194:197], v180 offset:35840
	ds_read_b128 v[198:201], v180 offset:36864
	ds_read_b128 v[202:205], v180 offset:37888
	ds_read_b128 v[206:209], v180 offset:38912
	ds_read_b128 v[210:213], v180 offset:39936
	global_load_lds_dwordx4 v[232:233], off
	v_lshl_add_u64 v[232:233], s[18:19], 0, v[150:151]
	s_mov_b32 m0, s53
	s_nop 0
	global_load_lds_dwordx4 v[232:233], off
	s_waitcnt vmcnt(8)
	s_waitcnt lgkmcnt(0)
	s_barrier
	s_waitcnt lgkmcnt(0)
	v_mfma_f32_16x16x32_bf16 v[126:129], v[130:133], v[182:185], v[126:129]
	v_mfma_f32_16x16x32_bf16 v[122:125], v[138:141], v[182:185], v[122:125]
	v_mfma_f32_16x16x32_bf16 v[110:113], v[130:133], v[190:193], v[110:113]
	v_mfma_f32_16x16x32_bf16 v[106:109], v[138:141], v[190:193], v[106:109]
	v_mfma_f32_16x16x32_bf16 v[94:97], v[130:133], v[198:201], v[94:97]
	v_mfma_f32_16x16x32_bf16 v[90:93], v[138:141], v[198:201], v[90:93]
	v_mfma_f32_16x16x32_bf16 v[78:81], v[130:133], v[206:209], v[78:81]
	v_mfma_f32_16x16x32_bf16 v[74:77], v[138:141], v[206:209], v[74:77]
	v_mfma_f32_16x16x32_bf16 v[126:129], v[134:137], v[186:189], v[126:129]
	v_mfma_f32_16x16x32_bf16 v[122:125], v[142:145], v[186:189], v[122:125]
	v_mfma_f32_16x16x32_bf16 v[110:113], v[134:137], v[194:197], v[110:113]
	v_mfma_f32_16x16x32_bf16 v[106:109], v[142:145], v[194:197], v[106:109]
	v_mfma_f32_16x16x32_bf16 v[94:97], v[134:137], v[202:205], v[94:97]
	v_mfma_f32_16x16x32_bf16 v[90:93], v[142:145], v[202:205], v[90:93]
	v_mfma_f32_16x16x32_bf16 v[78:81], v[134:137], v[210:213], v[78:81]
	v_mfma_f32_16x16x32_bf16 v[74:77], v[142:145], v[210:213], v[74:77]
	v_mfma_f32_16x16x32_bf16 v[118:121], v[158:161], v[182:185], v[118:121]
	v_mfma_f32_16x16x32_bf16 v[114:117], v[166:169], v[182:185], v[114:117]
	v_mfma_f32_16x16x32_bf16 v[102:105], v[158:161], v[190:193], v[102:105]
	v_mfma_f32_16x16x32_bf16 v[98:101], v[166:169], v[190:193], v[98:101]
	v_mfma_f32_16x16x32_bf16 v[86:89], v[158:161], v[198:201], v[86:89]
	v_mfma_f32_16x16x32_bf16 v[82:85], v[166:169], v[198:201], v[82:85]
	v_mfma_f32_16x16x32_bf16 v[70:73], v[158:161], v[206:209], v[70:73]
	v_mfma_f32_16x16x32_bf16 v[66:69], v[166:169], v[206:209], v[66:69]
	v_mfma_f32_16x16x32_bf16 v[118:121], v[162:165], v[186:189], v[118:121]
	v_mfma_f32_16x16x32_bf16 v[114:117], v[170:173], v[186:189], v[114:117]
	v_mfma_f32_16x16x32_bf16 v[102:105], v[162:165], v[194:197], v[102:105]
	v_mfma_f32_16x16x32_bf16 v[98:101], v[170:173], v[194:197], v[98:101]
	v_mfma_f32_16x16x32_bf16 v[86:89], v[162:165], v[202:205], v[86:89]
	v_mfma_f32_16x16x32_bf16 v[82:85], v[170:173], v[202:205], v[82:85]
	v_mfma_f32_16x16x32_bf16 v[70:73], v[162:165], v[210:213], v[70:73]
	v_mfma_f32_16x16x32_bf16 v[66:69], v[170:173], v[210:213], v[66:69]
	s_barrier
; #define PG8_STAGE(bufoff, gbase, voff) do { _Pragma("unroll") for (int _i = 0; _i < 2; ++_i) \
;         __builtin_amdgcn_global_load_lds((const unsigned*)((const char*)(gbase) + (voff)[_i]), (LAS unsigned*)(lds + (bufoff) + ldsw + _i * 8192), 16, 0, 0); } while (0)
; #define PG8_LDA(dst, b, h) do { _Pragma("unroll") for (int m = 0; m < 4; ++m) _Pragma("unroll") for (int k = 0; k < 2; ++k) dst[m][k] = *(const LAS bf16x8*)(lds + PG8_SA(b, h) + aoff + m * 2048 + k * 1024); } while (0)
; #define PG8_MMA(ai, bj, At, Bt) do { __builtin_amdgcn_s_setprio(1); _Pragma("unroll") for (int m = 0; m < 4; ++m) _Pragma("unroll") for (int n = 0; n < 2; ++n) _Pragma("unroll") for (int k = 0; k < 2; ++k) \
;         acc[ai][bj][m][n] = __builtin_amdgcn_mfma_f32_16x16x32_bf16(Bt[n][k], At[m][k], acc[ai][bj][m][n], 0, 0, 0); __builtin_amdgcn_s_setprio(0); } while (0)
; #define PG8_WAIT_V(n) asm volatile("s_waitcnt vmcnt(" #n ")" ::: "memory")
; #define PG8_WAIT_L(n) asm volatile("s_waitcnt lgkmcnt(" #n ")" ::: "memory")
; #define PG8_BAR __builtin_amdgcn_s_barrier()
; #define PG8_SCHED __builtin_amdgcn_sched_barrier(0)
; template <class Epi, bool ALIGN_EPI, bool ASLOT = false>
; __device__ __forceinline__ void gemm_phase(LAS unsigned char* lds, const Gemm g, const Sched& S, const Epi& E) {
;     ...
;             PG8_LDA(At, 1, 1); PG8_STAGE(PG8_SB(1, 0), b3, voffB); PG8_STAGE(PG8_SB(1, 1), b3 + hstep, voffB); PG8_STAGE(PG8_SA(1, 0), a3, voffA);
;             PG8_WAIT_V(8); PG8_WAIT_L(0); PG8_BAR; PG8_MMA(1, 0, At, B0); PG8_MMA(1, 1, At, B1); PG8_BAR; PG8_SCHED;
;         }
	s_add_i32 s18, s29, s27
	v_lshl_add_u64 v[174:175], v[174:175], 0, s[16:17]
	s_mov_b32 m0, s18
	ds_read_b128 v[182:185], v180 offset:49152
	ds_read_b128 v[186:189], v180 offset:50176
	ds_read_b128 v[190:193], v180 offset:51200
	ds_read_b128 v[194:197], v180 offset:52224
	ds_read_b128 v[198:201], v180 offset:53248
	ds_read_b128 v[202:205], v180 offset:54272
	ds_read_b128 v[206:209], v180 offset:55296
	ds_read_b128 v[210:213], v180 offset:56320
	global_load_lds_dwordx4 v[174:175], off
	s_add_i32 m0, s18, 0x2000
	s_add_u32 s14, s14, 0x40080
	v_lshl_add_u64 v[174:175], v[214:215], 0, s[16:17]
	s_addc_u32 s15, s15, 0
	s_add_i32 s18, s26, s27
	global_load_lds_dwordx4 v[174:175], off
	v_lshl_add_u64 v[174:175], s[14:15], 0, v[148:149]
	s_mov_b32 m0, s18
	s_nop 0
	global_load_lds_dwordx4 v[174:175], off
	v_lshl_add_u64 v[174:175], s[14:15], 0, v[152:153]
	s_add_i32 m0, s18, 0x2000
	s_nop 0
	global_load_lds_dwordx4 v[174:175], off
	v_lshl_add_u64 v[174:175], v[220:221], 0, s[16:17]
	s_mov_b32 m0, s54
	s_nop 0
	global_load_lds_dwordx4 v[174:175], off
	v_lshl_add_u64 v[174:175], v[222:223], 0, s[16:17]
	s_mov_b32 m0, s55
	s_nop 0
	global_load_lds_dwordx4 v[174:175], off
	s_waitcnt vmcnt(8)
	s_waitcnt lgkmcnt(0)
	s_barrier
	s_waitcnt lgkmcnt(0)
	v_mfma_f32_16x16x32_bf16 v[62:65], v[130:133], v[182:185], v[62:65]
	v_mfma_f32_16x16x32_bf16 v[58:61], v[138:141], v[182:185], v[58:61]
	v_mfma_f32_16x16x32_bf16 v[46:49], v[130:133], v[190:193], v[46:49]
	v_mfma_f32_16x16x32_bf16 v[42:45], v[138:141], v[190:193], v[42:45]
	v_mfma_f32_16x16x32_bf16 v[30:33], v[130:133], v[198:201], v[30:33]
	v_mfma_f32_16x16x32_bf16 v[26:29], v[138:141], v[198:201], v[26:29]
	v_mfma_f32_16x16x32_bf16 v[14:17], v[130:133], v[206:209], v[14:17]
	v_mfma_f32_16x16x32_bf16 v[10:13], v[138:141], v[206:209], v[10:13]
	v_mfma_f32_16x16x32_bf16 v[62:65], v[134:137], v[186:189], v[62:65]
	v_mfma_f32_16x16x32_bf16 v[58:61], v[142:145], v[186:189], v[58:61]
	v_mfma_f32_16x16x32_bf16 v[46:49], v[134:137], v[194:197], v[46:49]
	v_mfma_f32_16x16x32_bf16 v[42:45], v[142:145], v[194:197], v[42:45]
	v_mfma_f32_16x16x32_bf16 v[30:33], v[134:137], v[202:205], v[30:33]
	v_mfma_f32_16x16x32_bf16 v[26:29], v[142:145], v[202:205], v[26:29]
	v_mfma_f32_16x16x32_bf16 v[14:17], v[134:137], v[210:213], v[14:17]
	v_mfma_f32_16x16x32_bf16 v[10:13], v[142:145], v[210:213], v[10:13]
	v_mfma_f32_16x16x32_bf16 v[54:57], v[158:161], v[182:185], v[54:57]
	v_mfma_f32_16x16x32_bf16 v[50:53], v[166:169], v[182:185], v[50:53]
	v_mfma_f32_16x16x32_bf16 v[38:41], v[158:161], v[190:193], v[38:41]
	v_mfma_f32_16x16x32_bf16 v[34:37], v[166:169], v[190:193], v[34:37]
	v_mfma_f32_16x16x32_bf16 v[22:25], v[158:161], v[198:201], v[22:25]
	v_mfma_f32_16x16x32_bf16 v[18:21], v[166:169], v[198:201], v[18:21]
	v_mfma_f32_16x16x32_bf16 v[6:9], v[158:161], v[206:209], v[6:9]
	v_mfma_f32_16x16x32_bf16 v[2:5], v[166:169], v[206:209], v[2:5]
	v_mfma_f32_16x16x32_bf16 v[54:57], v[162:165], v[186:189], v[54:57]
	v_mfma_f32_16x16x32_bf16 v[50:53], v[170:173], v[186:189], v[50:53]
	v_mfma_f32_16x16x32_bf16 v[38:41], v[162:165], v[194:197], v[38:41]
	v_mfma_f32_16x16x32_bf16 v[34:37], v[170:173], v[194:197], v[34:37]
	v_mfma_f32_16x16x32_bf16 v[22:25], v[162:165], v[202:205], v[22:25]
	v_mfma_f32_16x16x32_bf16 v[18:21], v[170:173], v[202:205], v[18:21]
	v_mfma_f32_16x16x32_bf16 v[6:9], v[162:165], v[210:213], v[6:9]
	v_mfma_f32_16x16x32_bf16 v[2:5], v[170:173], v[210:213], v[2:5]
	s_barrier
	s_add_i32 s57, s57, 2
	s_add_u32 s0, s0, 0x100
	s_addc_u32 s1, s1, 0
	s_add_u32 s43, s43, 0x100
	s_addc_u32 s45, s45, 0
	s_cmp_gt_u32 s57, 13
	s_cbranch_scc0 .LBB0_300
	s_and_b64 vcc, exec, s[12:13]
	s_cbranch_vccz .LBB0_303
	s_barrier

; #define PG8_STAGE(bufoff, gbase, voff) do { _Pragma("unroll") for (int _i = 0; _i < 2; ++_i) \
;         __builtin_amdgcn_global_load_lds((const unsigned*)((const char*)(gbase) + (voff)[_i]), (LAS unsigned*)(lds + (bufoff) + ldsw + _i * 8192), 16, 0, 0); } while (0)
; #define PG8_LDA(dst, b, h) do { _Pragma("unroll") for (int m = 0; m < 4; ++m) _Pragma("unroll") for (int k = 0; k < 2; ++k) dst[m][k] = *(const LAS bf16x8*)(lds + PG8_SA(b, h) + aoff + m * 2048 + k * 1024); } while (0)
; #define PG8_LDB(dst, b, h) do { _Pragma("unroll") for (int n = 0; n < 2; ++n) _Pragma("unroll") for (int k = 0; k < 2; ++k) dst[n][k] = *(const LAS bf16x8*)(lds + PG8_SB(b, h) + boff + n * 2048 + k * 1024); } while (0)
; #define PG8_MMA(ai, bj, At, Bt) do { __builtin_amdgcn_s_setprio(1); _Pragma("unroll") for (int m = 0; m < 4; ++m) _Pragma("unroll") for (int n = 0; n < 2; ++n) _Pragma("unroll") for (int k = 0; k < 2; ++k) \
;         acc[ai][bj][m][n] = __builtin_amdgcn_mfma_f32_16x16x32_bf16(Bt[n][k], At[m][k], acc[ai][bj][m][n], 0, 0, 0); __builtin_amdgcn_s_setprio(0); } while (0)
; #define PG8_WAIT_V(n) asm volatile("s_waitcnt vmcnt(" #n ")" ::: "memory")
; #define PG8_WAIT_L(n) asm volatile("s_waitcnt lgkmcnt(" #n ")" ::: "memory")
; #define PG8_BAR __builtin_amdgcn_s_barrier()
; #define PG8_SCHED __builtin_amdgcn_sched_barrier(0)
; template <class Epi, bool ALIGN_EPI, bool ASLOT = false>
; __device__ __forceinline__ void gemm_phase(LAS unsigned char* lds, const Gemm g, const Sched& S, const Epi& E) {
;     ...
;         for (int t = 0; t < nt; t += 2) {
;             const bool last = (t == nt - 2);
;             const char* a1 = cA + (size_t)(t + 1) * kstep;
;             const char* a2 = last ? nA : cA + (size_t)(t + 2) * kstep; const char* b2 = last ? nB : cB + (size_t)(t + 2) * kstep;
;             const char* a3 = a2 + kstep; const char* b3 = b2 + kstep;
;             PG8_LDB(B0, 0, 0); PG8_LDB(B1, 0, 1); PG8_SCHED; PG8_LDA(At, 0, 0); PG8_STAGE(PG8_SA(1, 1), a1 + hstep, voffA);
;             PG8_WAIT_V(8); PG8_WAIT_L(0); PG8_BAR; PG8_MMA(0, 0, At, B0); PG8_MMA(0, 1, At, B1); PG8_BAR; PG8_SCHED;
;             PG8_LDA(At, 0, 1); PG8_STAGE(PG8_SB(0, 0), b2, voffB); PG8_STAGE(PG8_SB(0, 1), b2 + hstep, voffB); PG8_STAGE(PG8_SA(0, 0), a2, voffA);
;             PG8_WAIT_V(8); PG8_WAIT_L(0); PG8_BAR; PG8_MMA(1, 0, At, B0); PG8_MMA(1, 1, At, B1); PG8_BAR; PG8_SCHED;
.Lbr_keep_acc:
.LBB0_664:
	v_add_u32_e32 v148, s28, v151
	ds_read_b128 v[140:143], v148
	ds_read_b128 v[144:147], v148 offset:1024
	ds_read_b128 v[154:157], v148 offset:2048
	ds_read_b128 v[158:161], v148 offset:3072
	v_add_u32_e32 v148, s33, v151
	ds_read_b128 v[162:165], v148
	ds_read_b128 v[166:169], v148 offset:1024
	ds_read_b128 v[170:173], v148 offset:2048
	ds_read_b128 v[174:177], v148 offset:3072
	s_add_u32 s18, s36, 0xfffe0080
	s_addc_u32 s19, s37, -1
	s_cmp_eq_u32 s40, 4
	s_cselect_b32 s21, s13, s19
	s_cselect_b32 s20, s15, s18
	s_cselect_b32 s19, s9, s25
	s_cselect_b32 s18, s11, s24
	v_lshl_add_u64 v[148:149], s[36:37], 0, v[136:137]
	s_add_i32 m0, s51, 0xc000
	ds_read_b128 v[178:181], v153
	ds_read_b128 v[182:185], v153 offset:1024
	ds_read_b128 v[186:189], v153 offset:2048
	ds_read_b128 v[190:193], v153 offset:3072
	ds_read_b128 v[194:197], v153 offset:4096
	ds_read_b128 v[198:201], v153 offset:5120
	ds_read_b128 v[202:205], v153 offset:6144
	ds_read_b128 v[206:209], v153 offset:7168
	global_load_lds_dwordx4 v[148:149], off
	v_lshl_add_u64 v[148:149], s[36:37], 0, v[138:139]
	s_add_i32 m0, s51, 0xe000
	s_nop 0
	global_load_lds_dwordx4 v[148:149], off
	s_waitcnt vmcnt(8)
	s_waitcnt lgkmcnt(0)
	s_barrier
	s_waitcnt lgkmcnt(0)
	v_mfma_f32_16x16x32_bf16 v[126:129], v[140:143], v[178:181], v[126:129]
	v_mfma_f32_16x16x32_bf16 v[122:125], v[154:157], v[178:181], v[122:125]
	v_mfma_f32_16x16x32_bf16 v[110:113], v[140:143], v[186:189], v[110:113]
	v_mfma_f32_16x16x32_bf16 v[106:109], v[154:157], v[186:189], v[106:109]
	v_mfma_f32_16x16x32_bf16 v[94:97], v[140:143], v[194:197], v[94:97]
	v_mfma_f32_16x16x32_bf16 v[90:93], v[154:157], v[194:197], v[90:93]
	v_mfma_f32_16x16x32_bf16 v[78:81], v[140:143], v[202:205], v[78:81]
	v_mfma_f32_16x16x32_bf16 v[74:77], v[154:157], v[202:205], v[74:77]
	v_mfma_f32_16x16x32_bf16 v[126:129], v[144:147], v[182:185], v[126:129]
	v_mfma_f32_16x16x32_bf16 v[122:125], v[158:161], v[182:185], v[122:125]
	v_mfma_f32_16x16x32_bf16 v[110:113], v[144:147], v[190:193], v[110:113]
	v_mfma_f32_16x16x32_bf16 v[106:109], v[158:161], v[190:193], v[106:109]
	v_mfma_f32_16x16x32_bf16 v[94:97], v[144:147], v[198:201], v[94:97]
	v_mfma_f32_16x16x32_bf16 v[90:93], v[158:161], v[198:201], v[90:93]
	v_mfma_f32_16x16x32_bf16 v[78:81], v[144:147], v[206:209], v[78:81]
	v_mfma_f32_16x16x32_bf16 v[74:77], v[158:161], v[206:209], v[74:77]
	v_mfma_f32_16x16x32_bf16 v[118:121], v[162:165], v[178:181], v[118:121]
	v_mfma_f32_16x16x32_bf16 v[114:117], v[170:173], v[178:181], v[114:117]
	v_mfma_f32_16x16x32_bf16 v[102:105], v[162:165], v[186:189], v[102:105]
	v_mfma_f32_16x16x32_bf16 v[98:101], v[170:173], v[186:189], v[98:101]
	v_mfma_f32_16x16x32_bf16 v[86:89], v[162:165], v[194:197], v[86:89]
	v_mfma_f32_16x16x32_bf16 v[82:85], v[170:173], v[194:197], v[82:85]
	v_mfma_f32_16x16x32_bf16 v[70:73], v[162:165], v[202:205], v[70:73]
	v_mfma_f32_16x16x32_bf16 v[66:69], v[170:173], v[202:205], v[66:69]
	v_mfma_f32_16x16x32_bf16 v[118:121], v[166:169], v[182:185], v[118:121]
	v_mfma_f32_16x16x32_bf16 v[114:117], v[174:177], v[182:185], v[114:117]
	v_mfma_f32_16x16x32_bf16 v[102:105], v[166:169], v[190:193], v[102:105]
	v_mfma_f32_16x16x32_bf16 v[98:101], v[174:177], v[190:193], v[98:101]
	v_mfma_f32_16x16x32_bf16 v[86:89], v[166:169], v[198:201], v[86:89]
	v_mfma_f32_16x16x32_bf16 v[82:85], v[174:177], v[198:201], v[82:85]
	v_mfma_f32_16x16x32_bf16 v[70:73], v[166:169], v[206:209], v[70:73]
	v_mfma_f32_16x16x32_bf16 v[66:69], v[174:177], v[206:209], v[66:69]
	s_barrier
	s_add_i32 s22, s28, s50
	v_lshl_add_u64 v[148:149], s[18:19], 0, v[0:1]
	s_mov_b32 m0, s22
	ds_read_b128 v[178:181], v153 offset:16384
	ds_read_b128 v[182:185], v153 offset:17408
	ds_read_b128 v[186:189], v153 offset:18432
	ds_read_b128 v[190:193], v153 offset:19456
	ds_read_b128 v[194:197], v153 offset:20480
	ds_read_b128 v[198:201], v153 offset:21504
	ds_read_b128 v[202:205], v153 offset:22528
	ds_read_b128 v[206:209], v153 offset:23552
	global_load_lds_dwordx4 v[148:149], off
	s_add_i32 m0, s22, 0x2000
	s_add_u32 s22, s18, 0x20000
	v_lshl_add_u64 v[210:211], s[18:19], 0, v[134:135]
	s_addc_u32 s23, s19, 0
	s_add_i32 s30, s33, s50
	global_load_lds_dwordx4 v[210:211], off
	v_lshl_add_u64 v[212:213], s[22:23], 0, v[0:1]
	s_mov_b32 m0, s30
	v_lshl_add_u64 v[214:215], s[20:21], 0, v[132:133]
	global_load_lds_dwordx4 v[212:213], off
	v_lshl_add_u64 v[212:213], s[22:23], 0, v[134:135]
	s_add_i32 m0, s30, 0x2000
	s_nop 0
	global_load_lds_dwordx4 v[212:213], off
	v_lshl_add_u64 v[212:213], s[20:21], 0, v[130:131]
	s_mov_b32 m0, s51
	s_nop 0
	global_load_lds_dwordx4 v[212:213], off
	s_mov_b32 m0, s52
	s_nop 0
	global_load_lds_dwordx4 v[214:215], off
	s_waitcnt vmcnt(8)
	s_waitcnt lgkmcnt(0)
	s_barrier
; #define PG8_STAGE(bufoff, gbase, voff) do { _Pragma("unroll") for (int _i = 0; _i < 2; ++_i) \
;         __builtin_amdgcn_global_load_lds((const unsigned*)((const char*)(gbase) + (voff)[_i]), (LAS unsigned*)(lds + (bufoff) + ldsw + _i * 8192), 16, 0, 0); } while (0)
; #define PG8_LDA(dst, b, h) do { _Pragma("unroll") for (int m = 0; m < 4; ++m) _Pragma("unroll") for (int k = 0; k < 2; ++k) dst[m][k] = *(const LAS bf16x8*)(lds + PG8_SA(b, h) + aoff + m * 2048 + k * 1024); } while (0)
; #define PG8_LDB(dst, b, h) do { _Pragma("unroll") for (int n = 0; n < 2; ++n) _Pragma("unroll") for (int k = 0; k < 2; ++k) dst[n][k] = *(const LAS bf16x8*)(lds + PG8_SB(b, h) + boff + n * 2048 + k * 1024); } while (0)
; #define PG8_MMA(ai, bj, At, Bt) do { __builtin_amdgcn_s_setprio(1); _Pragma("unroll") for (int m = 0; m < 4; ++m) _Pragma("unroll") for (int n = 0; n < 2; ++n) _Pragma("unroll") for (int k = 0; k < 2; ++k) \
;         acc[ai][bj][m][n] = __builtin_amdgcn_mfma_f32_16x16x32_bf16(Bt[n][k], At[m][k], acc[ai][bj][m][n], 0, 0, 0); __builtin_amdgcn_s_setprio(0); } while (0)
; #define PG8_WAIT_V(n) asm volatile("s_waitcnt vmcnt(" #n ")" ::: "memory")
; #define PG8_WAIT_L(n) asm volatile("s_waitcnt lgkmcnt(" #n ")" ::: "memory")
; #define PG8_BAR __builtin_amdgcn_s_barrier()
; #define PG8_SCHED __builtin_amdgcn_sched_barrier(0)
; template <class Epi, bool ALIGN_EPI, bool ASLOT = false>
; __device__ __forceinline__ void gemm_phase(LAS unsigned char* lds, const Gemm g, const Sched& S, const Epi& E) {
;     ...
;             PG8_WAIT_V(8); PG8_WAIT_L(0); PG8_BAR; PG8_MMA(1, 0, At, B0); PG8_MMA(1, 1, At, B1); PG8_BAR; PG8_SCHED;
;             PG8_LDB(B0, 1, 0); PG8_LDB(B1, 1, 1); PG8_SCHED; PG8_LDA(At, 1, 0); PG8_STAGE(PG8_SA(0, 1), a2 + hstep, voffA);
;             PG8_WAIT_V(8); PG8_WAIT_L(0); PG8_BAR; PG8_MMA(0, 0, At, B0); PG8_MMA(0, 1, At, B1); PG8_BAR; PG8_SCHED;
	s_waitcnt lgkmcnt(0)
	v_mfma_f32_16x16x32_bf16 v[62:65], v[140:143], v[178:181], v[62:65]
	v_mfma_f32_16x16x32_bf16 v[58:61], v[154:157], v[178:181], v[58:61]
	v_mfma_f32_16x16x32_bf16 v[46:49], v[140:143], v[186:189], v[46:49]
	v_mfma_f32_16x16x32_bf16 v[42:45], v[154:157], v[186:189], v[42:45]
	v_mfma_f32_16x16x32_bf16 v[30:33], v[140:143], v[194:197], v[30:33]
	v_mfma_f32_16x16x32_bf16 v[26:29], v[154:157], v[194:197], v[26:29]
	v_mfma_f32_16x16x32_bf16 v[14:17], v[140:143], v[202:205], v[14:17]
	v_mfma_f32_16x16x32_bf16 v[10:13], v[154:157], v[202:205], v[10:13]
	v_mfma_f32_16x16x32_bf16 v[62:65], v[144:147], v[182:185], v[62:65]
	v_mfma_f32_16x16x32_bf16 v[58:61], v[158:161], v[182:185], v[58:61]
	v_mfma_f32_16x16x32_bf16 v[46:49], v[144:147], v[190:193], v[46:49]
	v_mfma_f32_16x16x32_bf16 v[42:45], v[158:161], v[190:193], v[42:45]
	v_mfma_f32_16x16x32_bf16 v[30:33], v[144:147], v[198:201], v[30:33]
	v_mfma_f32_16x16x32_bf16 v[26:29], v[158:161], v[198:201], v[26:29]
	v_mfma_f32_16x16x32_bf16 v[14:17], v[144:147], v[206:209], v[14:17]
	v_mfma_f32_16x16x32_bf16 v[10:13], v[158:161], v[206:209], v[10:13]
	v_mfma_f32_16x16x32_bf16 v[54:57], v[162:165], v[178:181], v[54:57]
	v_mfma_f32_16x16x32_bf16 v[50:53], v[170:173], v[178:181], v[50:53]
	v_mfma_f32_16x16x32_bf16 v[38:41], v[162:165], v[186:189], v[38:41]
	v_mfma_f32_16x16x32_bf16 v[34:37], v[170:173], v[186:189], v[34:37]
	v_mfma_f32_16x16x32_bf16 v[22:25], v[162:165], v[194:197], v[22:25]
	v_mfma_f32_16x16x32_bf16 v[18:21], v[170:173], v[194:197], v[18:21]
	v_mfma_f32_16x16x32_bf16 v[6:9], v[162:165], v[202:205], v[6:9]
	v_mfma_f32_16x16x32_bf16 v[2:5], v[170:173], v[202:205], v[2:5]
	v_mfma_f32_16x16x32_bf16 v[54:57], v[166:169], v[182:185], v[54:57]
	v_mfma_f32_16x16x32_bf16 v[50:53], v[174:177], v[182:185], v[50:53]
	v_mfma_f32_16x16x32_bf16 v[38:41], v[166:169], v[190:193], v[38:41]
	v_mfma_f32_16x16x32_bf16 v[34:37], v[174:177], v[190:193], v[34:37]
	v_mfma_f32_16x16x32_bf16 v[22:25], v[166:169], v[198:201], v[22:25]
	v_mfma_f32_16x16x32_bf16 v[18:21], v[174:177], v[198:201], v[18:21]
	v_mfma_f32_16x16x32_bf16 v[6:9], v[166:169], v[206:209], v[6:9]
	v_mfma_f32_16x16x32_bf16 v[2:5], v[174:177], v[206:209], v[2:5]
	s_barrier
	v_add_u32_e32 v158, s29, v151
	v_add_u32_e32 v174, s26, v151
	ds_read_b128 v[140:143], v158
	ds_read_b128 v[144:147], v158 offset:1024
	ds_read_b128 v[154:157], v158 offset:2048
	ds_read_b128 v[158:161], v158 offset:3072
	ds_read_b128 v[162:165], v174
	ds_read_b128 v[166:169], v174 offset:1024
	ds_read_b128 v[170:173], v174 offset:2048
	ds_read_b128 v[174:177], v174 offset:3072
	s_add_u32 s20, s20, 0x20000
	s_addc_u32 s21, s21, 0
	s_mov_b32 m0, s53
	v_lshl_add_u64 v[220:221], s[20:21], 0, v[130:131]
	ds_read_b128 v[178:181], v153 offset:32768
	ds_read_b128 v[182:185], v153 offset:33792
	ds_read_b128 v[186:189], v153 offset:34816
	ds_read_b128 v[190:193], v153 offset:35840
	ds_read_b128 v[194:197], v153 offset:36864
	ds_read_b128 v[198:201], v153 offset:37888
	ds_read_b128 v[202:205], v153 offset:38912
	ds_read_b128 v[206:209], v153 offset:39936
	global_load_lds_dwordx4 v[220:221], off
	v_lshl_add_u64 v[220:221], s[20:21], 0, v[132:133]
	s_mov_b32 m0, s54
	s_nop 0
	global_load_lds_dwordx4 v[220:221], off
	s_waitcnt vmcnt(8)
	s_waitcnt lgkmcnt(0)
	s_barrier
	s_waitcnt lgkmcnt(0)
	v_mfma_f32_16x16x32_bf16 v[126:129], v[140:143], v[178:181], v[126:129]
	v_mfma_f32_16x16x32_bf16 v[122:125], v[154:157], v[178:181], v[122:125]
	v_mfma_f32_16x16x32_bf16 v[110:113], v[140:143], v[186:189], v[110:113]
	v_mfma_f32_16x16x32_bf16 v[106:109], v[154:157], v[186:189], v[106:109]
	v_mfma_f32_16x16x32_bf16 v[94:97], v[140:143], v[194:197], v[94:97]
	v_mfma_f32_16x16x32_bf16 v[90:93], v[154:157], v[194:197], v[90:93]
	v_mfma_f32_16x16x32_bf16 v[78:81], v[140:143], v[202:205], v[78:81]
	v_mfma_f32_16x16x32_bf16 v[74:77], v[154:157], v[202:205], v[74:77]
	v_mfma_f32_16x16x32_bf16 v[126:129], v[144:147], v[182:185], v[126:129]
	v_mfma_f32_16x16x32_bf16 v[122:125], v[158:161], v[182:185], v[122:125]
	v_mfma_f32_16x16x32_bf16 v[110:113], v[144:147], v[190:193], v[110:113]
	v_mfma_f32_16x16x32_bf16 v[106:109], v[158:161], v[190:193], v[106:109]
	v_mfma_f32_16x16x32_bf16 v[94:97], v[144:147], v[198:201], v[94:97]
	v_mfma_f32_16x16x32_bf16 v[90:93], v[158:161], v[198:201], v[90:93]
	v_mfma_f32_16x16x32_bf16 v[78:81], v[144:147], v[206:209], v[78:81]
	v_mfma_f32_16x16x32_bf16 v[74:77], v[158:161], v[206:209], v[74:77]
	v_mfma_f32_16x16x32_bf16 v[118:121], v[162:165], v[178:181], v[118:121]
	v_mfma_f32_16x16x32_bf16 v[114:117], v[170:173], v[178:181], v[114:117]
	v_mfma_f32_16x16x32_bf16 v[102:105], v[162:165], v[186:189], v[102:105]
	v_mfma_f32_16x16x32_bf16 v[98:101], v[170:173], v[186:189], v[98:101]
	v_mfma_f32_16x16x32_bf16 v[86:89], v[162:165], v[194:197], v[86:89]
	v_mfma_f32_16x16x32_bf16 v[82:85], v[170:173], v[194:197], v[82:85]
	v_mfma_f32_16x16x32_bf16 v[70:73], v[162:165], v[202:205], v[70:73]
	v_mfma_f32_16x16x32_bf16 v[66:69], v[170:173], v[202:205], v[66:69]
	v_mfma_f32_16x16x32_bf16 v[118:121], v[166:169], v[182:185], v[118:121]
	v_mfma_f32_16x16x32_bf16 v[114:117], v[174:177], v[182:185], v[114:117]
	v_mfma_f32_16x16x32_bf16 v[102:105], v[166:169], v[190:193], v[102:105]
	v_mfma_f32_16x16x32_bf16 v[98:101], v[174:177], v[190:193], v[98:101]
	v_mfma_f32_16x16x32_bf16 v[86:89], v[166:169], v[198:201], v[86:89]
	v_mfma_f32_16x16x32_bf16 v[82:85], v[174:177], v[198:201], v[82:85]
	v_mfma_f32_16x16x32_bf16 v[70:73], v[166:169], v[206:209], v[70:73]
	v_mfma_f32_16x16x32_bf16 v[66:69], v[174:177], v[206:209], v[66:69]
	s_barrier
; #define PG8_STAGE(bufoff, gbase, voff) do { _Pragma("unroll") for (int _i = 0; _i < 2; ++_i) \
;         __builtin_amdgcn_global_load_lds((const unsigned*)((const char*)(gbase) + (voff)[_i]), (LAS unsigned*)(lds + (bufoff) + ldsw + _i * 8192), 16, 0, 0); } while (0)
; #define PG8_LDA(dst, b, h) do { _Pragma("unroll") for (int m = 0; m < 4; ++m) _Pragma("unroll") for (int k = 0; k < 2; ++k) dst[m][k] = *(const LAS bf16x8*)(lds + PG8_SA(b, h) + aoff + m * 2048 + k * 1024); } while (0)
; #define PG8_MMA(ai, bj, At, Bt) do { __builtin_amdgcn_s_setprio(1); _Pragma("unroll") for (int m = 0; m < 4; ++m) _Pragma("unroll") for (int n = 0; n < 2; ++n) _Pragma("unroll") for (int k = 0; k < 2; ++k) \
;         acc[ai][bj][m][n] = __builtin_amdgcn_mfma_f32_16x16x32_bf16(Bt[n][k], At[m][k], acc[ai][bj][m][n], 0, 0, 0); __builtin_amdgcn_s_setprio(0); } while (0)
; #define PG8_WAIT_V(n) asm volatile("s_waitcnt vmcnt(" #n ")" ::: "memory")
; #define PG8_WAIT_L(n) asm volatile("s_waitcnt lgkmcnt(" #n ")" ::: "memory")
; #define PG8_BAR __builtin_amdgcn_s_barrier()
; #define PG8_SCHED __builtin_amdgcn_sched_barrier(0)
; template <class Epi, bool ALIGN_EPI, bool ASLOT = false>
; __device__ __forceinline__ void gemm_phase(LAS unsigned char* lds, const Gemm g, const Sched& S, const Epi& E) {
;     ...
;             PG8_LDA(At, 1, 1); PG8_STAGE(PG8_SB(1, 0), b3, voffB); PG8_STAGE(PG8_SB(1, 1), b3 + hstep, voffB); PG8_STAGE(PG8_SA(1, 0), a3, voffA);
;             PG8_WAIT_V(8); PG8_WAIT_L(0); PG8_BAR; PG8_MMA(1, 0, At, B0); PG8_MMA(1, 1, At, B1); PG8_BAR; PG8_SCHED;
;         }
	s_add_i32 s20, s29, s50
	v_lshl_add_u64 v[148:149], v[148:149], 0, s[16:17]
	s_mov_b32 m0, s20
	ds_read_b128 v[178:181], v153 offset:49152
	ds_read_b128 v[182:185], v153 offset:50176
	ds_read_b128 v[186:189], v153 offset:51200
	ds_read_b128 v[190:193], v153 offset:52224
	ds_read_b128 v[194:197], v153 offset:53248
	ds_read_b128 v[198:201], v153 offset:54272
	ds_read_b128 v[202:205], v153 offset:55296
	ds_read_b128 v[206:209], v153 offset:56320
	global_load_lds_dwordx4 v[148:149], off
	s_add_i32 m0, s20, 0x2000
	s_add_u32 s18, s18, 0x20080
	v_lshl_add_u64 v[148:149], v[210:211], 0, s[16:17]
	s_addc_u32 s19, s19, 0
	s_add_i32 s20, s26, s50
	global_load_lds_dwordx4 v[148:149], off
	v_lshl_add_u64 v[148:149], s[18:19], 0, v[0:1]
	s_mov_b32 m0, s20
	s_nop 0
	global_load_lds_dwordx4 v[148:149], off
	v_lshl_add_u64 v[148:149], s[18:19], 0, v[134:135]
	s_add_i32 m0, s20, 0x2000
	s_nop 0
	global_load_lds_dwordx4 v[148:149], off
	v_lshl_add_u64 v[148:149], v[212:213], 0, s[16:17]
	s_mov_b32 m0, s55
	s_nop 0
	global_load_lds_dwordx4 v[148:149], off
	v_lshl_add_u64 v[148:149], v[214:215], 0, s[16:17]
	s_mov_b32 m0, s56
	s_nop 0
	global_load_lds_dwordx4 v[148:149], off
	s_waitcnt vmcnt(8)
	s_waitcnt lgkmcnt(0)
	s_barrier
	s_waitcnt lgkmcnt(0)
	v_mfma_f32_16x16x32_bf16 v[62:65], v[140:143], v[178:181], v[62:65]
	v_mfma_f32_16x16x32_bf16 v[58:61], v[154:157], v[178:181], v[58:61]
	v_mfma_f32_16x16x32_bf16 v[46:49], v[140:143], v[186:189], v[46:49]
	v_mfma_f32_16x16x32_bf16 v[42:45], v[154:157], v[186:189], v[42:45]
	v_mfma_f32_16x16x32_bf16 v[30:33], v[140:143], v[194:197], v[30:33]
	v_mfma_f32_16x16x32_bf16 v[26:29], v[154:157], v[194:197], v[26:29]
	v_mfma_f32_16x16x32_bf16 v[14:17], v[140:143], v[202:205], v[14:17]
	v_mfma_f32_16x16x32_bf16 v[10:13], v[154:157], v[202:205], v[10:13]
	v_mfma_f32_16x16x32_bf16 v[62:65], v[144:147], v[182:185], v[62:65]
	v_mfma_f32_16x16x32_bf16 v[58:61], v[158:161], v[182:185], v[58:61]
	v_mfma_f32_16x16x32_bf16 v[46:49], v[144:147], v[190:193], v[46:49]
	v_mfma_f32_16x16x32_bf16 v[42:45], v[158:161], v[190:193], v[42:45]
	v_mfma_f32_16x16x32_bf16 v[30:33], v[144:147], v[198:201], v[30:33]
	v_mfma_f32_16x16x32_bf16 v[26:29], v[158:161], v[198:201], v[26:29]
	v_mfma_f32_16x16x32_bf16 v[14:17], v[144:147], v[206:209], v[14:17]
	v_mfma_f32_16x16x32_bf16 v[10:13], v[158:161], v[206:209], v[10:13]
	v_mfma_f32_16x16x32_bf16 v[54:57], v[162:165], v[178:181], v[54:57]
	v_mfma_f32_16x16x32_bf16 v[50:53], v[170:173], v[178:181], v[50:53]
	v_mfma_f32_16x16x32_bf16 v[38:41], v[162:165], v[186:189], v[38:41]
	v_mfma_f32_16x16x32_bf16 v[34:37], v[170:173], v[186:189], v[34:37]
	v_mfma_f32_16x16x32_bf16 v[22:25], v[162:165], v[194:197], v[22:25]
	v_mfma_f32_16x16x32_bf16 v[18:21], v[170:173], v[194:197], v[18:21]
	v_mfma_f32_16x16x32_bf16 v[6:9], v[162:165], v[202:205], v[6:9]
	v_mfma_f32_16x16x32_bf16 v[2:5], v[170:173], v[202:205], v[2:5]
	v_mfma_f32_16x16x32_bf16 v[54:57], v[166:169], v[182:185], v[54:57]
	v_mfma_f32_16x16x32_bf16 v[50:53], v[174:177], v[182:185], v[50:53]
	v_mfma_f32_16x16x32_bf16 v[38:41], v[166:169], v[190:193], v[38:41]
	v_mfma_f32_16x16x32_bf16 v[34:37], v[174:177], v[190:193], v[34:37]
	v_mfma_f32_16x16x32_bf16 v[22:25], v[166:169], v[198:201], v[22:25]
	v_mfma_f32_16x16x32_bf16 v[18:21], v[174:177], v[198:201], v[18:21]
	v_mfma_f32_16x16x32_bf16 v[6:9], v[166:169], v[206:209], v[6:9]
	v_mfma_f32_16x16x32_bf16 v[2:5], v[174:177], v[206:209], v[2:5]
	s_barrier
	s_add_i32 s40, s40, 2
	s_add_u32 s36, s36, 0x100
	s_addc_u32 s37, s37, 0
	s_add_u32 s24, s24, 0x100
	s_addc_u32 s25, s25, 0
	s_cmp_gt_u32 s40, 5
	s_cbranch_scc0 .LBB0_664
	s_and_b64 vcc, exec, s[6:7]
	s_cbranch_vccz .LBB0_667
	s_barrier

; #define PG8_STAGE(bufoff, gbase, voff) do { _Pragma("unroll") for (int _i = 0; _i < 2; ++_i) \
;         __builtin_amdgcn_global_load_lds((const unsigned*)((const char*)(gbase) + (voff)[_i]), (LAS unsigned*)(lds + (bufoff) + ldsw + _i * 8192), 16, 0, 0); } while (0)
; #define PG8_LDA(dst, b, h) do { _Pragma("unroll") for (int m = 0; m < 4; ++m) _Pragma("unroll") for (int k = 0; k < 2; ++k) dst[m][k] = *(const LAS bf16x8*)(lds + PG8_SA(b, h) + aoff + m * 2048 + k * 1024); } while (0)
; #define PG8_LDB(dst, b, h) do { _Pragma("unroll") for (int n = 0; n < 2; ++n) _Pragma("unroll") for (int k = 0; k < 2; ++k) dst[n][k] = *(const LAS bf16x8*)(lds + PG8_SB(b, h) + boff + n * 2048 + k * 1024); } while (0)
; #define PG8_MMA(ai, bj, At, Bt) do { __builtin_amdgcn_s_setprio(1); _Pragma("unroll") for (int m = 0; m < 4; ++m) _Pragma("unroll") for (int n = 0; n < 2; ++n) _Pragma("unroll") for (int k = 0; k < 2; ++k) \
;         acc[ai][bj][m][n] = __builtin_amdgcn_mfma_f32_16x16x32_bf16(Bt[n][k], At[m][k], acc[ai][bj][m][n], 0, 0, 0); __builtin_amdgcn_s_setprio(0); } while (0)
; #define PG8_WAIT_V(n) asm volatile("s_waitcnt vmcnt(" #n ")" ::: "memory")
; #define PG8_WAIT_L(n) asm volatile("s_waitcnt lgkmcnt(" #n ")" ::: "memory")
; #define PG8_BAR __builtin_amdgcn_s_barrier()
; #define PG8_SCHED __builtin_amdgcn_sched_barrier(0)
; template <class Epi, bool ALIGN_EPI, bool ASLOT = false>
; __device__ __forceinline__ void gemm_phase(LAS unsigned char* lds, const Gemm g, const Sched& S, const Epi& E) {
;     ...
;         for (int t = 0; t < nt; t += 2) {
;             const bool last = (t == nt - 2);
;             const char* a1 = cA + (size_t)(t + 1) * kstep;
;             const char* a2 = last ? nA : cA + (size_t)(t + 2) * kstep; const char* b2 = last ? nB : cB + (size_t)(t + 2) * kstep;
;             const char* a3 = a2 + kstep; const char* b3 = b2 + kstep;
;             PG8_LDB(B0, 0, 0); PG8_LDB(B1, 0, 1); PG8_SCHED; PG8_LDA(At, 0, 0); PG8_STAGE(PG8_SA(1, 1), a1 + hstep, voffA);
;             PG8_WAIT_V(8); PG8_WAIT_L(0); PG8_BAR; PG8_MMA(0, 0, At, B0); PG8_MMA(0, 1, At, B1); PG8_BAR; PG8_SCHED;
;             PG8_LDA(At, 0, 1); PG8_STAGE(PG8_SB(0, 0), b2, voffB); PG8_STAGE(PG8_SB(0, 1), b2 + hstep, voffB); PG8_STAGE(PG8_SA(0, 0), a2, voffA);
;             PG8_WAIT_V(8); PG8_WAIT_L(0); PG8_BAR; PG8_MMA(1, 0, At, B0); PG8_MMA(1, 1, At, B1); PG8_BAR; PG8_SCHED;
.LBB0_783:
	v_add_u32_e32 v156, s28, v142
	v_add_u32_e32 v172, s33, v142
	s_add_u32 s6, s30, s4
	ds_read_b128 v[144:147], v156
	ds_read_b128 v[148:151], v156 offset:1024
	ds_read_b128 v[152:155], v156 offset:2048
	ds_read_b128 v[156:159], v156 offset:3072
	ds_read_b128 v[160:163], v172
	ds_read_b128 v[164:167], v172 offset:1024
	ds_read_b128 v[168:171], v172 offset:2048
	ds_read_b128 v[172:175], v172 offset:3072
	s_addc_u32 s7, s38, s5
	s_add_u32 s6, s6, 0x4800100
	s_addc_u32 s7, s7, 0
	s_add_u32 s22, s19, s4
	s_addc_u32 s23, s20, s5
	s_cmpk_eq_i32 s4, 0x700
	s_cselect_b32 s9, s37, s7
	s_cselect_b32 s8, s36, s6
	s_cselect_b32 s7, s1, s23
	s_cselect_b32 s6, s0, s22
	v_lshl_add_u64 v[208:209], v[136:137], 0, s[4:5]
	s_add_i32 m0, s10, 0xc000
	ds_read_b128 v[176:179], v143
	ds_read_b128 v[180:183], v143 offset:1024
	ds_read_b128 v[184:187], v143 offset:2048
	ds_read_b128 v[188:191], v143 offset:3072
	ds_read_b128 v[192:195], v143 offset:4096
	ds_read_b128 v[196:199], v143 offset:5120
	ds_read_b128 v[200:203], v143 offset:6144
	ds_read_b128 v[204:207], v143 offset:7168
	global_load_lds_dwordx4 v[208:209], off
	v_lshl_add_u64 v[208:209], v[138:139], 0, s[4:5]
	s_add_i32 m0, s10, 0xe000
	s_nop 0
	global_load_lds_dwordx4 v[208:209], off
	s_waitcnt vmcnt(8)
	s_waitcnt lgkmcnt(0)
	s_barrier
	s_waitcnt lgkmcnt(0)
	v_mfma_f32_16x16x32_bf16 v[126:129], v[144:147], v[176:179], v[126:129]
	v_mfma_f32_16x16x32_bf16 v[122:125], v[152:155], v[176:179], v[122:125]
	v_mfma_f32_16x16x32_bf16 v[118:121], v[144:147], v[184:187], v[118:121]
	v_mfma_f32_16x16x32_bf16 v[114:117], v[152:155], v[184:187], v[114:117]
	v_mfma_f32_16x16x32_bf16 v[102:105], v[144:147], v[192:195], v[102:105]
	v_mfma_f32_16x16x32_bf16 v[98:101], v[152:155], v[192:195], v[98:101]
	v_mfma_f32_16x16x32_bf16 v[86:89], v[144:147], v[200:203], v[86:89]
	v_mfma_f32_16x16x32_bf16 v[82:85], v[152:155], v[200:203], v[82:85]
	v_mfma_f32_16x16x32_bf16 v[126:129], v[148:151], v[180:183], v[126:129]
	v_mfma_f32_16x16x32_bf16 v[122:125], v[156:159], v[180:183], v[122:125]
	v_mfma_f32_16x16x32_bf16 v[118:121], v[148:151], v[188:191], v[118:121]
	v_mfma_f32_16x16x32_bf16 v[114:117], v[156:159], v[188:191], v[114:117]
	v_mfma_f32_16x16x32_bf16 v[102:105], v[148:151], v[196:199], v[102:105]
	v_mfma_f32_16x16x32_bf16 v[98:101], v[156:159], v[196:199], v[98:101]
	v_mfma_f32_16x16x32_bf16 v[86:89], v[148:151], v[204:207], v[86:89]
	v_mfma_f32_16x16x32_bf16 v[82:85], v[156:159], v[204:207], v[82:85]
	v_mfma_f32_16x16x32_bf16 v[110:113], v[160:163], v[176:179], v[110:113]
	v_mfma_f32_16x16x32_bf16 v[106:109], v[168:171], v[176:179], v[106:109]
	v_mfma_f32_16x16x32_bf16 v[94:97], v[160:163], v[184:187], v[94:97]
	v_mfma_f32_16x16x32_bf16 v[90:93], v[168:171], v[184:187], v[90:93]
	v_mfma_f32_16x16x32_bf16 v[78:81], v[160:163], v[192:195], v[78:81]
	v_mfma_f32_16x16x32_bf16 v[74:77], v[168:171], v[192:195], v[74:77]
	v_mfma_f32_16x16x32_bf16 v[70:73], v[160:163], v[200:203], v[70:73]
	v_mfma_f32_16x16x32_bf16 v[66:69], v[168:171], v[200:203], v[66:69]
	v_mfma_f32_16x16x32_bf16 v[110:113], v[164:167], v[180:183], v[110:113]
	v_mfma_f32_16x16x32_bf16 v[106:109], v[172:175], v[180:183], v[106:109]
	v_mfma_f32_16x16x32_bf16 v[94:97], v[164:167], v[188:191], v[94:97]
	v_mfma_f32_16x16x32_bf16 v[90:93], v[172:175], v[188:191], v[90:93]
	v_mfma_f32_16x16x32_bf16 v[78:81], v[164:167], v[196:199], v[78:81]
	v_mfma_f32_16x16x32_bf16 v[74:77], v[172:175], v[196:199], v[74:77]
	v_mfma_f32_16x16x32_bf16 v[70:73], v[164:167], v[204:207], v[70:73]
	v_mfma_f32_16x16x32_bf16 v[66:69], v[172:175], v[204:207], v[66:69]
	s_barrier
	s_add_i32 s22, s28, s3
	v_lshl_add_u64 v[208:209], s[6:7], 0, v[0:1]
	s_mov_b32 m0, s22
	ds_read_b128 v[176:179], v143 offset:16384
	ds_read_b128 v[180:183], v143 offset:17408
	ds_read_b128 v[184:187], v143 offset:18432
	ds_read_b128 v[188:191], v143 offset:19456
	ds_read_b128 v[192:195], v143 offset:20480
	ds_read_b128 v[196:199], v143 offset:21504
	ds_read_b128 v[200:203], v143 offset:22528
	ds_read_b128 v[204:207], v143 offset:23552
	global_load_lds_dwordx4 v[208:209], off
	s_add_i32 m0, s22, 0x2000
	s_add_u32 s22, s6, 0x40000
	v_lshl_add_u64 v[210:211], s[6:7], 0, v[134:135]
	s_addc_u32 s23, s7, 0
	s_add_i32 s24, s33, s3
	global_load_lds_dwordx4 v[210:211], off
	v_lshl_add_u64 v[212:213], s[22:23], 0, v[0:1]
	s_mov_b32 m0, s24
	v_lshl_add_u64 v[214:215], s[8:9], 0, v[132:133]
	global_load_lds_dwordx4 v[212:213], off
	v_lshl_add_u64 v[212:213], s[22:23], 0, v[134:135]
	s_add_i32 m0, s24, 0x2000
	s_nop 0
	global_load_lds_dwordx4 v[212:213], off
	v_lshl_add_u64 v[212:213], s[8:9], 0, v[130:131]
	s_mov_b32 m0, s10
	s_nop 0
	global_load_lds_dwordx4 v[212:213], off
	s_mov_b32 m0, s11
	s_nop 0
	global_load_lds_dwordx4 v[214:215], off
	s_waitcnt vmcnt(8)
	s_waitcnt lgkmcnt(0)
	s_barrier
; #define PG8_STAGE(bufoff, gbase, voff) do { _Pragma("unroll") for (int _i = 0; _i < 2; ++_i) \
;         __builtin_amdgcn_global_load_lds((const unsigned*)((const char*)(gbase) + (voff)[_i]), (LAS unsigned*)(lds + (bufoff) + ldsw + _i * 8192), 16, 0, 0); } while (0)
; #define PG8_LDA(dst, b, h) do { _Pragma("unroll") for (int m = 0; m < 4; ++m) _Pragma("unroll") for (int k = 0; k < 2; ++k) dst[m][k] = *(const LAS bf16x8*)(lds + PG8_SA(b, h) + aoff + m * 2048 + k * 1024); } while (0)
; #define PG8_LDB(dst, b, h) do { _Pragma("unroll") for (int n = 0; n < 2; ++n) _Pragma("unroll") for (int k = 0; k < 2; ++k) dst[n][k] = *(const LAS bf16x8*)(lds + PG8_SB(b, h) + boff + n * 2048 + k * 1024); } while (0)
; #define PG8_MMA(ai, bj, At, Bt) do { __builtin_amdgcn_s_setprio(1); _Pragma("unroll") for (int m = 0; m < 4; ++m) _Pragma("unroll") for (int n = 0; n < 2; ++n) _Pragma("unroll") for (int k = 0; k < 2; ++k) \
;         acc[ai][bj][m][n] = __builtin_amdgcn_mfma_f32_16x16x32_bf16(Bt[n][k], At[m][k], acc[ai][bj][m][n], 0, 0, 0); __builtin_amdgcn_s_setprio(0); } while (0)
; #define PG8_WAIT_V(n) asm volatile("s_waitcnt vmcnt(" #n ")" ::: "memory")
; #define PG8_WAIT_L(n) asm volatile("s_waitcnt lgkmcnt(" #n ")" ::: "memory")
; #define PG8_BAR __builtin_amdgcn_s_barrier()
; #define PG8_SCHED __builtin_amdgcn_sched_barrier(0)
; template <class Epi, bool ALIGN_EPI, bool ASLOT = false>
; __device__ __forceinline__ void gemm_phase(LAS unsigned char* lds, const Gemm g, const Sched& S, const Epi& E) {
;     ...
;             PG8_WAIT_V(8); PG8_WAIT_L(0); PG8_BAR; PG8_MMA(1, 0, At, B0); PG8_MMA(1, 1, At, B1); PG8_BAR; PG8_SCHED;
;             PG8_LDB(B0, 1, 0); PG8_LDB(B1, 1, 1); PG8_SCHED; PG8_LDA(At, 1, 0); PG8_STAGE(PG8_SA(0, 1), a2 + hstep, voffA);
;             PG8_WAIT_V(8); PG8_WAIT_L(0); PG8_BAR; PG8_MMA(0, 0, At, B0); PG8_MMA(0, 1, At, B1); PG8_BAR; PG8_SCHED;
	s_waitcnt lgkmcnt(0)
	v_mfma_f32_16x16x32_bf16 v[62:65], v[144:147], v[176:179], v[62:65]
	v_mfma_f32_16x16x32_bf16 v[58:61], v[152:155], v[176:179], v[58:61]
	v_mfma_f32_16x16x32_bf16 v[54:57], v[144:147], v[184:187], v[54:57]
	v_mfma_f32_16x16x32_bf16 v[50:53], v[152:155], v[184:187], v[50:53]
	v_mfma_f32_16x16x32_bf16 v[38:41], v[144:147], v[192:195], v[38:41]
	v_mfma_f32_16x16x32_bf16 v[34:37], v[152:155], v[192:195], v[34:37]
	v_mfma_f32_16x16x32_bf16 v[22:25], v[144:147], v[200:203], v[22:25]
	v_mfma_f32_16x16x32_bf16 v[18:21], v[152:155], v[200:203], v[18:21]
	v_mfma_f32_16x16x32_bf16 v[62:65], v[148:151], v[180:183], v[62:65]
	v_mfma_f32_16x16x32_bf16 v[58:61], v[156:159], v[180:183], v[58:61]
	v_mfma_f32_16x16x32_bf16 v[54:57], v[148:151], v[188:191], v[54:57]
	v_mfma_f32_16x16x32_bf16 v[50:53], v[156:159], v[188:191], v[50:53]
	v_mfma_f32_16x16x32_bf16 v[38:41], v[148:151], v[196:199], v[38:41]
	v_mfma_f32_16x16x32_bf16 v[34:37], v[156:159], v[196:199], v[34:37]
	v_mfma_f32_16x16x32_bf16 v[22:25], v[148:151], v[204:207], v[22:25]
	v_mfma_f32_16x16x32_bf16 v[18:21], v[156:159], v[204:207], v[18:21]
	v_mfma_f32_16x16x32_bf16 v[46:49], v[160:163], v[176:179], v[46:49]
	v_mfma_f32_16x16x32_bf16 v[42:45], v[168:171], v[176:179], v[42:45]
	v_mfma_f32_16x16x32_bf16 v[30:33], v[160:163], v[184:187], v[30:33]
	v_mfma_f32_16x16x32_bf16 v[26:29], v[168:171], v[184:187], v[26:29]
	v_mfma_f32_16x16x32_bf16 v[14:17], v[160:163], v[192:195], v[14:17]
	v_mfma_f32_16x16x32_bf16 v[10:13], v[168:171], v[192:195], v[10:13]
	v_mfma_f32_16x16x32_bf16 v[6:9], v[160:163], v[200:203], v[6:9]
	v_mfma_f32_16x16x32_bf16 v[2:5], v[168:171], v[200:203], v[2:5]
	v_mfma_f32_16x16x32_bf16 v[46:49], v[164:167], v[180:183], v[46:49]
	v_mfma_f32_16x16x32_bf16 v[42:45], v[172:175], v[180:183], v[42:45]
	v_mfma_f32_16x16x32_bf16 v[30:33], v[164:167], v[188:191], v[30:33]
	v_mfma_f32_16x16x32_bf16 v[26:29], v[172:175], v[188:191], v[26:29]
	v_mfma_f32_16x16x32_bf16 v[14:17], v[164:167], v[196:199], v[14:17]
	v_mfma_f32_16x16x32_bf16 v[10:13], v[172:175], v[196:199], v[10:13]
	v_mfma_f32_16x16x32_bf16 v[6:9], v[164:167], v[204:207], v[6:9]
	v_mfma_f32_16x16x32_bf16 v[2:5], v[172:175], v[204:207], v[2:5]
	s_barrier
	v_add_u32_e32 v156, s29, v142
	v_add_u32_e32 v172, s26, v142
	ds_read_b128 v[144:147], v156
	ds_read_b128 v[148:151], v156 offset:1024
	ds_read_b128 v[152:155], v156 offset:2048
	ds_read_b128 v[156:159], v156 offset:3072
	ds_read_b128 v[160:163], v172
	ds_read_b128 v[164:167], v172 offset:1024
	ds_read_b128 v[168:171], v172 offset:2048
	ds_read_b128 v[172:175], v172 offset:3072
	s_add_u32 s8, s8, 0x40000
	s_addc_u32 s9, s9, 0
	s_mov_b32 m0, s12
	v_lshl_add_u64 v[220:221], s[8:9], 0, v[130:131]
	ds_read_b128 v[176:179], v143 offset:32768
	ds_read_b128 v[180:183], v143 offset:33792
	ds_read_b128 v[184:187], v143 offset:34816
	ds_read_b128 v[188:191], v143 offset:35840
	ds_read_b128 v[192:195], v143 offset:36864
	ds_read_b128 v[196:199], v143 offset:37888
	ds_read_b128 v[200:203], v143 offset:38912
	ds_read_b128 v[204:207], v143 offset:39936
	global_load_lds_dwordx4 v[220:221], off
	v_lshl_add_u64 v[220:221], s[8:9], 0, v[132:133]
	s_mov_b32 m0, s13
	s_nop 0
	global_load_lds_dwordx4 v[220:221], off
	s_waitcnt vmcnt(8)
	s_waitcnt lgkmcnt(0)
	s_barrier
	s_waitcnt lgkmcnt(0)
	v_mfma_f32_16x16x32_bf16 v[126:129], v[144:147], v[176:179], v[126:129]
	v_mfma_f32_16x16x32_bf16 v[122:125], v[152:155], v[176:179], v[122:125]
	v_mfma_f32_16x16x32_bf16 v[118:121], v[144:147], v[184:187], v[118:121]
	v_mfma_f32_16x16x32_bf16 v[114:117], v[152:155], v[184:187], v[114:117]
	v_mfma_f32_16x16x32_bf16 v[102:105], v[144:147], v[192:195], v[102:105]
	v_mfma_f32_16x16x32_bf16 v[98:101], v[152:155], v[192:195], v[98:101]
	v_mfma_f32_16x16x32_bf16 v[86:89], v[144:147], v[200:203], v[86:89]
	v_mfma_f32_16x16x32_bf16 v[82:85], v[152:155], v[200:203], v[82:85]
	v_mfma_f32_16x16x32_bf16 v[126:129], v[148:151], v[180:183], v[126:129]
	v_mfma_f32_16x16x32_bf16 v[122:125], v[156:159], v[180:183], v[122:125]
	v_mfma_f32_16x16x32_bf16 v[118:121], v[148:151], v[188:191], v[118:121]
	v_mfma_f32_16x16x32_bf16 v[114:117], v[156:159], v[188:191], v[114:117]
	v_mfma_f32_16x16x32_bf16 v[102:105], v[148:151], v[196:199], v[102:105]
	v_mfma_f32_16x16x32_bf16 v[98:101], v[156:159], v[196:199], v[98:101]
	v_mfma_f32_16x16x32_bf16 v[86:89], v[148:151], v[204:207], v[86:89]
	v_mfma_f32_16x16x32_bf16 v[82:85], v[156:159], v[204:207], v[82:85]
	v_mfma_f32_16x16x32_bf16 v[110:113], v[160:163], v[176:179], v[110:113]
	v_mfma_f32_16x16x32_bf16 v[106:109], v[168:171], v[176:179], v[106:109]
	v_mfma_f32_16x16x32_bf16 v[94:97], v[160:163], v[184:187], v[94:97]
	v_mfma_f32_16x16x32_bf16 v[90:93], v[168:171], v[184:187], v[90:93]
	v_mfma_f32_16x16x32_bf16 v[78:81], v[160:163], v[192:195], v[78:81]
	v_mfma_f32_16x16x32_bf16 v[74:77], v[168:171], v[192:195], v[74:77]
	v_mfma_f32_16x16x32_bf16 v[70:73], v[160:163], v[200:203], v[70:73]
	v_mfma_f32_16x16x32_bf16 v[66:69], v[168:171], v[200:203], v[66:69]
	v_mfma_f32_16x16x32_bf16 v[110:113], v[164:167], v[180:183], v[110:113]
	v_mfma_f32_16x16x32_bf16 v[106:109], v[172:175], v[180:183], v[106:109]
	v_mfma_f32_16x16x32_bf16 v[94:97], v[164:167], v[188:191], v[94:97]
	v_mfma_f32_16x16x32_bf16 v[90:93], v[172:175], v[188:191], v[90:93]
	v_mfma_f32_16x16x32_bf16 v[78:81], v[164:167], v[196:199], v[78:81]
	v_mfma_f32_16x16x32_bf16 v[74:77], v[172:175], v[196:199], v[74:77]
	v_mfma_f32_16x16x32_bf16 v[70:73], v[164:167], v[204:207], v[70:73]
	v_mfma_f32_16x16x32_bf16 v[66:69], v[172:175], v[204:207], v[66:69]
	s_barrier
; #define PG8_STAGE(bufoff, gbase, voff) do { _Pragma("unroll") for (int _i = 0; _i < 2; ++_i) \
;         __builtin_amdgcn_global_load_lds((const unsigned*)((const char*)(gbase) + (voff)[_i]), (LAS unsigned*)(lds + (bufoff) + ldsw + _i * 8192), 16, 0, 0); } while (0)
; #define PG8_LDA(dst, b, h) do { _Pragma("unroll") for (int m = 0; m < 4; ++m) _Pragma("unroll") for (int k = 0; k < 2; ++k) dst[m][k] = *(const LAS bf16x8*)(lds + PG8_SA(b, h) + aoff + m * 2048 + k * 1024); } while (0)
; #define PG8_MMA(ai, bj, At, Bt) do { __builtin_amdgcn_s_setprio(1); _Pragma("unroll") for (int m = 0; m < 4; ++m) _Pragma("unroll") for (int n = 0; n < 2; ++n) _Pragma("unroll") for (int k = 0; k < 2; ++k) \
;         acc[ai][bj][m][n] = __builtin_amdgcn_mfma_f32_16x16x32_bf16(Bt[n][k], At[m][k], acc[ai][bj][m][n], 0, 0, 0); __builtin_amdgcn_s_setprio(0); } while (0)
; #define PG8_WAIT_V(n) asm volatile("s_waitcnt vmcnt(" #n ")" ::: "memory")
; #define PG8_WAIT_L(n) asm volatile("s_waitcnt lgkmcnt(" #n ")" ::: "memory")
; #define PG8_BAR __builtin_amdgcn_s_barrier()
; #define PG8_SCHED __builtin_amdgcn_sched_barrier(0)
; template <class Epi, bool ALIGN_EPI, bool ASLOT = false>
; __device__ __forceinline__ void gemm_phase(LAS unsigned char* lds, const Gemm g, const Sched& S, const Epi& E) {
;     ...
;             PG8_LDA(At, 1, 1); PG8_STAGE(PG8_SB(1, 0), b3, voffB); PG8_STAGE(PG8_SB(1, 1), b3 + hstep, voffB); PG8_STAGE(PG8_SA(1, 0), a3, voffA);
;             PG8_WAIT_V(8); PG8_WAIT_L(0); PG8_BAR; PG8_MMA(1, 0, At, B0); PG8_MMA(1, 1, At, B1); PG8_BAR; PG8_SCHED;
;         }
	s_add_i32 s8, s29, s3
	v_lshl_add_u64 v[208:209], v[208:209], 0, s[16:17]
	s_mov_b32 m0, s8
	ds_read_b128 v[176:179], v143 offset:49152
	ds_read_b128 v[180:183], v143 offset:50176
	ds_read_b128 v[184:187], v143 offset:51200
	ds_read_b128 v[188:191], v143 offset:52224
	ds_read_b128 v[192:195], v143 offset:53248
	ds_read_b128 v[196:199], v143 offset:54272
	ds_read_b128 v[200:203], v143 offset:55296
	ds_read_b128 v[204:207], v143 offset:56320
	global_load_lds_dwordx4 v[208:209], off
	s_add_i32 m0, s8, 0x2000
	s_add_u32 s6, s6, 0x40080
	v_lshl_add_u64 v[208:209], v[210:211], 0, s[16:17]
	s_addc_u32 s7, s7, 0
	s_add_i32 s8, s26, s3
	global_load_lds_dwordx4 v[208:209], off
	v_lshl_add_u64 v[208:209], s[6:7], 0, v[0:1]
	s_mov_b32 m0, s8
	s_nop 0
	global_load_lds_dwordx4 v[208:209], off
	v_lshl_add_u64 v[208:209], s[6:7], 0, v[134:135]
	s_add_i32 m0, s8, 0x2000
	s_nop 0
	global_load_lds_dwordx4 v[208:209], off
	v_lshl_add_u64 v[208:209], v[212:213], 0, s[16:17]
	s_mov_b32 m0, s15
	s_nop 0
	global_load_lds_dwordx4 v[208:209], off
	v_lshl_add_u64 v[208:209], v[214:215], 0, s[16:17]
	s_mov_b32 m0, s18
	s_nop 0
	global_load_lds_dwordx4 v[208:209], off
	s_waitcnt vmcnt(8)
	s_waitcnt lgkmcnt(0)
	s_barrier
	s_waitcnt lgkmcnt(0)
	v_mfma_f32_16x16x32_bf16 v[62:65], v[144:147], v[176:179], v[62:65]
	v_mfma_f32_16x16x32_bf16 v[58:61], v[152:155], v[176:179], v[58:61]
	v_mfma_f32_16x16x32_bf16 v[54:57], v[144:147], v[184:187], v[54:57]
	v_mfma_f32_16x16x32_bf16 v[50:53], v[152:155], v[184:187], v[50:53]
	v_mfma_f32_16x16x32_bf16 v[38:41], v[144:147], v[192:195], v[38:41]
	v_mfma_f32_16x16x32_bf16 v[34:37], v[152:155], v[192:195], v[34:37]
	v_mfma_f32_16x16x32_bf16 v[22:25], v[144:147], v[200:203], v[22:25]
	v_mfma_f32_16x16x32_bf16 v[18:21], v[152:155], v[200:203], v[18:21]
	v_mfma_f32_16x16x32_bf16 v[62:65], v[148:151], v[180:183], v[62:65]
	v_mfma_f32_16x16x32_bf16 v[58:61], v[156:159], v[180:183], v[58:61]
	v_mfma_f32_16x16x32_bf16 v[54:57], v[148:151], v[188:191], v[54:57]
	v_mfma_f32_16x16x32_bf16 v[50:53], v[156:159], v[188:191], v[50:53]
	v_mfma_f32_16x16x32_bf16 v[38:41], v[148:151], v[196:199], v[38:41]
	v_mfma_f32_16x16x32_bf16 v[34:37], v[156:159], v[196:199], v[34:37]
	v_mfma_f32_16x16x32_bf16 v[22:25], v[148:151], v[204:207], v[22:25]
	v_mfma_f32_16x16x32_bf16 v[18:21], v[156:159], v[204:207], v[18:21]
	v_mfma_f32_16x16x32_bf16 v[46:49], v[160:163], v[176:179], v[46:49]
	v_mfma_f32_16x16x32_bf16 v[42:45], v[168:171], v[176:179], v[42:45]
	v_mfma_f32_16x16x32_bf16 v[30:33], v[160:163], v[184:187], v[30:33]
	v_mfma_f32_16x16x32_bf16 v[26:29], v[168:171], v[184:187], v[26:29]
	v_mfma_f32_16x16x32_bf16 v[14:17], v[160:163], v[192:195], v[14:17]
	v_mfma_f32_16x16x32_bf16 v[10:13], v[168:171], v[192:195], v[10:13]
	v_mfma_f32_16x16x32_bf16 v[6:9], v[160:163], v[200:203], v[6:9]
	v_mfma_f32_16x16x32_bf16 v[2:5], v[168:171], v[200:203], v[2:5]
	v_mfma_f32_16x16x32_bf16 v[46:49], v[164:167], v[180:183], v[46:49]
	v_mfma_f32_16x16x32_bf16 v[42:45], v[172:175], v[180:183], v[42:45]
	v_mfma_f32_16x16x32_bf16 v[30:33], v[164:167], v[188:191], v[30:33]
	v_mfma_f32_16x16x32_bf16 v[26:29], v[172:175], v[188:191], v[26:29]
	v_mfma_f32_16x16x32_bf16 v[14:17], v[164:167], v[196:199], v[14:17]
	v_mfma_f32_16x16x32_bf16 v[10:13], v[172:175], v[196:199], v[10:13]
	v_mfma_f32_16x16x32_bf16 v[6:9], v[164:167], v[204:207], v[6:9]
	v_mfma_f32_16x16x32_bf16 v[2:5], v[172:175], v[204:207], v[2:5]
	s_barrier
	s_add_i32 s21, s21, 2
	s_add_u32 s4, s4, 0x100
	s_addc_u32 s5, s5, 0
	s_cmp_gt_u32 s21, 13
	s_cbranch_scc0 .LBB0_783
	s_cmpk_lt_u32 s2, 0x100
	s_cbranch_scc0 .LBB0_786
	s_barrier

; #define PG8_STAGE(bufoff, gbase, voff) do { _Pragma("unroll") for (int _i = 0; _i < 2; ++_i) \
;         __builtin_amdgcn_global_load_lds((const unsigned*)((const char*)(gbase) + (voff)[_i]), (LAS unsigned*)(lds + (bufoff) + ldsw + _i * 8192), 16, 0, 0); } while (0)
; #define PG8_LDA(dst, b, h) do { _Pragma("unroll") for (int m = 0; m < 4; ++m) _Pragma("unroll") for (int k = 0; k < 2; ++k) dst[m][k] = *(const LAS bf16x8*)(lds + PG8_SA(b, h) + aoff + m * 2048 + k * 1024); } while (0)
; #define PG8_LDB(dst, b, h) do { _Pragma("unroll") for (int n = 0; n < 2; ++n) _Pragma("unroll") for (int k = 0; k < 2; ++k) dst[n][k] = *(const LAS bf16x8*)(lds + PG8_SB(b, h) + boff + n * 2048 + k * 1024); } while (0)
; #define PG8_MMA(ai, bj, At, Bt) do { __builtin_amdgcn_s_setprio(1); _Pragma("unroll") for (int m = 0; m < 4; ++m) _Pragma("unroll") for (int n = 0; n < 2; ++n) _Pragma("unroll") for (int k = 0; k < 2; ++k) \
;         acc[ai][bj][m][n] = __builtin_amdgcn_mfma_f32_16x16x32_bf16(Bt[n][k], At[m][k], acc[ai][bj][m][n], 0, 0, 0); __builtin_amdgcn_s_setprio(0); } while (0)
; #define PG8_WAIT_V(n) asm volatile("s_waitcnt vmcnt(" #n ")" ::: "memory")
; #define PG8_WAIT_L(n) asm volatile("s_waitcnt lgkmcnt(" #n ")" ::: "memory")
; #define PG8_BAR __builtin_amdgcn_s_barrier()
; #define PG8_SCHED __builtin_amdgcn_sched_barrier(0)
; template <class Epi, bool ALIGN_EPI, bool ASLOT = false>
; __device__ __forceinline__ void gemm_phase(LAS unsigned char* lds, const Gemm g, const Sched& S, const Epi& E) {
;     ...
;         for (int t = 0; t < nt; t += 2) {
;             const bool last = (t == nt - 2);
;             const char* a1 = cA + (size_t)(t + 1) * kstep;
;             const char* a2 = last ? nA : cA + (size_t)(t + 2) * kstep; const char* b2 = last ? nB : cB + (size_t)(t + 2) * kstep;
;             const char* a3 = a2 + kstep; const char* b3 = b2 + kstep;
;             PG8_LDB(B0, 0, 0); PG8_LDB(B1, 0, 1); PG8_SCHED; PG8_LDA(At, 0, 0); PG8_STAGE(PG8_SA(1, 1), a1 + hstep, voffA);
;             PG8_WAIT_V(8); PG8_WAIT_L(0); PG8_BAR; PG8_MMA(0, 0, At, B0); PG8_MMA(0, 1, At, B1); PG8_BAR; PG8_SCHED;
;             PG8_LDA(At, 0, 1); PG8_STAGE(PG8_SB(0, 0), b2, voffB); PG8_STAGE(PG8_SB(0, 1), b2 + hstep, voffB); PG8_STAGE(PG8_SA(0, 0), a2, voffA);
;             PG8_WAIT_V(8); PG8_WAIT_L(0); PG8_BAR; PG8_MMA(1, 0, At, B0); PG8_MMA(1, 1, At, B1); PG8_BAR; PG8_SCHED;
.LBB0_853:
	v_add_u32_e32 v156, s28, v158
	ds_read_b128 v[162:165], v156
	ds_read_b128 v[166:169], v156 offset:1024
	ds_read_b128 v[170:173], v156 offset:2048
	ds_read_b128 v[174:177], v156 offset:3072
	v_add_u32_e32 v156, s33, v158
	ds_read_b128 v[178:181], v156
	ds_read_b128 v[182:185], v156 offset:1024
	ds_read_b128 v[186:189], v156 offset:2048
	ds_read_b128 v[190:193], v156 offset:3072
	s_add_u32 s18, s36, 0xfffc0080
	s_addc_u32 s19, s37, -1
	s_cmp_eq_u32 s50, 12
	s_cselect_b32 s21, s9, s19
	s_cselect_b32 s20, s24, s18
	s_cselect_b32 s19, s11, s49
	s_cselect_b32 s18, s25, s48
	v_lshl_add_u64 v[156:157], s[36:37], 0, v[152:153]
	s_add_i32 m0, s42, 0xc000
	ds_read_b128 v[194:197], v160
	ds_read_b128 v[198:201], v160 offset:1024
	ds_read_b128 v[202:205], v160 offset:2048
	ds_read_b128 v[206:209], v160 offset:3072
	ds_read_b128 v[210:213], v160 offset:4096
	ds_read_b128 v[220:223], v160 offset:5120
	ds_read_b128 v[236:239], v160 offset:6144
	ds_read_b128 v[240:243], v160 offset:7168
	global_load_lds_dwordx4 v[156:157], off
	v_lshl_add_u64 v[156:157], s[36:37], 0, v[154:155]
	s_add_i32 m0, s42, 0xe000
	s_nop 0
	global_load_lds_dwordx4 v[156:157], off
	s_waitcnt vmcnt(8)
	s_waitcnt lgkmcnt(0)
	s_barrier
	s_waitcnt lgkmcnt(0)
	v_mfma_f32_16x16x32_bf16 v[126:129], v[162:165], v[194:197], v[126:129]
	v_mfma_f32_16x16x32_bf16 v[122:125], v[170:173], v[194:197], v[122:125]
	v_mfma_f32_16x16x32_bf16 v[110:113], v[162:165], v[202:205], v[110:113]
	v_mfma_f32_16x16x32_bf16 v[106:109], v[170:173], v[202:205], v[106:109]
	v_mfma_f32_16x16x32_bf16 v[94:97], v[162:165], v[210:213], v[94:97]
	v_mfma_f32_16x16x32_bf16 v[90:93], v[170:173], v[210:213], v[90:93]
	v_mfma_f32_16x16x32_bf16 v[78:81], v[162:165], v[236:239], v[78:81]
	v_mfma_f32_16x16x32_bf16 v[74:77], v[170:173], v[236:239], v[74:77]
	v_mfma_f32_16x16x32_bf16 v[126:129], v[166:169], v[198:201], v[126:129]
	v_mfma_f32_16x16x32_bf16 v[122:125], v[174:177], v[198:201], v[122:125]
	v_mfma_f32_16x16x32_bf16 v[110:113], v[166:169], v[206:209], v[110:113]
	v_mfma_f32_16x16x32_bf16 v[106:109], v[174:177], v[206:209], v[106:109]
	v_mfma_f32_16x16x32_bf16 v[94:97], v[166:169], v[220:223], v[94:97]
	v_mfma_f32_16x16x32_bf16 v[90:93], v[174:177], v[220:223], v[90:93]
	v_mfma_f32_16x16x32_bf16 v[78:81], v[166:169], v[240:243], v[78:81]
	v_mfma_f32_16x16x32_bf16 v[74:77], v[174:177], v[240:243], v[74:77]
	v_mfma_f32_16x16x32_bf16 v[118:121], v[178:181], v[194:197], v[118:121]
	v_mfma_f32_16x16x32_bf16 v[114:117], v[186:189], v[194:197], v[114:117]
	v_mfma_f32_16x16x32_bf16 v[102:105], v[178:181], v[202:205], v[102:105]
	v_mfma_f32_16x16x32_bf16 v[98:101], v[186:189], v[202:205], v[98:101]
	v_mfma_f32_16x16x32_bf16 v[86:89], v[178:181], v[210:213], v[86:89]
	v_mfma_f32_16x16x32_bf16 v[82:85], v[186:189], v[210:213], v[82:85]
	v_mfma_f32_16x16x32_bf16 v[70:73], v[178:181], v[236:239], v[70:73]
	v_mfma_f32_16x16x32_bf16 v[66:69], v[186:189], v[236:239], v[66:69]
	v_mfma_f32_16x16x32_bf16 v[118:121], v[182:185], v[198:201], v[118:121]
	v_mfma_f32_16x16x32_bf16 v[114:117], v[190:193], v[198:201], v[114:117]
	v_mfma_f32_16x16x32_bf16 v[102:105], v[182:185], v[206:209], v[102:105]
	v_mfma_f32_16x16x32_bf16 v[98:101], v[190:193], v[206:209], v[98:101]
	v_mfma_f32_16x16x32_bf16 v[86:89], v[182:185], v[220:223], v[86:89]
	v_mfma_f32_16x16x32_bf16 v[82:85], v[190:193], v[220:223], v[82:85]
	v_mfma_f32_16x16x32_bf16 v[70:73], v[182:185], v[240:243], v[70:73]
	v_mfma_f32_16x16x32_bf16 v[66:69], v[190:193], v[240:243], v[66:69]
	s_barrier
	s_add_i32 s22, s28, s39
	v_lshl_add_u64 v[156:157], s[18:19], 0, v[0:1]
	s_mov_b32 m0, s22
	ds_read_b128 v[194:197], v160 offset:16384
	ds_read_b128 v[198:201], v160 offset:17408
	ds_read_b128 v[202:205], v160 offset:18432
	ds_read_b128 v[206:209], v160 offset:19456
	ds_read_b128 v[210:213], v160 offset:20480
	ds_read_b128 v[220:223], v160 offset:21504
	ds_read_b128 v[236:239], v160 offset:22528
	ds_read_b128 v[240:243], v160 offset:23552
	global_load_lds_dwordx4 v[156:157], off
	s_add_i32 m0, s22, 0x2000
	s_add_u32 s22, s18, 0x40000
	v_lshl_add_u64 v[214:215], s[18:19], 0, v[134:135]
	s_addc_u32 s23, s19, 0
	s_add_i32 s30, s33, s39
	global_load_lds_dwordx4 v[214:215], off
	v_lshl_add_u64 v[232:233], s[22:23], 0, v[0:1]
	s_mov_b32 m0, s30
	v_lshl_add_u64 v[244:245], s[20:21], 0, v[132:133]
	global_load_lds_dwordx4 v[232:233], off
	v_lshl_add_u64 v[232:233], s[22:23], 0, v[134:135]
	s_add_i32 m0, s30, 0x2000
	s_nop 0
	global_load_lds_dwordx4 v[232:233], off
	v_lshl_add_u64 v[232:233], s[20:21], 0, v[130:131]
	s_mov_b32 m0, s42
	s_nop 0
	global_load_lds_dwordx4 v[232:233], off
	s_mov_b32 m0, s43
	s_nop 0
	global_load_lds_dwordx4 v[244:245], off
	s_waitcnt vmcnt(8)
	s_waitcnt lgkmcnt(0)
	s_barrier
; #define PG8_STAGE(bufoff, gbase, voff) do { _Pragma("unroll") for (int _i = 0; _i < 2; ++_i) \
;         __builtin_amdgcn_global_load_lds((const unsigned*)((const char*)(gbase) + (voff)[_i]), (LAS unsigned*)(lds + (bufoff) + ldsw + _i * 8192), 16, 0, 0); } while (0)
; #define PG8_LDA(dst, b, h) do { _Pragma("unroll") for (int m = 0; m < 4; ++m) _Pragma("unroll") for (int k = 0; k < 2; ++k) dst[m][k] = *(const LAS bf16x8*)(lds + PG8_SA(b, h) + aoff + m * 2048 + k * 1024); } while (0)
; #define PG8_LDB(dst, b, h) do { _Pragma("unroll") for (int n = 0; n < 2; ++n) _Pragma("unroll") for (int k = 0; k < 2; ++k) dst[n][k] = *(const LAS bf16x8*)(lds + PG8_SB(b, h) + boff + n * 2048 + k * 1024); } while (0)
; #define PG8_MMA(ai, bj, At, Bt) do { __builtin_amdgcn_s_setprio(1); _Pragma("unroll") for (int m = 0; m < 4; ++m) _Pragma("unroll") for (int n = 0; n < 2; ++n) _Pragma("unroll") for (int k = 0; k < 2; ++k) \
;         acc[ai][bj][m][n] = __builtin_amdgcn_mfma_f32_16x16x32_bf16(Bt[n][k], At[m][k], acc[ai][bj][m][n], 0, 0, 0); __builtin_amdgcn_s_setprio(0); } while (0)
; #define PG8_WAIT_V(n) asm volatile("s_waitcnt vmcnt(" #n ")" ::: "memory")
; #define PG8_WAIT_L(n) asm volatile("s_waitcnt lgkmcnt(" #n ")" ::: "memory")
; #define PG8_BAR __builtin_amdgcn_s_barrier()
; #define PG8_SCHED __builtin_amdgcn_sched_barrier(0)
; template <class Epi, bool ALIGN_EPI, bool ASLOT = false>
; __device__ __forceinline__ void gemm_phase(LAS unsigned char* lds, const Gemm g, const Sched& S, const Epi& E) {
;     ...
;             PG8_WAIT_V(8); PG8_WAIT_L(0); PG8_BAR; PG8_MMA(1, 0, At, B0); PG8_MMA(1, 1, At, B1); PG8_BAR; PG8_SCHED;
;             PG8_LDB(B0, 1, 0); PG8_LDB(B1, 1, 1); PG8_SCHED; PG8_LDA(At, 1, 0); PG8_STAGE(PG8_SA(0, 1), a2 + hstep, voffA);
;             PG8_WAIT_V(8); PG8_WAIT_L(0); PG8_BAR; PG8_MMA(0, 0, At, B0); PG8_MMA(0, 1, At, B1); PG8_BAR; PG8_SCHED;
	s_waitcnt lgkmcnt(0)
	v_mfma_f32_16x16x32_bf16 v[62:65], v[162:165], v[194:197], v[62:65]
	v_mfma_f32_16x16x32_bf16 v[58:61], v[170:173], v[194:197], v[58:61]
	v_mfma_f32_16x16x32_bf16 v[46:49], v[162:165], v[202:205], v[46:49]
	v_mfma_f32_16x16x32_bf16 v[42:45], v[170:173], v[202:205], v[42:45]
	v_mfma_f32_16x16x32_bf16 v[30:33], v[162:165], v[210:213], v[30:33]
	v_mfma_f32_16x16x32_bf16 v[26:29], v[170:173], v[210:213], v[26:29]
	v_mfma_f32_16x16x32_bf16 v[14:17], v[162:165], v[236:239], v[14:17]
	v_mfma_f32_16x16x32_bf16 v[10:13], v[170:173], v[236:239], v[10:13]
	v_mfma_f32_16x16x32_bf16 v[62:65], v[166:169], v[198:201], v[62:65]
	v_mfma_f32_16x16x32_bf16 v[58:61], v[174:177], v[198:201], v[58:61]
	v_mfma_f32_16x16x32_bf16 v[46:49], v[166:169], v[206:209], v[46:49]
	v_mfma_f32_16x16x32_bf16 v[42:45], v[174:177], v[206:209], v[42:45]
	v_mfma_f32_16x16x32_bf16 v[30:33], v[166:169], v[220:223], v[30:33]
	v_mfma_f32_16x16x32_bf16 v[26:29], v[174:177], v[220:223], v[26:29]
	v_mfma_f32_16x16x32_bf16 v[14:17], v[166:169], v[240:243], v[14:17]
	v_mfma_f32_16x16x32_bf16 v[10:13], v[174:177], v[240:243], v[10:13]
	v_mfma_f32_16x16x32_bf16 v[54:57], v[178:181], v[194:197], v[54:57]
	v_mfma_f32_16x16x32_bf16 v[50:53], v[186:189], v[194:197], v[50:53]
	v_mfma_f32_16x16x32_bf16 v[38:41], v[178:181], v[202:205], v[38:41]
	v_mfma_f32_16x16x32_bf16 v[34:37], v[186:189], v[202:205], v[34:37]
	v_mfma_f32_16x16x32_bf16 v[22:25], v[178:181], v[210:213], v[22:25]
	v_mfma_f32_16x16x32_bf16 v[18:21], v[186:189], v[210:213], v[18:21]
	v_mfma_f32_16x16x32_bf16 v[6:9], v[178:181], v[236:239], v[6:9]
	v_mfma_f32_16x16x32_bf16 v[2:5], v[186:189], v[236:239], v[2:5]
	v_mfma_f32_16x16x32_bf16 v[54:57], v[182:185], v[198:201], v[54:57]
	v_mfma_f32_16x16x32_bf16 v[50:53], v[190:193], v[198:201], v[50:53]
	v_mfma_f32_16x16x32_bf16 v[38:41], v[182:185], v[206:209], v[38:41]
	v_mfma_f32_16x16x32_bf16 v[34:37], v[190:193], v[206:209], v[34:37]
	v_mfma_f32_16x16x32_bf16 v[22:25], v[182:185], v[220:223], v[22:25]
	v_mfma_f32_16x16x32_bf16 v[18:21], v[190:193], v[220:223], v[18:21]
	v_mfma_f32_16x16x32_bf16 v[6:9], v[182:185], v[240:243], v[6:9]
	v_mfma_f32_16x16x32_bf16 v[2:5], v[190:193], v[240:243], v[2:5]
	s_barrier
	v_add_u32_e32 v161, s29, v158
	ds_read_b128 v[162:165], v161
	ds_read_b128 v[166:169], v161 offset:1024
	ds_read_b128 v[170:173], v161 offset:2048
	ds_read_b128 v[174:177], v161 offset:3072
	v_add_u32_e32 v161, s26, v158
	ds_read_b128 v[178:181], v161
	ds_read_b128 v[182:185], v161 offset:1024
	ds_read_b128 v[186:189], v161 offset:2048
	ds_read_b128 v[190:193], v161 offset:3072
	s_add_u32 s20, s20, 0x40000
	s_addc_u32 s21, s21, 0
	s_mov_b32 m0, s44
	v_lshl_add_u64 v[246:247], s[20:21], 0, v[130:131]
	ds_read_b128 v[194:197], v160 offset:32768
	ds_read_b128 v[198:201], v160 offset:33792
	ds_read_b128 v[202:205], v160 offset:34816
	ds_read_b128 v[206:209], v160 offset:35840
	ds_read_b128 v[210:213], v160 offset:36864
	ds_read_b128 v[220:223], v160 offset:37888
	ds_read_b128 v[236:239], v160 offset:38912
	ds_read_b128 v[240:243], v160 offset:39936
	global_load_lds_dwordx4 v[246:247], off
	v_lshl_add_u64 v[246:247], s[20:21], 0, v[132:133]
	s_mov_b32 m0, s45
	s_nop 0
	global_load_lds_dwordx4 v[246:247], off
	s_waitcnt vmcnt(8)
	s_waitcnt lgkmcnt(0)
	s_barrier
	s_waitcnt lgkmcnt(0)
	v_mfma_f32_16x16x32_bf16 v[126:129], v[162:165], v[194:197], v[126:129]
	v_mfma_f32_16x16x32_bf16 v[122:125], v[170:173], v[194:197], v[122:125]
	v_mfma_f32_16x16x32_bf16 v[110:113], v[162:165], v[202:205], v[110:113]
	v_mfma_f32_16x16x32_bf16 v[106:109], v[170:173], v[202:205], v[106:109]
	v_mfma_f32_16x16x32_bf16 v[94:97], v[162:165], v[210:213], v[94:97]
	v_mfma_f32_16x16x32_bf16 v[90:93], v[170:173], v[210:213], v[90:93]
	v_mfma_f32_16x16x32_bf16 v[78:81], v[162:165], v[236:239], v[78:81]
	v_mfma_f32_16x16x32_bf16 v[74:77], v[170:173], v[236:239], v[74:77]
	v_mfma_f32_16x16x32_bf16 v[126:129], v[166:169], v[198:201], v[126:129]
	v_mfma_f32_16x16x32_bf16 v[122:125], v[174:177], v[198:201], v[122:125]
	v_mfma_f32_16x16x32_bf16 v[110:113], v[166:169], v[206:209], v[110:113]
	v_mfma_f32_16x16x32_bf16 v[106:109], v[174:177], v[206:209], v[106:109]
	v_mfma_f32_16x16x32_bf16 v[94:97], v[166:169], v[220:223], v[94:97]
	v_mfma_f32_16x16x32_bf16 v[90:93], v[174:177], v[220:223], v[90:93]
	v_mfma_f32_16x16x32_bf16 v[78:81], v[166:169], v[240:243], v[78:81]
	v_mfma_f32_16x16x32_bf16 v[74:77], v[174:177], v[240:243], v[74:77]
	v_mfma_f32_16x16x32_bf16 v[118:121], v[178:181], v[194:197], v[118:121]
	v_mfma_f32_16x16x32_bf16 v[114:117], v[186:189], v[194:197], v[114:117]
	v_mfma_f32_16x16x32_bf16 v[102:105], v[178:181], v[202:205], v[102:105]
	v_mfma_f32_16x16x32_bf16 v[98:101], v[186:189], v[202:205], v[98:101]
	v_mfma_f32_16x16x32_bf16 v[86:89], v[178:181], v[210:213], v[86:89]
	v_mfma_f32_16x16x32_bf16 v[82:85], v[186:189], v[210:213], v[82:85]
	v_mfma_f32_16x16x32_bf16 v[70:73], v[178:181], v[236:239], v[70:73]
	v_mfma_f32_16x16x32_bf16 v[66:69], v[186:189], v[236:239], v[66:69]
	v_mfma_f32_16x16x32_bf16 v[118:121], v[182:185], v[198:201], v[118:121]
	v_mfma_f32_16x16x32_bf16 v[114:117], v[190:193], v[198:201], v[114:117]
	v_mfma_f32_16x16x32_bf16 v[102:105], v[182:185], v[206:209], v[102:105]
	v_mfma_f32_16x16x32_bf16 v[98:101], v[190:193], v[206:209], v[98:101]
	v_mfma_f32_16x16x32_bf16 v[86:89], v[182:185], v[220:223], v[86:89]
	v_mfma_f32_16x16x32_bf16 v[82:85], v[190:193], v[220:223], v[82:85]
	v_mfma_f32_16x16x32_bf16 v[70:73], v[182:185], v[240:243], v[70:73]
	v_mfma_f32_16x16x32_bf16 v[66:69], v[190:193], v[240:243], v[66:69]
	s_barrier
; #define PG8_STAGE(bufoff, gbase, voff) do { _Pragma("unroll") for (int _i = 0; _i < 2; ++_i) \
;         __builtin_amdgcn_global_load_lds((const unsigned*)((const char*)(gbase) + (voff)[_i]), (LAS unsigned*)(lds + (bufoff) + ldsw + _i * 8192), 16, 0, 0); } while (0)
; #define PG8_LDA(dst, b, h) do { _Pragma("unroll") for (int m = 0; m < 4; ++m) _Pragma("unroll") for (int k = 0; k < 2; ++k) dst[m][k] = *(const LAS bf16x8*)(lds + PG8_SA(b, h) + aoff + m * 2048 + k * 1024); } while (0)
; #define PG8_MMA(ai, bj, At, Bt) do { __builtin_amdgcn_s_setprio(1); _Pragma("unroll") for (int m = 0; m < 4; ++m) _Pragma("unroll") for (int n = 0; n < 2; ++n) _Pragma("unroll") for (int k = 0; k < 2; ++k) \
;         acc[ai][bj][m][n] = __builtin_amdgcn_mfma_f32_16x16x32_bf16(Bt[n][k], At[m][k], acc[ai][bj][m][n], 0, 0, 0); __builtin_amdgcn_s_setprio(0); } while (0)
; #define PG8_WAIT_V(n) asm volatile("s_waitcnt vmcnt(" #n ")" ::: "memory")
; #define PG8_WAIT_L(n) asm volatile("s_waitcnt lgkmcnt(" #n ")" ::: "memory")
; #define PG8_BAR __builtin_amdgcn_s_barrier()
; #define PG8_SCHED __builtin_amdgcn_sched_barrier(0)
; template <class Epi, bool ALIGN_EPI, bool ASLOT = false>
; __device__ __forceinline__ void gemm_phase(LAS unsigned char* lds, const Gemm g, const Sched& S, const Epi& E) {
;     ...
;             PG8_LDA(At, 1, 1); PG8_STAGE(PG8_SB(1, 0), b3, voffB); PG8_STAGE(PG8_SB(1, 1), b3 + hstep, voffB); PG8_STAGE(PG8_SA(1, 0), a3, voffA);
;             PG8_WAIT_V(8); PG8_WAIT_L(0); PG8_BAR; PG8_MMA(1, 0, At, B0); PG8_MMA(1, 1, At, B1); PG8_BAR; PG8_SCHED;
;         }
	s_add_i32 s20, s29, s39
	v_lshl_add_u64 v[156:157], v[156:157], 0, s[16:17]
	s_mov_b32 m0, s20
	ds_read_b128 v[194:197], v160 offset:49152
	ds_read_b128 v[198:201], v160 offset:50176
	ds_read_b128 v[202:205], v160 offset:51200
	ds_read_b128 v[206:209], v160 offset:52224
	ds_read_b128 v[210:213], v160 offset:53248
	ds_read_b128 v[220:223], v160 offset:54272
	ds_read_b128 v[236:239], v160 offset:55296
	ds_read_b128 v[240:243], v160 offset:56320
	global_load_lds_dwordx4 v[156:157], off
	s_add_i32 m0, s20, 0x2000
	s_add_u32 s18, s18, 0x40080
	v_lshl_add_u64 v[156:157], v[214:215], 0, s[16:17]
	s_addc_u32 s19, s19, 0
	s_add_i32 s20, s26, s39
	global_load_lds_dwordx4 v[156:157], off
	v_lshl_add_u64 v[156:157], s[18:19], 0, v[0:1]
	s_mov_b32 m0, s20
	s_nop 0
	global_load_lds_dwordx4 v[156:157], off
	v_lshl_add_u64 v[156:157], s[18:19], 0, v[134:135]
	s_add_i32 m0, s20, 0x2000
	s_nop 0
	global_load_lds_dwordx4 v[156:157], off
	v_lshl_add_u64 v[156:157], v[232:233], 0, s[16:17]
	s_mov_b32 m0, s46
	s_nop 0
	global_load_lds_dwordx4 v[156:157], off
	v_lshl_add_u64 v[156:157], v[244:245], 0, s[16:17]
	s_mov_b32 m0, s47
	s_nop 0
	global_load_lds_dwordx4 v[156:157], off
	s_waitcnt vmcnt(8)
	s_waitcnt lgkmcnt(0)
	s_barrier
	s_waitcnt lgkmcnt(0)
	v_mfma_f32_16x16x32_bf16 v[62:65], v[162:165], v[194:197], v[62:65]
	v_mfma_f32_16x16x32_bf16 v[58:61], v[170:173], v[194:197], v[58:61]
	v_mfma_f32_16x16x32_bf16 v[46:49], v[162:165], v[202:205], v[46:49]
	v_mfma_f32_16x16x32_bf16 v[42:45], v[170:173], v[202:205], v[42:45]
	v_mfma_f32_16x16x32_bf16 v[30:33], v[162:165], v[210:213], v[30:33]
	v_mfma_f32_16x16x32_bf16 v[26:29], v[170:173], v[210:213], v[26:29]
	v_mfma_f32_16x16x32_bf16 v[14:17], v[162:165], v[236:239], v[14:17]
	v_mfma_f32_16x16x32_bf16 v[10:13], v[170:173], v[236:239], v[10:13]
	v_mfma_f32_16x16x32_bf16 v[62:65], v[166:169], v[198:201], v[62:65]
	v_mfma_f32_16x16x32_bf16 v[58:61], v[174:177], v[198:201], v[58:61]
	v_mfma_f32_16x16x32_bf16 v[46:49], v[166:169], v[206:209], v[46:49]
	v_mfma_f32_16x16x32_bf16 v[42:45], v[174:177], v[206:209], v[42:45]
	v_mfma_f32_16x16x32_bf16 v[30:33], v[166:169], v[220:223], v[30:33]
	v_mfma_f32_16x16x32_bf16 v[26:29], v[174:177], v[220:223], v[26:29]
	v_mfma_f32_16x16x32_bf16 v[14:17], v[166:169], v[240:243], v[14:17]
	v_mfma_f32_16x16x32_bf16 v[10:13], v[174:177], v[240:243], v[10:13]
	v_mfma_f32_16x16x32_bf16 v[54:57], v[178:181], v[194:197], v[54:57]
	v_mfma_f32_16x16x32_bf16 v[50:53], v[186:189], v[194:197], v[50:53]
	v_mfma_f32_16x16x32_bf16 v[38:41], v[178:181], v[202:205], v[38:41]
	v_mfma_f32_16x16x32_bf16 v[34:37], v[186:189], v[202:205], v[34:37]
	v_mfma_f32_16x16x32_bf16 v[22:25], v[178:181], v[210:213], v[22:25]
	v_mfma_f32_16x16x32_bf16 v[18:21], v[186:189], v[210:213], v[18:21]
	v_mfma_f32_16x16x32_bf16 v[6:9], v[178:181], v[236:239], v[6:9]
	v_mfma_f32_16x16x32_bf16 v[2:5], v[186:189], v[236:239], v[2:5]
	v_mfma_f32_16x16x32_bf16 v[54:57], v[182:185], v[198:201], v[54:57]
	v_mfma_f32_16x16x32_bf16 v[50:53], v[190:193], v[198:201], v[50:53]
	v_mfma_f32_16x16x32_bf16 v[38:41], v[182:185], v[206:209], v[38:41]
	v_mfma_f32_16x16x32_bf16 v[34:37], v[190:193], v[206:209], v[34:37]
	v_mfma_f32_16x16x32_bf16 v[22:25], v[182:185], v[220:223], v[22:25]
	v_mfma_f32_16x16x32_bf16 v[18:21], v[190:193], v[220:223], v[18:21]
	v_mfma_f32_16x16x32_bf16 v[6:9], v[182:185], v[240:243], v[6:9]
	v_mfma_f32_16x16x32_bf16 v[2:5], v[190:193], v[240:243], v[2:5]
	s_barrier
	s_add_i32 s50, s50, 2
	s_add_u32 s36, s36, 0x100
	s_addc_u32 s37, s37, 0
	s_add_u32 s48, s48, 0x100
	s_addc_u32 s49, s49, 0
	s_cmp_gt_u32 s50, 13
	s_cbranch_scc0 .LBB0_853
	s_and_b64 vcc, exec, s[6:7]
	s_cbranch_vccz .LBB0_856
	s_barrier

; #define PG8_STAGE(bufoff, gbase, voff) do { _Pragma("unroll") for (int _i = 0; _i < 2; ++_i) \
;         __builtin_amdgcn_global_load_lds((const unsigned*)((const char*)(gbase) + (voff)[_i]), (LAS unsigned*)(lds + (bufoff) + ldsw + _i * 8192), 16, 0, 0); } while (0)
; #define PG8_LDA(dst, b, h) do { _Pragma("unroll") for (int m = 0; m < 4; ++m) _Pragma("unroll") for (int k = 0; k < 2; ++k) dst[m][k] = *(const LAS bf16x8*)(lds + PG8_SA(b, h) + aoff + m * 2048 + k * 1024); } while (0)
; #define PG8_LDB(dst, b, h) do { _Pragma("unroll") for (int n = 0; n < 2; ++n) _Pragma("unroll") for (int k = 0; k < 2; ++k) dst[n][k] = *(const LAS bf16x8*)(lds + PG8_SB(b, h) + boff + n * 2048 + k * 1024); } while (0)
; #define PG8_MMA(ai, bj, At, Bt) do { __builtin_amdgcn_s_setprio(1); _Pragma("unroll") for (int m = 0; m < 4; ++m) _Pragma("unroll") for (int n = 0; n < 2; ++n) _Pragma("unroll") for (int k = 0; k < 2; ++k) \
;         acc[ai][bj][m][n] = __builtin_amdgcn_mfma_f32_16x16x32_bf16(Bt[n][k], At[m][k], acc[ai][bj][m][n], 0, 0, 0); __builtin_amdgcn_s_setprio(0); } while (0)
; #define PG8_WAIT_V(n) asm volatile("s_waitcnt vmcnt(" #n ")" ::: "memory")
; #define PG8_WAIT_L(n) asm volatile("s_waitcnt lgkmcnt(" #n ")" ::: "memory")
; #define PG8_BAR __builtin_amdgcn_s_barrier()
; #define PG8_SCHED __builtin_amdgcn_sched_barrier(0)
; template <class Epi, bool ALIGN_EPI, bool ASLOT = false>
; __device__ __forceinline__ void gemm_phase(LAS unsigned char* lds, const Gemm g, const Sched& S, const Epi& E) {
;     ...
;         for (int t = 0; t < nt; t += 2) {
;             const bool last = (t == nt - 2);
;             const char* a1 = cA + (size_t)(t + 1) * kstep;
;             const char* a2 = last ? nA : cA + (size_t)(t + 2) * kstep; const char* b2 = last ? nB : cB + (size_t)(t + 2) * kstep;
;             const char* a3 = a2 + kstep; const char* b3 = b2 + kstep;
;             PG8_LDB(B0, 0, 0); PG8_LDB(B1, 0, 1); PG8_SCHED; PG8_LDA(At, 0, 0); PG8_STAGE(PG8_SA(1, 1), a1 + hstep, voffA);
;             PG8_WAIT_V(8); PG8_WAIT_L(0); PG8_BAR; PG8_MMA(0, 0, At, B0); PG8_MMA(0, 1, At, B1); PG8_BAR; PG8_SCHED;
;             PG8_LDA(At, 0, 1); PG8_STAGE(PG8_SB(0, 0), b2, voffB); PG8_STAGE(PG8_SB(0, 1), b2 + hstep, voffB); PG8_STAGE(PG8_SA(0, 0), a2, voffA);
;             PG8_WAIT_V(8); PG8_WAIT_L(0); PG8_BAR; PG8_MMA(1, 0, At, B0); PG8_MMA(1, 1, At, B1); PG8_BAR; PG8_SCHED;
.LBB0_884:
	v_add_u32_e32 v156, s28, v142
	v_add_u32_e32 v172, s33, v142
	s_add_u32 s8, s30, s6
	ds_read_b128 v[144:147], v156
	ds_read_b128 v[148:151], v156 offset:1024
	ds_read_b128 v[152:155], v156 offset:2048
	ds_read_b128 v[156:159], v156 offset:3072
	ds_read_b128 v[160:163], v172
	ds_read_b128 v[164:167], v172 offset:1024
	ds_read_b128 v[168:171], v172 offset:2048
	ds_read_b128 v[172:175], v172 offset:3072
	s_addc_u32 s9, s38, s7
	s_add_u32 s8, s8, 0x8800100
	s_addc_u32 s9, s9, 0
	s_add_u32 s22, s21, s6
	s_addc_u32 s23, s24, s7
	s_cmpk_eq_i32 s6, 0x1500
	s_cselect_b32 s11, s37, s9
	s_cselect_b32 s10, s36, s8
	s_cselect_b32 s9, s1, s23
	s_cselect_b32 s8, s0, s22
	v_lshl_add_u64 v[208:209], v[136:137], 0, s[6:7]
	s_add_i32 m0, s12, 0xc000
	ds_read_b128 v[176:179], v143
	ds_read_b128 v[180:183], v143 offset:1024
	ds_read_b128 v[184:187], v143 offset:2048
	ds_read_b128 v[188:191], v143 offset:3072
	ds_read_b128 v[192:195], v143 offset:4096
	ds_read_b128 v[196:199], v143 offset:5120
	ds_read_b128 v[200:203], v143 offset:6144
	ds_read_b128 v[204:207], v143 offset:7168
	global_load_lds_dwordx4 v[208:209], off
	v_lshl_add_u64 v[208:209], v[138:139], 0, s[6:7]
	s_add_i32 m0, s12, 0xe000
	s_nop 0
	global_load_lds_dwordx4 v[208:209], off
	s_waitcnt vmcnt(8)
	s_waitcnt lgkmcnt(0)
	s_barrier
	s_waitcnt lgkmcnt(0)
	v_mfma_f32_16x16x32_bf16 v[126:129], v[144:147], v[176:179], v[126:129]
	v_mfma_f32_16x16x32_bf16 v[122:125], v[152:155], v[176:179], v[122:125]
	v_mfma_f32_16x16x32_bf16 v[118:121], v[144:147], v[184:187], v[118:121]
	v_mfma_f32_16x16x32_bf16 v[114:117], v[152:155], v[184:187], v[114:117]
	v_mfma_f32_16x16x32_bf16 v[102:105], v[144:147], v[192:195], v[102:105]
	v_mfma_f32_16x16x32_bf16 v[98:101], v[152:155], v[192:195], v[98:101]
	v_mfma_f32_16x16x32_bf16 v[86:89], v[144:147], v[200:203], v[86:89]
	v_mfma_f32_16x16x32_bf16 v[82:85], v[152:155], v[200:203], v[82:85]
	v_mfma_f32_16x16x32_bf16 v[126:129], v[148:151], v[180:183], v[126:129]
	v_mfma_f32_16x16x32_bf16 v[122:125], v[156:159], v[180:183], v[122:125]
	v_mfma_f32_16x16x32_bf16 v[118:121], v[148:151], v[188:191], v[118:121]
	v_mfma_f32_16x16x32_bf16 v[114:117], v[156:159], v[188:191], v[114:117]
	v_mfma_f32_16x16x32_bf16 v[102:105], v[148:151], v[196:199], v[102:105]
	v_mfma_f32_16x16x32_bf16 v[98:101], v[156:159], v[196:199], v[98:101]
	v_mfma_f32_16x16x32_bf16 v[86:89], v[148:151], v[204:207], v[86:89]
	v_mfma_f32_16x16x32_bf16 v[82:85], v[156:159], v[204:207], v[82:85]
	v_mfma_f32_16x16x32_bf16 v[110:113], v[160:163], v[176:179], v[110:113]
	v_mfma_f32_16x16x32_bf16 v[106:109], v[168:171], v[176:179], v[106:109]
	v_mfma_f32_16x16x32_bf16 v[94:97], v[160:163], v[184:187], v[94:97]
	v_mfma_f32_16x16x32_bf16 v[90:93], v[168:171], v[184:187], v[90:93]
	v_mfma_f32_16x16x32_bf16 v[78:81], v[160:163], v[192:195], v[78:81]
	v_mfma_f32_16x16x32_bf16 v[74:77], v[168:171], v[192:195], v[74:77]
	v_mfma_f32_16x16x32_bf16 v[70:73], v[160:163], v[200:203], v[70:73]
	v_mfma_f32_16x16x32_bf16 v[66:69], v[168:171], v[200:203], v[66:69]
	v_mfma_f32_16x16x32_bf16 v[110:113], v[164:167], v[180:183], v[110:113]
	v_mfma_f32_16x16x32_bf16 v[106:109], v[172:175], v[180:183], v[106:109]
	v_mfma_f32_16x16x32_bf16 v[94:97], v[164:167], v[188:191], v[94:97]
	v_mfma_f32_16x16x32_bf16 v[90:93], v[172:175], v[188:191], v[90:93]
	v_mfma_f32_16x16x32_bf16 v[78:81], v[164:167], v[196:199], v[78:81]
	v_mfma_f32_16x16x32_bf16 v[74:77], v[172:175], v[196:199], v[74:77]
	v_mfma_f32_16x16x32_bf16 v[70:73], v[164:167], v[204:207], v[70:73]
	v_mfma_f32_16x16x32_bf16 v[66:69], v[172:175], v[204:207], v[66:69]
	s_barrier
	s_add_i32 s22, s28, s3
	v_lshl_add_u64 v[208:209], s[8:9], 0, v[0:1]
	s_mov_b32 m0, s22
	ds_read_b128 v[176:179], v143 offset:16384
	ds_read_b128 v[180:183], v143 offset:17408
	ds_read_b128 v[184:187], v143 offset:18432
	ds_read_b128 v[188:191], v143 offset:19456
	ds_read_b128 v[192:195], v143 offset:20480
	ds_read_b128 v[196:199], v143 offset:21504
	ds_read_b128 v[200:203], v143 offset:22528
	ds_read_b128 v[204:207], v143 offset:23552
	global_load_lds_dwordx4 v[208:209], off
	s_add_i32 m0, s22, 0x2000
	s_add_u32 s22, s8, 0xb0000
	v_lshl_add_u64 v[210:211], s[8:9], 0, v[134:135]
	s_addc_u32 s23, s9, 0
	s_add_i32 s27, s33, s3
	global_load_lds_dwordx4 v[210:211], off
	v_lshl_add_u64 v[212:213], s[22:23], 0, v[0:1]
	s_mov_b32 m0, s27
	v_lshl_add_u64 v[214:215], s[10:11], 0, v[132:133]
	global_load_lds_dwordx4 v[212:213], off
	v_lshl_add_u64 v[212:213], s[22:23], 0, v[134:135]
	s_add_i32 m0, s27, 0x2000
	s_nop 0
	global_load_lds_dwordx4 v[212:213], off
	v_lshl_add_u64 v[212:213], s[10:11], 0, v[130:131]
	s_mov_b32 m0, s12
	s_nop 0
	global_load_lds_dwordx4 v[212:213], off
	s_mov_b32 m0, s13
	s_nop 0
	global_load_lds_dwordx4 v[214:215], off
	s_waitcnt vmcnt(8)
	s_waitcnt lgkmcnt(0)
	s_barrier
; #define PG8_STAGE(bufoff, gbase, voff) do { _Pragma("unroll") for (int _i = 0; _i < 2; ++_i) \
;         __builtin_amdgcn_global_load_lds((const unsigned*)((const char*)(gbase) + (voff)[_i]), (LAS unsigned*)(lds + (bufoff) + ldsw + _i * 8192), 16, 0, 0); } while (0)
; #define PG8_LDA(dst, b, h) do { _Pragma("unroll") for (int m = 0; m < 4; ++m) _Pragma("unroll") for (int k = 0; k < 2; ++k) dst[m][k] = *(const LAS bf16x8*)(lds + PG8_SA(b, h) + aoff + m * 2048 + k * 1024); } while (0)
; #define PG8_LDB(dst, b, h) do { _Pragma("unroll") for (int n = 0; n < 2; ++n) _Pragma("unroll") for (int k = 0; k < 2; ++k) dst[n][k] = *(const LAS bf16x8*)(lds + PG8_SB(b, h) + boff + n * 2048 + k * 1024); } while (0)
; #define PG8_MMA(ai, bj, At, Bt) do { __builtin_amdgcn_s_setprio(1); _Pragma("unroll") for (int m = 0; m < 4; ++m) _Pragma("unroll") for (int n = 0; n < 2; ++n) _Pragma("unroll") for (int k = 0; k < 2; ++k) \
;         acc[ai][bj][m][n] = __builtin_amdgcn_mfma_f32_16x16x32_bf16(Bt[n][k], At[m][k], acc[ai][bj][m][n], 0, 0, 0); __builtin_amdgcn_s_setprio(0); } while (0)
; #define PG8_WAIT_V(n) asm volatile("s_waitcnt vmcnt(" #n ")" ::: "memory")
; #define PG8_WAIT_L(n) asm volatile("s_waitcnt lgkmcnt(" #n ")" ::: "memory")
; #define PG8_BAR __builtin_amdgcn_s_barrier()
; #define PG8_SCHED __builtin_amdgcn_sched_barrier(0)
; template <class Epi, bool ALIGN_EPI, bool ASLOT = false>
; __device__ __forceinline__ void gemm_phase(LAS unsigned char* lds, const Gemm g, const Sched& S, const Epi& E) {
;     ...
;             PG8_WAIT_V(8); PG8_WAIT_L(0); PG8_BAR; PG8_MMA(1, 0, At, B0); PG8_MMA(1, 1, At, B1); PG8_BAR; PG8_SCHED;
;             PG8_LDB(B0, 1, 0); PG8_LDB(B1, 1, 1); PG8_SCHED; PG8_LDA(At, 1, 0); PG8_STAGE(PG8_SA(0, 1), a2 + hstep, voffA);
;             PG8_WAIT_V(8); PG8_WAIT_L(0); PG8_BAR; PG8_MMA(0, 0, At, B0); PG8_MMA(0, 1, At, B1); PG8_BAR; PG8_SCHED;
	s_waitcnt lgkmcnt(0)
	v_mfma_f32_16x16x32_bf16 v[62:65], v[144:147], v[176:179], v[62:65]
	v_mfma_f32_16x16x32_bf16 v[58:61], v[152:155], v[176:179], v[58:61]
	v_mfma_f32_16x16x32_bf16 v[54:57], v[144:147], v[184:187], v[54:57]
	v_mfma_f32_16x16x32_bf16 v[50:53], v[152:155], v[184:187], v[50:53]
	v_mfma_f32_16x16x32_bf16 v[38:41], v[144:147], v[192:195], v[38:41]
	v_mfma_f32_16x16x32_bf16 v[34:37], v[152:155], v[192:195], v[34:37]
	v_mfma_f32_16x16x32_bf16 v[22:25], v[144:147], v[200:203], v[22:25]
	v_mfma_f32_16x16x32_bf16 v[18:21], v[152:155], v[200:203], v[18:21]
	v_mfma_f32_16x16x32_bf16 v[62:65], v[148:151], v[180:183], v[62:65]
	v_mfma_f32_16x16x32_bf16 v[58:61], v[156:159], v[180:183], v[58:61]
	v_mfma_f32_16x16x32_bf16 v[54:57], v[148:151], v[188:191], v[54:57]
	v_mfma_f32_16x16x32_bf16 v[50:53], v[156:159], v[188:191], v[50:53]
	v_mfma_f32_16x16x32_bf16 v[38:41], v[148:151], v[196:199], v[38:41]
	v_mfma_f32_16x16x32_bf16 v[34:37], v[156:159], v[196:199], v[34:37]
	v_mfma_f32_16x16x32_bf16 v[22:25], v[148:151], v[204:207], v[22:25]
	v_mfma_f32_16x16x32_bf16 v[18:21], v[156:159], v[204:207], v[18:21]
	v_mfma_f32_16x16x32_bf16 v[46:49], v[160:163], v[176:179], v[46:49]
	v_mfma_f32_16x16x32_bf16 v[42:45], v[168:171], v[176:179], v[42:45]
	v_mfma_f32_16x16x32_bf16 v[30:33], v[160:163], v[184:187], v[30:33]
	v_mfma_f32_16x16x32_bf16 v[26:29], v[168:171], v[184:187], v[26:29]
	v_mfma_f32_16x16x32_bf16 v[14:17], v[160:163], v[192:195], v[14:17]
	v_mfma_f32_16x16x32_bf16 v[10:13], v[168:171], v[192:195], v[10:13]
	v_mfma_f32_16x16x32_bf16 v[6:9], v[160:163], v[200:203], v[6:9]
	v_mfma_f32_16x16x32_bf16 v[2:5], v[168:171], v[200:203], v[2:5]
	v_mfma_f32_16x16x32_bf16 v[46:49], v[164:167], v[180:183], v[46:49]
	v_mfma_f32_16x16x32_bf16 v[42:45], v[172:175], v[180:183], v[42:45]
	v_mfma_f32_16x16x32_bf16 v[30:33], v[164:167], v[188:191], v[30:33]
	v_mfma_f32_16x16x32_bf16 v[26:29], v[172:175], v[188:191], v[26:29]
	v_mfma_f32_16x16x32_bf16 v[14:17], v[164:167], v[196:199], v[14:17]
	v_mfma_f32_16x16x32_bf16 v[10:13], v[172:175], v[196:199], v[10:13]
	v_mfma_f32_16x16x32_bf16 v[6:9], v[164:167], v[204:207], v[6:9]
	v_mfma_f32_16x16x32_bf16 v[2:5], v[172:175], v[204:207], v[2:5]
	s_barrier
	v_add_u32_e32 v156, s29, v142
	v_add_u32_e32 v172, s26, v142
	ds_read_b128 v[144:147], v156
	ds_read_b128 v[148:151], v156 offset:1024
	ds_read_b128 v[152:155], v156 offset:2048
	ds_read_b128 v[156:159], v156 offset:3072
	ds_read_b128 v[160:163], v172
	ds_read_b128 v[164:167], v172 offset:1024
	ds_read_b128 v[168:171], v172 offset:2048
	ds_read_b128 v[172:175], v172 offset:3072
	s_add_u32 s10, s10, 0xb0000
	s_addc_u32 s11, s11, 0
	s_mov_b32 m0, s14
	v_lshl_add_u64 v[220:221], s[10:11], 0, v[130:131]
	ds_read_b128 v[176:179], v143 offset:32768
	ds_read_b128 v[180:183], v143 offset:33792
	ds_read_b128 v[184:187], v143 offset:34816
	ds_read_b128 v[188:191], v143 offset:35840
	ds_read_b128 v[192:195], v143 offset:36864
	ds_read_b128 v[196:199], v143 offset:37888
	ds_read_b128 v[200:203], v143 offset:38912
	ds_read_b128 v[204:207], v143 offset:39936
	global_load_lds_dwordx4 v[220:221], off
	v_lshl_add_u64 v[220:221], s[10:11], 0, v[132:133]
	s_mov_b32 m0, s15
	s_nop 0
	global_load_lds_dwordx4 v[220:221], off
	s_waitcnt vmcnt(8)
	s_waitcnt lgkmcnt(0)
	s_barrier
	s_waitcnt lgkmcnt(0)
	v_mfma_f32_16x16x32_bf16 v[126:129], v[144:147], v[176:179], v[126:129]
	v_mfma_f32_16x16x32_bf16 v[122:125], v[152:155], v[176:179], v[122:125]
	v_mfma_f32_16x16x32_bf16 v[118:121], v[144:147], v[184:187], v[118:121]
	v_mfma_f32_16x16x32_bf16 v[114:117], v[152:155], v[184:187], v[114:117]
	v_mfma_f32_16x16x32_bf16 v[102:105], v[144:147], v[192:195], v[102:105]
	v_mfma_f32_16x16x32_bf16 v[98:101], v[152:155], v[192:195], v[98:101]
	v_mfma_f32_16x16x32_bf16 v[86:89], v[144:147], v[200:203], v[86:89]
	v_mfma_f32_16x16x32_bf16 v[82:85], v[152:155], v[200:203], v[82:85]
	v_mfma_f32_16x16x32_bf16 v[126:129], v[148:151], v[180:183], v[126:129]
	v_mfma_f32_16x16x32_bf16 v[122:125], v[156:159], v[180:183], v[122:125]
	v_mfma_f32_16x16x32_bf16 v[118:121], v[148:151], v[188:191], v[118:121]
	v_mfma_f32_16x16x32_bf16 v[114:117], v[156:159], v[188:191], v[114:117]
	v_mfma_f32_16x16x32_bf16 v[102:105], v[148:151], v[196:199], v[102:105]
	v_mfma_f32_16x16x32_bf16 v[98:101], v[156:159], v[196:199], v[98:101]
	v_mfma_f32_16x16x32_bf16 v[86:89], v[148:151], v[204:207], v[86:89]
	v_mfma_f32_16x16x32_bf16 v[82:85], v[156:159], v[204:207], v[82:85]
	v_mfma_f32_16x16x32_bf16 v[110:113], v[160:163], v[176:179], v[110:113]
	v_mfma_f32_16x16x32_bf16 v[106:109], v[168:171], v[176:179], v[106:109]
	v_mfma_f32_16x16x32_bf16 v[94:97], v[160:163], v[184:187], v[94:97]
	v_mfma_f32_16x16x32_bf16 v[90:93], v[168:171], v[184:187], v[90:93]
	v_mfma_f32_16x16x32_bf16 v[78:81], v[160:163], v[192:195], v[78:81]
	v_mfma_f32_16x16x32_bf16 v[74:77], v[168:171], v[192:195], v[74:77]
	v_mfma_f32_16x16x32_bf16 v[70:73], v[160:163], v[200:203], v[70:73]
	v_mfma_f32_16x16x32_bf16 v[66:69], v[168:171], v[200:203], v[66:69]
	v_mfma_f32_16x16x32_bf16 v[110:113], v[164:167], v[180:183], v[110:113]
	v_mfma_f32_16x16x32_bf16 v[106:109], v[172:175], v[180:183], v[106:109]
	v_mfma_f32_16x16x32_bf16 v[94:97], v[164:167], v[188:191], v[94:97]
	v_mfma_f32_16x16x32_bf16 v[90:93], v[172:175], v[188:191], v[90:93]
	v_mfma_f32_16x16x32_bf16 v[78:81], v[164:167], v[196:199], v[78:81]
	v_mfma_f32_16x16x32_bf16 v[74:77], v[172:175], v[196:199], v[74:77]
	v_mfma_f32_16x16x32_bf16 v[70:73], v[164:167], v[204:207], v[70:73]
	v_mfma_f32_16x16x32_bf16 v[66:69], v[172:175], v[204:207], v[66:69]
	s_barrier
; #define PG8_STAGE(bufoff, gbase, voff) do { _Pragma("unroll") for (int _i = 0; _i < 2; ++_i) \
;         __builtin_amdgcn_global_load_lds((const unsigned*)((const char*)(gbase) + (voff)[_i]), (LAS unsigned*)(lds + (bufoff) + ldsw + _i * 8192), 16, 0, 0); } while (0)
; #define PG8_LDA(dst, b, h) do { _Pragma("unroll") for (int m = 0; m < 4; ++m) _Pragma("unroll") for (int k = 0; k < 2; ++k) dst[m][k] = *(const LAS bf16x8*)(lds + PG8_SA(b, h) + aoff + m * 2048 + k * 1024); } while (0)
; #define PG8_MMA(ai, bj, At, Bt) do { __builtin_amdgcn_s_setprio(1); _Pragma("unroll") for (int m = 0; m < 4; ++m) _Pragma("unroll") for (int n = 0; n < 2; ++n) _Pragma("unroll") for (int k = 0; k < 2; ++k) \
;         acc[ai][bj][m][n] = __builtin_amdgcn_mfma_f32_16x16x32_bf16(Bt[n][k], At[m][k], acc[ai][bj][m][n], 0, 0, 0); __builtin_amdgcn_s_setprio(0); } while (0)
; #define PG8_WAIT_V(n) asm volatile("s_waitcnt vmcnt(" #n ")" ::: "memory")
; #define PG8_WAIT_L(n) asm volatile("s_waitcnt lgkmcnt(" #n ")" ::: "memory")
; #define PG8_BAR __builtin_amdgcn_s_barrier()
; #define PG8_SCHED __builtin_amdgcn_sched_barrier(0)
; template <class Epi, bool ALIGN_EPI, bool ASLOT = false>
; __device__ __forceinline__ void gemm_phase(LAS unsigned char* lds, const Gemm g, const Sched& S, const Epi& E) {
;     ...
;             PG8_LDA(At, 1, 1); PG8_STAGE(PG8_SB(1, 0), b3, voffB); PG8_STAGE(PG8_SB(1, 1), b3 + hstep, voffB); PG8_STAGE(PG8_SA(1, 0), a3, voffA);
;             PG8_WAIT_V(8); PG8_WAIT_L(0); PG8_BAR; PG8_MMA(1, 0, At, B0); PG8_MMA(1, 1, At, B1); PG8_BAR; PG8_SCHED;
;         }
	s_add_i32 s10, s29, s3
	v_lshl_add_u64 v[208:209], v[208:209], 0, s[16:17]
	s_mov_b32 m0, s10
	ds_read_b128 v[176:179], v143 offset:49152
	ds_read_b128 v[180:183], v143 offset:50176
	ds_read_b128 v[184:187], v143 offset:51200
	ds_read_b128 v[188:191], v143 offset:52224
	ds_read_b128 v[192:195], v143 offset:53248
	ds_read_b128 v[196:199], v143 offset:54272
	ds_read_b128 v[200:203], v143 offset:55296
	ds_read_b128 v[204:207], v143 offset:56320
	global_load_lds_dwordx4 v[208:209], off
	s_add_i32 m0, s10, 0x2000
	s_add_u32 s8, s8, 0xb0080
	v_lshl_add_u64 v[208:209], v[210:211], 0, s[16:17]
	s_addc_u32 s9, s9, 0
	s_add_i32 s10, s26, s3
	global_load_lds_dwordx4 v[208:209], off
	v_lshl_add_u64 v[208:209], s[8:9], 0, v[0:1]
	s_mov_b32 m0, s10
	s_nop 0
	global_load_lds_dwordx4 v[208:209], off
	v_lshl_add_u64 v[208:209], s[8:9], 0, v[134:135]
	s_add_i32 m0, s10, 0x2000
	s_nop 0
	global_load_lds_dwordx4 v[208:209], off
	v_lshl_add_u64 v[208:209], v[212:213], 0, s[16:17]
	s_mov_b32 m0, s19
	s_nop 0
	global_load_lds_dwordx4 v[208:209], off
	v_lshl_add_u64 v[208:209], v[214:215], 0, s[16:17]
	s_mov_b32 m0, s20
	s_nop 0
	global_load_lds_dwordx4 v[208:209], off
	s_waitcnt vmcnt(8)
	s_waitcnt lgkmcnt(0)
	s_barrier
	s_waitcnt lgkmcnt(0)
	v_mfma_f32_16x16x32_bf16 v[62:65], v[144:147], v[176:179], v[62:65]
	v_mfma_f32_16x16x32_bf16 v[58:61], v[152:155], v[176:179], v[58:61]
	v_mfma_f32_16x16x32_bf16 v[54:57], v[144:147], v[184:187], v[54:57]
	v_mfma_f32_16x16x32_bf16 v[50:53], v[152:155], v[184:187], v[50:53]
	v_mfma_f32_16x16x32_bf16 v[38:41], v[144:147], v[192:195], v[38:41]
	v_mfma_f32_16x16x32_bf16 v[34:37], v[152:155], v[192:195], v[34:37]
	v_mfma_f32_16x16x32_bf16 v[22:25], v[144:147], v[200:203], v[22:25]
	v_mfma_f32_16x16x32_bf16 v[18:21], v[152:155], v[200:203], v[18:21]
	v_mfma_f32_16x16x32_bf16 v[62:65], v[148:151], v[180:183], v[62:65]
	v_mfma_f32_16x16x32_bf16 v[58:61], v[156:159], v[180:183], v[58:61]
	v_mfma_f32_16x16x32_bf16 v[54:57], v[148:151], v[188:191], v[54:57]
	v_mfma_f32_16x16x32_bf16 v[50:53], v[156:159], v[188:191], v[50:53]
	v_mfma_f32_16x16x32_bf16 v[38:41], v[148:151], v[196:199], v[38:41]
	v_mfma_f32_16x16x32_bf16 v[34:37], v[156:159], v[196:199], v[34:37]
	v_mfma_f32_16x16x32_bf16 v[22:25], v[148:151], v[204:207], v[22:25]
	v_mfma_f32_16x16x32_bf16 v[18:21], v[156:159], v[204:207], v[18:21]
	v_mfma_f32_16x16x32_bf16 v[46:49], v[160:163], v[176:179], v[46:49]
	v_mfma_f32_16x16x32_bf16 v[42:45], v[168:171], v[176:179], v[42:45]
	v_mfma_f32_16x16x32_bf16 v[30:33], v[160:163], v[184:187], v[30:33]
	v_mfma_f32_16x16x32_bf16 v[26:29], v[168:171], v[184:187], v[26:29]
	v_mfma_f32_16x16x32_bf16 v[14:17], v[160:163], v[192:195], v[14:17]
	v_mfma_f32_16x16x32_bf16 v[10:13], v[168:171], v[192:195], v[10:13]
	v_mfma_f32_16x16x32_bf16 v[6:9], v[160:163], v[200:203], v[6:9]
	v_mfma_f32_16x16x32_bf16 v[2:5], v[168:171], v[200:203], v[2:5]
	v_mfma_f32_16x16x32_bf16 v[46:49], v[164:167], v[180:183], v[46:49]
	v_mfma_f32_16x16x32_bf16 v[42:45], v[172:175], v[180:183], v[42:45]
	v_mfma_f32_16x16x32_bf16 v[30:33], v[164:167], v[188:191], v[30:33]
	v_mfma_f32_16x16x32_bf16 v[26:29], v[172:175], v[188:191], v[26:29]
	v_mfma_f32_16x16x32_bf16 v[14:17], v[164:167], v[196:199], v[14:17]
	v_mfma_f32_16x16x32_bf16 v[10:13], v[172:175], v[196:199], v[10:13]
	v_mfma_f32_16x16x32_bf16 v[6:9], v[164:167], v[204:207], v[6:9]
	v_mfma_f32_16x16x32_bf16 v[2:5], v[172:175], v[204:207], v[2:5]
	s_barrier
	s_add_i32 s25, s25, 2
	s_add_u32 s6, s6, 0x100
	s_addc_u32 s7, s7, 0
	s_cmp_gt_u32 s25, 41
	s_cbranch_scc0 .LBB0_884
	s_cmpk_lt_u32 s2, 0x100
	s_cbranch_scc0 .LBB0_887
	s_barrier
